# GEMM K-loops: per-section priority flips deleted (A/B of the template's s_setprio pairs)
# speedup vs baseline: 1.0069x; 1.0069x over previous
; #define PG8_STAGE(bufoff, gbase, voff) do { _Pragma("unroll") for (int _i = 0; _i < 2; ++_i) \
;         __builtin_amdgcn_global_load_lds((const unsigned*)((const char*)(gbase) + (voff)[_i]), (LAS unsigned*)(lds + (bufoff) + ldsw + _i * 8192), 16, 0, 0); } while (0)
; #define PG8_LDA(dst, b, h) do { _Pragma("unroll") for (int m = 0; m < 4; ++m) _Pragma("unroll") for (int k = 0; k < 2; ++k) dst[m][k] = *(const LAS bf16x8*)(lds + PG8_SA(b, h) + aoff + m * 2048 + k * 1024); } while (0)
; #define PG8_LDB(dst, b, h) do { _Pragma("unroll") for (int n = 0; n < 2; ++n) _Pragma("unroll") for (int k = 0; k < 2; ++k) dst[n][k] = *(const LAS bf16x8*)(lds + PG8_SB(b, h) + boff + n * 2048 + k * 1024); } while (0)
; #define PG8_MMA(ai, bj, At, Bt) do { __builtin_amdgcn_s_setprio(1); _Pragma("unroll") for (int m = 0; m < 4; ++m) _Pragma("unroll") for (int n = 0; n < 2; ++n) _Pragma("unroll") for (int k = 0; k < 2; ++k) \
;         acc[ai][bj][m][n] = __builtin_amdgcn_mfma_f32_16x16x32_bf16(Bt[n][k], At[m][k], acc[ai][bj][m][n], 0, 0, 0); __builtin_amdgcn_s_setprio(0); } while (0)
; #define PG8_WAIT_V(n) asm volatile("s_waitcnt vmcnt(" #n ")" ::: "memory")
; #define PG8_WAIT_L(n) asm volatile("s_waitcnt lgkmcnt(" #n ")" ::: "memory")
; #define PG8_BAR __builtin_amdgcn_s_barrier()
; #define PG8_SCHED __builtin_amdgcn_sched_barrier(0)
; template <class Epi, class Sched>
; __device__ __forceinline__ void gemm_phase(LAS unsigned char* lds, const Gemm g, const Sched& S, const Epi& E, int wv) {
;     ...
;         for (int t = 0; t < nt; t += 2) {
;             const bool last = (t == nt - 2);
;             const char* a1 = cA + (size_t)(t + 1) * kstep;
;             const char* a2 = last ? nA : cA + (size_t)(t + 2) * kstep; const char* b2 = last ? nB : cB + (size_t)(t + 2) * kstep;
;             const char* a3 = a2 + kstep; const char* b3 = b2 + kstep;
;             PG8_LDB(B0, 0, 0); PG8_LDB(B1, 0, 1); PG8_SCHED; PG8_LDA(At, 0, 0); PG8_STAGE(PG8_SA(1, 1), a1 + hstepA, voffA);
;             PG8_WAIT_V(8); PG8_WAIT_L(0); PG8_BAR; PG8_MMA(0, 0, At, B0); PG8_MMA(0, 1, At, B1); PG8_BAR; PG8_SCHED;
;             PG8_LDA(At, 0, 1); PG8_STAGE(PG8_SB(0, 0), b2, voffB); PG8_STAGE(PG8_SB(0, 1), b2 + hstepB, voffB); PG8_STAGE(PG8_SA(0, 0), a2, voffA);
;             PG8_WAIT_V(8); PG8_WAIT_L(0); PG8_BAR; PG8_MMA(1, 0, At, B0); PG8_MMA(1, 1, At, B1); PG8_BAR; PG8_SCHED;
.LBB0_141:
	s_add_u32 s0, s78, 0xfffc0080
	s_addc_u32 s1, s79, -1
	s_add_i32 s20, 0, 0x10000
	s_cmp_eq_u32 s35, 12
	s_cselect_b32 s83, s5, s1
	s_cselect_b32 s82, s10, s0
	v_add_u32_e32 v0, s20, v185
	s_cselect_b32 s81, s11, s34
	s_cselect_b32 s80, s21, s31
	s_add_i32 s26, 0, 0x14000
	ds_read_b128 v[142:145], v0
	ds_read_b128 v[146:149], v0 offset:1024
	ds_read_b128 v[150:153], v0 offset:2048
	ds_read_b128 v[154:157], v0 offset:3072
	v_add_u32_e32 v0, s26, v185
	ds_read_b128 v[158:161], v0
	ds_read_b128 v[162:165], v0 offset:1024
	ds_read_b128 v[166:169], v0 offset:2048
	ds_read_b128 v[170:173], v0 offset:3072
	v_lshl_add_u64 v[182:183], s[78:79], 0, v[138:139]
	s_add_i32 m0, s92, 0xc000
	ds_read_b128 v[174:177], v189
	ds_read_b128 v[178:181], v189 offset:1024
	ds_read_b128 v[190:193], v189 offset:2048
	ds_read_b128 v[196:199], v189 offset:3072
	ds_read_b128 v[200:203], v189 offset:4096
	ds_read_b128 v[204:207], v189 offset:5120
	ds_read_b128 v[208:211], v189 offset:6144
	ds_read_b128 v[212:215], v189 offset:7168
	global_load_lds_dwordx4 v[182:183], off
	v_lshl_add_u64 v[182:183], s[78:79], 0, v[140:141]
	s_add_i32 m0, s92, 0xe000
	s_nop 0
	global_load_lds_dwordx4 v[182:183], off
	s_waitcnt vmcnt(8)
	s_waitcnt lgkmcnt(0)
	s_barrier
	v_mfma_f32_16x16x32_bf16 v[126:129], v[142:145], v[174:177], v[126:129]
	v_mfma_f32_16x16x32_bf16 v[122:125], v[150:153], v[174:177], v[122:125]
	v_mfma_f32_16x16x32_bf16 v[110:113], v[142:145], v[190:193], v[110:113]
	v_mfma_f32_16x16x32_bf16 v[106:109], v[150:153], v[190:193], v[106:109]
	v_mfma_f32_16x16x32_bf16 v[94:97], v[142:145], v[200:203], v[94:97]
	v_mfma_f32_16x16x32_bf16 v[90:93], v[150:153], v[200:203], v[90:93]
	v_mfma_f32_16x16x32_bf16 v[78:81], v[142:145], v[208:211], v[78:81]
	v_mfma_f32_16x16x32_bf16 v[74:77], v[150:153], v[208:211], v[74:77]
	v_mfma_f32_16x16x32_bf16 v[126:129], v[146:149], v[178:181], v[126:129]
	v_mfma_f32_16x16x32_bf16 v[122:125], v[154:157], v[178:181], v[122:125]
	v_mfma_f32_16x16x32_bf16 v[110:113], v[146:149], v[196:199], v[110:113]
	v_mfma_f32_16x16x32_bf16 v[106:109], v[154:157], v[196:199], v[106:109]
	v_mfma_f32_16x16x32_bf16 v[94:97], v[146:149], v[204:207], v[94:97]
	v_mfma_f32_16x16x32_bf16 v[90:93], v[154:157], v[204:207], v[90:93]
	v_mfma_f32_16x16x32_bf16 v[78:81], v[146:149], v[212:215], v[78:81]
	v_mfma_f32_16x16x32_bf16 v[74:77], v[154:157], v[212:215], v[74:77]
	v_mfma_f32_16x16x32_bf16 v[118:121], v[158:161], v[174:177], v[118:121]
	v_mfma_f32_16x16x32_bf16 v[114:117], v[166:169], v[174:177], v[114:117]
	v_mfma_f32_16x16x32_bf16 v[102:105], v[158:161], v[190:193], v[102:105]
	v_mfma_f32_16x16x32_bf16 v[98:101], v[166:169], v[190:193], v[98:101]
	v_mfma_f32_16x16x32_bf16 v[86:89], v[158:161], v[200:203], v[86:89]
	v_mfma_f32_16x16x32_bf16 v[82:85], v[166:169], v[200:203], v[82:85]
	v_mfma_f32_16x16x32_bf16 v[70:73], v[158:161], v[208:211], v[70:73]
	v_mfma_f32_16x16x32_bf16 v[66:69], v[166:169], v[208:211], v[66:69]
	v_mfma_f32_16x16x32_bf16 v[118:121], v[162:165], v[178:181], v[118:121]
	v_mfma_f32_16x16x32_bf16 v[114:117], v[170:173], v[178:181], v[114:117]
	v_mfma_f32_16x16x32_bf16 v[102:105], v[162:165], v[196:199], v[102:105]
	v_mfma_f32_16x16x32_bf16 v[98:101], v[170:173], v[196:199], v[98:101]
	v_mfma_f32_16x16x32_bf16 v[86:89], v[162:165], v[204:207], v[86:89]
	v_mfma_f32_16x16x32_bf16 v[82:85], v[170:173], v[204:207], v[82:85]
	v_mfma_f32_16x16x32_bf16 v[70:73], v[162:165], v[212:215], v[70:73]
	v_mfma_f32_16x16x32_bf16 v[66:69], v[170:173], v[212:215], v[66:69]
	s_barrier
	s_add_i32 s0, s20, s91
	v_lshl_add_u64 v[182:183], s[80:81], 0, v[132:133]
	s_mov_b32 m0, s0
	ds_read_b128 v[174:177], v189 offset:16384
	ds_read_b128 v[178:181], v189 offset:17408
	ds_read_b128 v[190:193], v189 offset:18432
	ds_read_b128 v[196:199], v189 offset:19456
	ds_read_b128 v[200:203], v189 offset:20480
	ds_read_b128 v[204:207], v189 offset:21504
	ds_read_b128 v[208:211], v189 offset:22528
	ds_read_b128 v[212:215], v189 offset:23552
	global_load_lds_dwordx4 v[182:183], off
	s_add_i32 m0, s0, 0x2000
	s_add_u32 s0, s80, 0x40000
	v_lshl_add_u64 v[186:187], s[80:81], 0, v[136:137]
	s_addc_u32 s1, s81, 0
	s_add_i32 s20, s26, s91
	global_load_lds_dwordx4 v[186:187], off
	v_lshl_add_u64 v[216:217], s[0:1], 0, v[132:133]
	s_mov_b32 m0, s20
	v_lshl_add_u64 v[218:219], s[82:83], 0, v[134:135]
	global_load_lds_dwordx4 v[216:217], off
	v_lshl_add_u64 v[216:217], s[0:1], 0, v[136:137]
	s_add_i32 m0, s20, 0x2000
	s_nop 0
	global_load_lds_dwordx4 v[216:217], off
	v_lshl_add_u64 v[216:217], s[82:83], 0, v[130:131]
	s_mov_b32 m0, s92
	s_nop 0
	global_load_lds_dwordx4 v[216:217], off
	s_mov_b32 m0, s93
	s_nop 0
	global_load_lds_dwordx4 v[218:219], off
	s_waitcnt vmcnt(8)
	s_waitcnt lgkmcnt(0)
	s_barrier
; #define PG8_STAGE(bufoff, gbase, voff) do { _Pragma("unroll") for (int _i = 0; _i < 2; ++_i) \
;         __builtin_amdgcn_global_load_lds((const unsigned*)((const char*)(gbase) + (voff)[_i]), (LAS unsigned*)(lds + (bufoff) + ldsw + _i * 8192), 16, 0, 0); } while (0)
; #define PG8_LDA(dst, b, h) do { _Pragma("unroll") for (int m = 0; m < 4; ++m) _Pragma("unroll") for (int k = 0; k < 2; ++k) dst[m][k] = *(const LAS bf16x8*)(lds + PG8_SA(b, h) + aoff + m * 2048 + k * 1024); } while (0)
; #define PG8_LDB(dst, b, h) do { _Pragma("unroll") for (int n = 0; n < 2; ++n) _Pragma("unroll") for (int k = 0; k < 2; ++k) dst[n][k] = *(const LAS bf16x8*)(lds + PG8_SB(b, h) + boff + n * 2048 + k * 1024); } while (0)
; #define PG8_MMA(ai, bj, At, Bt) do { __builtin_amdgcn_s_setprio(1); _Pragma("unroll") for (int m = 0; m < 4; ++m) _Pragma("unroll") for (int n = 0; n < 2; ++n) _Pragma("unroll") for (int k = 0; k < 2; ++k) \
;         acc[ai][bj][m][n] = __builtin_amdgcn_mfma_f32_16x16x32_bf16(Bt[n][k], At[m][k], acc[ai][bj][m][n], 0, 0, 0); __builtin_amdgcn_s_setprio(0); } while (0)
; #define PG8_WAIT_V(n) asm volatile("s_waitcnt vmcnt(" #n ")" ::: "memory")
; #define PG8_WAIT_L(n) asm volatile("s_waitcnt lgkmcnt(" #n ")" ::: "memory")
; #define PG8_BAR __builtin_amdgcn_s_barrier()
; #define PG8_SCHED __builtin_amdgcn_sched_barrier(0)
; template <class Epi, class Sched>
; __device__ __forceinline__ void gemm_phase(LAS unsigned char* lds, const Gemm g, const Sched& S, const Epi& E, int wv) {
;     ...
;             PG8_WAIT_V(8); PG8_WAIT_L(0); PG8_BAR; PG8_MMA(0, 0, At, B0); PG8_MMA(0, 1, At, B1); PG8_BAR; PG8_SCHED;
;             PG8_LDA(At, 0, 1); PG8_STAGE(PG8_SB(0, 0), b2, voffB); PG8_STAGE(PG8_SB(0, 1), b2 + hstepB, voffB); PG8_STAGE(PG8_SA(0, 0), a2, voffA);
;             PG8_WAIT_V(8); PG8_WAIT_L(0); PG8_BAR; PG8_MMA(1, 0, At, B0); PG8_MMA(1, 1, At, B1); PG8_BAR; PG8_SCHED;
;             PG8_LDB(B0, 1, 0); PG8_LDB(B1, 1, 1); PG8_SCHED; PG8_LDA(At, 1, 0); PG8_STAGE(PG8_SA(0, 1), a2 + hstepA, voffA);
;             PG8_WAIT_V(8); PG8_WAIT_L(0); PG8_BAR; PG8_MMA(0, 0, At, B0); PG8_MMA(0, 1, At, B1); PG8_BAR; PG8_SCHED;
	v_mfma_f32_16x16x32_bf16 v[62:65], v[142:145], v[174:177], v[62:65]
	v_mfma_f32_16x16x32_bf16 v[58:61], v[150:153], v[174:177], v[58:61]
	v_mfma_f32_16x16x32_bf16 v[46:49], v[142:145], v[190:193], v[46:49]
	v_mfma_f32_16x16x32_bf16 v[42:45], v[150:153], v[190:193], v[42:45]
	v_mfma_f32_16x16x32_bf16 v[30:33], v[142:145], v[200:203], v[30:33]
	v_mfma_f32_16x16x32_bf16 v[26:29], v[150:153], v[200:203], v[26:29]
	v_mfma_f32_16x16x32_bf16 v[14:17], v[142:145], v[208:211], v[14:17]
	v_mfma_f32_16x16x32_bf16 v[10:13], v[150:153], v[208:211], v[10:13]
	v_mfma_f32_16x16x32_bf16 v[62:65], v[146:149], v[178:181], v[62:65]
	v_mfma_f32_16x16x32_bf16 v[58:61], v[154:157], v[178:181], v[58:61]
	v_mfma_f32_16x16x32_bf16 v[46:49], v[146:149], v[196:199], v[46:49]
	v_mfma_f32_16x16x32_bf16 v[42:45], v[154:157], v[196:199], v[42:45]
	v_mfma_f32_16x16x32_bf16 v[30:33], v[146:149], v[204:207], v[30:33]
	v_mfma_f32_16x16x32_bf16 v[26:29], v[154:157], v[204:207], v[26:29]
	v_mfma_f32_16x16x32_bf16 v[14:17], v[146:149], v[212:215], v[14:17]
	v_mfma_f32_16x16x32_bf16 v[10:13], v[154:157], v[212:215], v[10:13]
	v_mfma_f32_16x16x32_bf16 v[54:57], v[158:161], v[174:177], v[54:57]
	v_mfma_f32_16x16x32_bf16 v[50:53], v[166:169], v[174:177], v[50:53]
	v_mfma_f32_16x16x32_bf16 v[38:41], v[158:161], v[190:193], v[38:41]
	v_mfma_f32_16x16x32_bf16 v[34:37], v[166:169], v[190:193], v[34:37]
	v_mfma_f32_16x16x32_bf16 v[22:25], v[158:161], v[200:203], v[22:25]
	v_mfma_f32_16x16x32_bf16 v[18:21], v[166:169], v[200:203], v[18:21]
	v_mfma_f32_16x16x32_bf16 v[6:9], v[158:161], v[208:211], v[6:9]
	v_mfma_f32_16x16x32_bf16 v[2:5], v[166:169], v[208:211], v[2:5]
	v_mfma_f32_16x16x32_bf16 v[54:57], v[162:165], v[178:181], v[54:57]
	v_mfma_f32_16x16x32_bf16 v[50:53], v[170:173], v[178:181], v[50:53]
	v_mfma_f32_16x16x32_bf16 v[38:41], v[162:165], v[196:199], v[38:41]
	v_mfma_f32_16x16x32_bf16 v[34:37], v[170:173], v[196:199], v[34:37]
	v_mfma_f32_16x16x32_bf16 v[22:25], v[162:165], v[204:207], v[22:25]
	v_mfma_f32_16x16x32_bf16 v[18:21], v[170:173], v[204:207], v[18:21]
	v_mfma_f32_16x16x32_bf16 v[6:9], v[162:165], v[212:215], v[6:9]
	v_mfma_f32_16x16x32_bf16 v[2:5], v[170:173], v[212:215], v[2:5]
	s_barrier
	s_add_i32 s20, 0, 0x18000
	v_add_u32_e32 v0, s20, v185
	s_add_i32 s26, 0, 0x1c000
	ds_read_b128 v[142:145], v0
	ds_read_b128 v[146:149], v0 offset:1024
	ds_read_b128 v[150:153], v0 offset:2048
	ds_read_b128 v[154:157], v0 offset:3072
	v_add_u32_e32 v0, s26, v185
	ds_read_b128 v[158:161], v0
	ds_read_b128 v[162:165], v0 offset:1024
	ds_read_b128 v[166:169], v0 offset:2048
	ds_read_b128 v[170:173], v0 offset:3072
	s_add_u32 s0, s82, 0x40000
	s_addc_u32 s1, s83, 0
	s_mov_b32 m0, s96
	v_lshl_add_u64 v[220:221], s[0:1], 0, v[130:131]
	ds_read_b128 v[174:177], v189 offset:32768
	ds_read_b128 v[178:181], v189 offset:33792
	ds_read_b128 v[190:193], v189 offset:34816
	ds_read_b128 v[196:199], v189 offset:35840
	ds_read_b128 v[200:203], v189 offset:36864
	ds_read_b128 v[204:207], v189 offset:37888
	ds_read_b128 v[208:211], v189 offset:38912
	ds_read_b128 v[212:215], v189 offset:39936
	global_load_lds_dwordx4 v[220:221], off
	v_lshl_add_u64 v[220:221], s[0:1], 0, v[134:135]
	s_mov_b32 m0, s50
	s_nop 0
	global_load_lds_dwordx4 v[220:221], off
	s_waitcnt vmcnt(8)
	s_waitcnt lgkmcnt(0)
	s_barrier
	v_mfma_f32_16x16x32_bf16 v[126:129], v[142:145], v[174:177], v[126:129]
	v_mfma_f32_16x16x32_bf16 v[122:125], v[150:153], v[174:177], v[122:125]
	v_mfma_f32_16x16x32_bf16 v[110:113], v[142:145], v[190:193], v[110:113]
	v_mfma_f32_16x16x32_bf16 v[106:109], v[150:153], v[190:193], v[106:109]
	v_mfma_f32_16x16x32_bf16 v[94:97], v[142:145], v[200:203], v[94:97]
	v_mfma_f32_16x16x32_bf16 v[90:93], v[150:153], v[200:203], v[90:93]
	v_mfma_f32_16x16x32_bf16 v[78:81], v[142:145], v[208:211], v[78:81]
	v_mfma_f32_16x16x32_bf16 v[74:77], v[150:153], v[208:211], v[74:77]
	v_mfma_f32_16x16x32_bf16 v[126:129], v[146:149], v[178:181], v[126:129]
	v_mfma_f32_16x16x32_bf16 v[122:125], v[154:157], v[178:181], v[122:125]
	v_mfma_f32_16x16x32_bf16 v[110:113], v[146:149], v[196:199], v[110:113]
	v_mfma_f32_16x16x32_bf16 v[106:109], v[154:157], v[196:199], v[106:109]
	v_mfma_f32_16x16x32_bf16 v[94:97], v[146:149], v[204:207], v[94:97]
	v_mfma_f32_16x16x32_bf16 v[90:93], v[154:157], v[204:207], v[90:93]
	v_mfma_f32_16x16x32_bf16 v[78:81], v[146:149], v[212:215], v[78:81]
	v_mfma_f32_16x16x32_bf16 v[74:77], v[154:157], v[212:215], v[74:77]
	v_mfma_f32_16x16x32_bf16 v[118:121], v[158:161], v[174:177], v[118:121]
	v_mfma_f32_16x16x32_bf16 v[114:117], v[166:169], v[174:177], v[114:117]
	v_mfma_f32_16x16x32_bf16 v[102:105], v[158:161], v[190:193], v[102:105]
	v_mfma_f32_16x16x32_bf16 v[98:101], v[166:169], v[190:193], v[98:101]
	v_mfma_f32_16x16x32_bf16 v[86:89], v[158:161], v[200:203], v[86:89]
	v_mfma_f32_16x16x32_bf16 v[82:85], v[166:169], v[200:203], v[82:85]
	v_mfma_f32_16x16x32_bf16 v[70:73], v[158:161], v[208:211], v[70:73]
	v_mfma_f32_16x16x32_bf16 v[66:69], v[166:169], v[208:211], v[66:69]
	v_mfma_f32_16x16x32_bf16 v[118:121], v[162:165], v[178:181], v[118:121]
	v_mfma_f32_16x16x32_bf16 v[114:117], v[170:173], v[178:181], v[114:117]
	v_mfma_f32_16x16x32_bf16 v[102:105], v[162:165], v[196:199], v[102:105]
	v_mfma_f32_16x16x32_bf16 v[98:101], v[170:173], v[196:199], v[98:101]
	v_mfma_f32_16x16x32_bf16 v[86:89], v[162:165], v[204:207], v[86:89]
	v_mfma_f32_16x16x32_bf16 v[82:85], v[170:173], v[204:207], v[82:85]
	v_mfma_f32_16x16x32_bf16 v[70:73], v[162:165], v[212:215], v[70:73]
	v_mfma_f32_16x16x32_bf16 v[66:69], v[170:173], v[212:215], v[66:69]
	s_barrier
; #define PG8_STAGE(bufoff, gbase, voff) do { _Pragma("unroll") for (int _i = 0; _i < 2; ++_i) \
;         __builtin_amdgcn_global_load_lds((const unsigned*)((const char*)(gbase) + (voff)[_i]), (LAS unsigned*)(lds + (bufoff) + ldsw + _i * 8192), 16, 0, 0); } while (0)
; #define PG8_LDA(dst, b, h) do { _Pragma("unroll") for (int m = 0; m < 4; ++m) _Pragma("unroll") for (int k = 0; k < 2; ++k) dst[m][k] = *(const LAS bf16x8*)(lds + PG8_SA(b, h) + aoff + m * 2048 + k * 1024); } while (0)
; #define PG8_MMA(ai, bj, At, Bt) do { __builtin_amdgcn_s_setprio(1); _Pragma("unroll") for (int m = 0; m < 4; ++m) _Pragma("unroll") for (int n = 0; n < 2; ++n) _Pragma("unroll") for (int k = 0; k < 2; ++k) \
;         acc[ai][bj][m][n] = __builtin_amdgcn_mfma_f32_16x16x32_bf16(Bt[n][k], At[m][k], acc[ai][bj][m][n], 0, 0, 0); __builtin_amdgcn_s_setprio(0); } while (0)
; #define PG8_WAIT_V(n) asm volatile("s_waitcnt vmcnt(" #n ")" ::: "memory")
; #define PG8_WAIT_L(n) asm volatile("s_waitcnt lgkmcnt(" #n ")" ::: "memory")
; #define PG8_BAR __builtin_amdgcn_s_barrier()
; #define PG8_SCHED __builtin_amdgcn_sched_barrier(0)
; template <class Epi, class Sched>
; __device__ __forceinline__ void gemm_phase(LAS unsigned char* lds, const Gemm g, const Sched& S, const Epi& E, int wv) {
;     ...
;             PG8_WAIT_V(8); PG8_WAIT_L(0); PG8_BAR; PG8_MMA(0, 0, At, B0); PG8_MMA(0, 1, At, B1); PG8_BAR; PG8_SCHED;
;             PG8_LDA(At, 1, 1); PG8_STAGE(PG8_SB(1, 0), b3, voffB); PG8_STAGE(PG8_SB(1, 1), b3 + hstepB, voffB); PG8_STAGE(PG8_SA(1, 0), a3, voffA);
;             PG8_WAIT_V(8); PG8_WAIT_L(0); PG8_BAR; PG8_MMA(1, 0, At, B0); PG8_MMA(1, 1, At, B1); PG8_BAR; PG8_SCHED;
;         }
	s_add_i32 s0, s20, s91
	v_lshl_add_u64 v[182:183], v[182:183], 0, s[24:25]
	s_mov_b32 m0, s0
	ds_read_b128 v[174:177], v189 offset:49152
	ds_read_b128 v[178:181], v189 offset:50176
	ds_read_b128 v[190:193], v189 offset:51200
	ds_read_b128 v[196:199], v189 offset:52224
	ds_read_b128 v[200:203], v189 offset:53248
	ds_read_b128 v[204:207], v189 offset:54272
	ds_read_b128 v[208:211], v189 offset:55296
	ds_read_b128 v[212:215], v189 offset:56320
	global_load_lds_dwordx4 v[182:183], off
	s_add_i32 m0, s0, 0x2000
	s_add_u32 s0, s80, 0x40080
	v_lshl_add_u64 v[182:183], v[186:187], 0, s[24:25]
	s_addc_u32 s1, s81, 0
	s_add_i32 s20, s26, s91
	global_load_lds_dwordx4 v[182:183], off
	v_lshl_add_u64 v[182:183], s[0:1], 0, v[132:133]
	s_mov_b32 m0, s20
	s_nop 0
	global_load_lds_dwordx4 v[182:183], off
	v_lshl_add_u64 v[182:183], s[0:1], 0, v[136:137]
	s_add_i32 m0, s20, 0x2000
	s_nop 0
	global_load_lds_dwordx4 v[182:183], off
	v_lshl_add_u64 v[182:183], v[216:217], 0, s[24:25]
	s_mov_b32 m0, s62
	s_nop 0
	global_load_lds_dwordx4 v[182:183], off
	v_lshl_add_u64 v[182:183], v[218:219], 0, s[24:25]
	s_mov_b32 m0, s46
	s_nop 0
	global_load_lds_dwordx4 v[182:183], off
	s_waitcnt vmcnt(8)
	s_waitcnt lgkmcnt(0)
	s_barrier
	v_mfma_f32_16x16x32_bf16 v[62:65], v[142:145], v[174:177], v[62:65]
	v_mfma_f32_16x16x32_bf16 v[58:61], v[150:153], v[174:177], v[58:61]
	v_mfma_f32_16x16x32_bf16 v[46:49], v[142:145], v[190:193], v[46:49]
	v_mfma_f32_16x16x32_bf16 v[42:45], v[150:153], v[190:193], v[42:45]
	v_mfma_f32_16x16x32_bf16 v[30:33], v[142:145], v[200:203], v[30:33]
	v_mfma_f32_16x16x32_bf16 v[26:29], v[150:153], v[200:203], v[26:29]
	v_mfma_f32_16x16x32_bf16 v[14:17], v[142:145], v[208:211], v[14:17]
	v_mfma_f32_16x16x32_bf16 v[10:13], v[150:153], v[208:211], v[10:13]
	v_mfma_f32_16x16x32_bf16 v[62:65], v[146:149], v[178:181], v[62:65]
	v_mfma_f32_16x16x32_bf16 v[58:61], v[154:157], v[178:181], v[58:61]
	v_mfma_f32_16x16x32_bf16 v[46:49], v[146:149], v[196:199], v[46:49]
	v_mfma_f32_16x16x32_bf16 v[42:45], v[154:157], v[196:199], v[42:45]
	v_mfma_f32_16x16x32_bf16 v[30:33], v[146:149], v[204:207], v[30:33]
	v_mfma_f32_16x16x32_bf16 v[26:29], v[154:157], v[204:207], v[26:29]
	v_mfma_f32_16x16x32_bf16 v[14:17], v[146:149], v[212:215], v[14:17]
	v_mfma_f32_16x16x32_bf16 v[10:13], v[154:157], v[212:215], v[10:13]
	v_mfma_f32_16x16x32_bf16 v[54:57], v[158:161], v[174:177], v[54:57]
	v_mfma_f32_16x16x32_bf16 v[50:53], v[166:169], v[174:177], v[50:53]
	v_mfma_f32_16x16x32_bf16 v[38:41], v[158:161], v[190:193], v[38:41]
	v_mfma_f32_16x16x32_bf16 v[34:37], v[166:169], v[190:193], v[34:37]
	v_mfma_f32_16x16x32_bf16 v[22:25], v[158:161], v[200:203], v[22:25]
	v_mfma_f32_16x16x32_bf16 v[18:21], v[166:169], v[200:203], v[18:21]
	v_mfma_f32_16x16x32_bf16 v[6:9], v[158:161], v[208:211], v[6:9]
	v_mfma_f32_16x16x32_bf16 v[2:5], v[166:169], v[208:211], v[2:5]
	v_mfma_f32_16x16x32_bf16 v[54:57], v[162:165], v[178:181], v[54:57]
	v_mfma_f32_16x16x32_bf16 v[50:53], v[170:173], v[178:181], v[50:53]
	v_mfma_f32_16x16x32_bf16 v[38:41], v[162:165], v[196:199], v[38:41]
	v_mfma_f32_16x16x32_bf16 v[34:37], v[170:173], v[196:199], v[34:37]
	v_mfma_f32_16x16x32_bf16 v[22:25], v[162:165], v[204:207], v[22:25]
	v_mfma_f32_16x16x32_bf16 v[18:21], v[170:173], v[204:207], v[18:21]
	v_mfma_f32_16x16x32_bf16 v[6:9], v[162:165], v[212:215], v[6:9]
	v_mfma_f32_16x16x32_bf16 v[2:5], v[170:173], v[212:215], v[2:5]
	s_barrier
	s_add_i32 s35, s35, 2
	s_add_u32 s78, s78, 0x100
	s_addc_u32 s79, s79, 0
	s_add_u32 s31, s31, 0x100
	s_addc_u32 s34, s34, 0
	s_cmp_gt_u32 s35, 13
	s_cbranch_scc0 .LBB0_141
	s_and_b64 vcc, exec, s[68:69]
	s_cbranch_vccz .LBB0_144
	s_barrier

; #define PG8_STAGE(bufoff, gbase, voff) do { _Pragma("unroll") for (int _i = 0; _i < 2; ++_i) \
;         __builtin_amdgcn_global_load_lds((const unsigned*)((const char*)(gbase) + (voff)[_i]), (LAS unsigned*)(lds + (bufoff) + ldsw + _i * 8192), 16, 0, 0); } while (0)
; #define PG8_LDA(dst, b, h) do { _Pragma("unroll") for (int m = 0; m < 4; ++m) _Pragma("unroll") for (int k = 0; k < 2; ++k) dst[m][k] = *(const LAS bf16x8*)(lds + PG8_SA(b, h) + aoff + m * 2048 + k * 1024); } while (0)
; #define PG8_LDB(dst, b, h) do { _Pragma("unroll") for (int n = 0; n < 2; ++n) _Pragma("unroll") for (int k = 0; k < 2; ++k) dst[n][k] = *(const LAS bf16x8*)(lds + PG8_SB(b, h) + boff + n * 2048 + k * 1024); } while (0)
; #define PG8_MMA(ai, bj, At, Bt) do { __builtin_amdgcn_s_setprio(1); _Pragma("unroll") for (int m = 0; m < 4; ++m) _Pragma("unroll") for (int n = 0; n < 2; ++n) _Pragma("unroll") for (int k = 0; k < 2; ++k) \
;         acc[ai][bj][m][n] = __builtin_amdgcn_mfma_f32_16x16x32_bf16(Bt[n][k], At[m][k], acc[ai][bj][m][n], 0, 0, 0); __builtin_amdgcn_s_setprio(0); } while (0)
; #define PG8_WAIT_V(n) asm volatile("s_waitcnt vmcnt(" #n ")" ::: "memory")
; #define PG8_WAIT_L(n) asm volatile("s_waitcnt lgkmcnt(" #n ")" ::: "memory")
; #define PG8_BAR __builtin_amdgcn_s_barrier()
; #define PG8_SCHED __builtin_amdgcn_sched_barrier(0)
; template <class Epi, class Sched>
; __device__ __forceinline__ void gemm_phase(LAS unsigned char* lds, const Gemm g, const Sched& S, const Epi& E, int wv) {
;     ...
;         for (int t = 0; t < nt; t += 2) {
;             const bool last = (t == nt - 2);
;             const char* a1 = cA + (size_t)(t + 1) * kstep;
;             const char* a2 = last ? nA : cA + (size_t)(t + 2) * kstep; const char* b2 = last ? nB : cB + (size_t)(t + 2) * kstep;
;             const char* a3 = a2 + kstep; const char* b3 = b2 + kstep;
;             PG8_LDB(B0, 0, 0); PG8_LDB(B1, 0, 1); PG8_SCHED; PG8_LDA(At, 0, 0); PG8_STAGE(PG8_SA(1, 1), a1 + hstepA, voffA);
;             PG8_WAIT_V(8); PG8_WAIT_L(0); PG8_BAR; PG8_MMA(0, 0, At, B0); PG8_MMA(0, 1, At, B1); PG8_BAR; PG8_SCHED;
;             PG8_LDA(At, 0, 1); PG8_STAGE(PG8_SB(0, 0), b2, voffB); PG8_STAGE(PG8_SB(0, 1), b2 + hstepB, voffB); PG8_STAGE(PG8_SA(0, 0), a2, voffA);
;             PG8_WAIT_V(8); PG8_WAIT_L(0); PG8_BAR; PG8_MMA(1, 0, At, B0); PG8_MMA(1, 1, At, B1); PG8_BAR; PG8_SCHED;
.LBB0_174:
	s_add_u32 s70, s68, 0x100
	s_addc_u32 s71, s69, 0
	s_add_i32 s0, 0, 0x10000
	s_cmp_eq_u32 s31, 40
	s_cselect_b32 s75, s5, s71
	s_cselect_b32 s74, s4, s70
	v_add_u32_e32 v144, s0, v146
	s_cselect_b32 s73, s67, s21
	s_cselect_b32 s72, s66, s11
	s_add_i32 s20, 0, 0x14000
	ds_read_b128 v[140:143], v144
	ds_read_b128 v[148:151], v144 offset:1024
	ds_read_b128 v[152:155], v144 offset:2048
	ds_read_b128 v[156:159], v144 offset:3072
	v_add_u32_e32 v144, s20, v146
	ds_read_b128 v[160:163], v144
	ds_read_b128 v[164:167], v144 offset:1024
	ds_read_b128 v[168:171], v144 offset:2048
	ds_read_b128 v[172:175], v144 offset:3072
	v_lshl_add_u64 v[144:145], s[68:69], 0, v[136:137]
	s_add_i32 m0, s62, 0xc000
	ds_read_b128 v[176:179], v147
	ds_read_b128 v[180:183], v147 offset:1024
	ds_read_b128 v[184:187], v147 offset:2048
	ds_read_b128 v[188:191], v147 offset:3072
	ds_read_b128 v[196:199], v147 offset:4096
	ds_read_b128 v[200:203], v147 offset:5120
	ds_read_b128 v[204:207], v147 offset:6144
	ds_read_b128 v[208:211], v147 offset:7168
	global_load_lds_dwordx4 v[144:145], off
	v_lshl_add_u64 v[144:145], s[68:69], 0, v[138:139]
	s_add_i32 m0, s62, 0xe000
	s_nop 0
	global_load_lds_dwordx4 v[144:145], off
	s_waitcnt vmcnt(8)
	s_waitcnt lgkmcnt(0)
	s_barrier
	v_mfma_f32_16x16x32_bf16 v[126:129], v[140:143], v[176:179], v[126:129]
	v_mfma_f32_16x16x32_bf16 v[122:125], v[152:155], v[176:179], v[122:125]
	v_mfma_f32_16x16x32_bf16 v[110:113], v[140:143], v[184:187], v[110:113]
	v_mfma_f32_16x16x32_bf16 v[106:109], v[152:155], v[184:187], v[106:109]
	v_mfma_f32_16x16x32_bf16 v[94:97], v[140:143], v[196:199], v[94:97]
	v_mfma_f32_16x16x32_bf16 v[90:93], v[152:155], v[196:199], v[90:93]
	v_mfma_f32_16x16x32_bf16 v[78:81], v[140:143], v[204:207], v[78:81]
	v_mfma_f32_16x16x32_bf16 v[74:77], v[152:155], v[204:207], v[74:77]
	v_mfma_f32_16x16x32_bf16 v[126:129], v[148:151], v[180:183], v[126:129]
	v_mfma_f32_16x16x32_bf16 v[122:125], v[156:159], v[180:183], v[122:125]
	v_mfma_f32_16x16x32_bf16 v[110:113], v[148:151], v[188:191], v[110:113]
	v_mfma_f32_16x16x32_bf16 v[106:109], v[156:159], v[188:191], v[106:109]
	v_mfma_f32_16x16x32_bf16 v[94:97], v[148:151], v[200:203], v[94:97]
	v_mfma_f32_16x16x32_bf16 v[90:93], v[156:159], v[200:203], v[90:93]
	v_mfma_f32_16x16x32_bf16 v[78:81], v[148:151], v[208:211], v[78:81]
	v_mfma_f32_16x16x32_bf16 v[74:77], v[156:159], v[208:211], v[74:77]
	v_mfma_f32_16x16x32_bf16 v[118:121], v[160:163], v[176:179], v[118:121]
	v_mfma_f32_16x16x32_bf16 v[114:117], v[168:171], v[176:179], v[114:117]
	v_mfma_f32_16x16x32_bf16 v[102:105], v[160:163], v[184:187], v[102:105]
	v_mfma_f32_16x16x32_bf16 v[98:101], v[168:171], v[184:187], v[98:101]
	v_mfma_f32_16x16x32_bf16 v[86:89], v[160:163], v[196:199], v[86:89]
	v_mfma_f32_16x16x32_bf16 v[82:85], v[168:171], v[196:199], v[82:85]
	v_mfma_f32_16x16x32_bf16 v[70:73], v[160:163], v[204:207], v[70:73]
	v_mfma_f32_16x16x32_bf16 v[66:69], v[168:171], v[204:207], v[66:69]
	v_mfma_f32_16x16x32_bf16 v[118:121], v[164:167], v[180:183], v[118:121]
	v_mfma_f32_16x16x32_bf16 v[114:117], v[172:175], v[180:183], v[114:117]
	v_mfma_f32_16x16x32_bf16 v[102:105], v[164:167], v[188:191], v[102:105]
	v_mfma_f32_16x16x32_bf16 v[98:101], v[172:175], v[188:191], v[98:101]
	v_mfma_f32_16x16x32_bf16 v[86:89], v[164:167], v[200:203], v[86:89]
	v_mfma_f32_16x16x32_bf16 v[82:85], v[172:175], v[200:203], v[82:85]
	v_mfma_f32_16x16x32_bf16 v[70:73], v[164:167], v[208:211], v[70:73]
	v_mfma_f32_16x16x32_bf16 v[66:69], v[172:175], v[208:211], v[66:69]
	s_barrier
	s_add_i32 s0, s0, s61
	v_lshl_add_u64 v[144:145], s[72:73], 0, v[0:1]
	s_mov_b32 m0, s0
	ds_read_b128 v[176:179], v147 offset:16384
	ds_read_b128 v[180:183], v147 offset:17408
	ds_read_b128 v[184:187], v147 offset:18432
	ds_read_b128 v[188:191], v147 offset:19456
	ds_read_b128 v[196:199], v147 offset:20480
	ds_read_b128 v[200:203], v147 offset:21504
	ds_read_b128 v[204:207], v147 offset:22528
	ds_read_b128 v[208:211], v147 offset:23552
	global_load_lds_dwordx4 v[144:145], off
	s_add_i32 m0, s0, 0x2000
	s_add_u32 s0, s72, 0xb0000
	v_lshl_add_u64 v[192:193], s[72:73], 0, v[134:135]
	s_addc_u32 s1, s73, 0
	s_add_i32 s20, s20, s61
	global_load_lds_dwordx4 v[192:193], off
	v_lshl_add_u64 v[212:213], s[0:1], 0, v[0:1]
	s_mov_b32 m0, s20
	v_lshl_add_u64 v[214:215], s[74:75], 0, v[132:133]
	global_load_lds_dwordx4 v[212:213], off
	v_lshl_add_u64 v[212:213], s[0:1], 0, v[134:135]
	s_add_i32 m0, s20, 0x2000
	s_nop 0
	global_load_lds_dwordx4 v[212:213], off
	v_lshl_add_u64 v[212:213], s[74:75], 0, v[130:131]
	s_mov_b32 m0, s62
	s_nop 0
	global_load_lds_dwordx4 v[212:213], off
	s_mov_b32 m0, s76
	s_nop 0
	global_load_lds_dwordx4 v[214:215], off
	s_waitcnt vmcnt(8)
	s_waitcnt lgkmcnt(0)
	s_barrier
; #define PG8_STAGE(bufoff, gbase, voff) do { _Pragma("unroll") for (int _i = 0; _i < 2; ++_i) \
;         __builtin_amdgcn_global_load_lds((const unsigned*)((const char*)(gbase) + (voff)[_i]), (LAS unsigned*)(lds + (bufoff) + ldsw + _i * 8192), 16, 0, 0); } while (0)
; #define PG8_LDA(dst, b, h) do { _Pragma("unroll") for (int m = 0; m < 4; ++m) _Pragma("unroll") for (int k = 0; k < 2; ++k) dst[m][k] = *(const LAS bf16x8*)(lds + PG8_SA(b, h) + aoff + m * 2048 + k * 1024); } while (0)
; #define PG8_LDB(dst, b, h) do { _Pragma("unroll") for (int n = 0; n < 2; ++n) _Pragma("unroll") for (int k = 0; k < 2; ++k) dst[n][k] = *(const LAS bf16x8*)(lds + PG8_SB(b, h) + boff + n * 2048 + k * 1024); } while (0)
; #define PG8_MMA(ai, bj, At, Bt) do { __builtin_amdgcn_s_setprio(1); _Pragma("unroll") for (int m = 0; m < 4; ++m) _Pragma("unroll") for (int n = 0; n < 2; ++n) _Pragma("unroll") for (int k = 0; k < 2; ++k) \
;         acc[ai][bj][m][n] = __builtin_amdgcn_mfma_f32_16x16x32_bf16(Bt[n][k], At[m][k], acc[ai][bj][m][n], 0, 0, 0); __builtin_amdgcn_s_setprio(0); } while (0)
; #define PG8_WAIT_V(n) asm volatile("s_waitcnt vmcnt(" #n ")" ::: "memory")
; #define PG8_WAIT_L(n) asm volatile("s_waitcnt lgkmcnt(" #n ")" ::: "memory")
; #define PG8_BAR __builtin_amdgcn_s_barrier()
; #define PG8_SCHED __builtin_amdgcn_sched_barrier(0)
; template <class Epi, class Sched>
; __device__ __forceinline__ void gemm_phase(LAS unsigned char* lds, const Gemm g, const Sched& S, const Epi& E, int wv) {
;     ...
;             PG8_WAIT_V(8); PG8_WAIT_L(0); PG8_BAR; PG8_MMA(0, 0, At, B0); PG8_MMA(0, 1, At, B1); PG8_BAR; PG8_SCHED;
;             PG8_LDA(At, 0, 1); PG8_STAGE(PG8_SB(0, 0), b2, voffB); PG8_STAGE(PG8_SB(0, 1), b2 + hstepB, voffB); PG8_STAGE(PG8_SA(0, 0), a2, voffA);
;             PG8_WAIT_V(8); PG8_WAIT_L(0); PG8_BAR; PG8_MMA(1, 0, At, B0); PG8_MMA(1, 1, At, B1); PG8_BAR; PG8_SCHED;
;             PG8_LDB(B0, 1, 0); PG8_LDB(B1, 1, 1); PG8_SCHED; PG8_LDA(At, 1, 0); PG8_STAGE(PG8_SA(0, 1), a2 + hstepA, voffA);
;             PG8_WAIT_V(8); PG8_WAIT_L(0); PG8_BAR; PG8_MMA(0, 0, At, B0); PG8_MMA(0, 1, At, B1); PG8_BAR; PG8_SCHED;
;             PG8_LDA(At, 1, 1); PG8_STAGE(PG8_SB(1, 0), b3, voffB); PG8_STAGE(PG8_SB(1, 1), b3 + hstepB, voffB); PG8_STAGE(PG8_SA(1, 0), a3, voffA);
	v_mfma_f32_16x16x32_bf16 v[62:65], v[140:143], v[176:179], v[62:65]
	v_mfma_f32_16x16x32_bf16 v[58:61], v[152:155], v[176:179], v[58:61]
	v_mfma_f32_16x16x32_bf16 v[46:49], v[140:143], v[184:187], v[46:49]
	v_mfma_f32_16x16x32_bf16 v[42:45], v[152:155], v[184:187], v[42:45]
	v_mfma_f32_16x16x32_bf16 v[30:33], v[140:143], v[196:199], v[30:33]
	v_mfma_f32_16x16x32_bf16 v[26:29], v[152:155], v[196:199], v[26:29]
	v_mfma_f32_16x16x32_bf16 v[14:17], v[140:143], v[204:207], v[14:17]
	v_mfma_f32_16x16x32_bf16 v[10:13], v[152:155], v[204:207], v[10:13]
	v_mfma_f32_16x16x32_bf16 v[62:65], v[148:151], v[180:183], v[62:65]
	v_mfma_f32_16x16x32_bf16 v[58:61], v[156:159], v[180:183], v[58:61]
	v_mfma_f32_16x16x32_bf16 v[46:49], v[148:151], v[188:191], v[46:49]
	v_mfma_f32_16x16x32_bf16 v[42:45], v[156:159], v[188:191], v[42:45]
	v_mfma_f32_16x16x32_bf16 v[30:33], v[148:151], v[200:203], v[30:33]
	v_mfma_f32_16x16x32_bf16 v[26:29], v[156:159], v[200:203], v[26:29]
	v_mfma_f32_16x16x32_bf16 v[14:17], v[148:151], v[208:211], v[14:17]
	v_mfma_f32_16x16x32_bf16 v[10:13], v[156:159], v[208:211], v[10:13]
	v_mfma_f32_16x16x32_bf16 v[54:57], v[160:163], v[176:179], v[54:57]
	v_mfma_f32_16x16x32_bf16 v[50:53], v[168:171], v[176:179], v[50:53]
	v_mfma_f32_16x16x32_bf16 v[38:41], v[160:163], v[184:187], v[38:41]
	v_mfma_f32_16x16x32_bf16 v[34:37], v[168:171], v[184:187], v[34:37]
	v_mfma_f32_16x16x32_bf16 v[22:25], v[160:163], v[196:199], v[22:25]
	v_mfma_f32_16x16x32_bf16 v[18:21], v[168:171], v[196:199], v[18:21]
	v_mfma_f32_16x16x32_bf16 v[6:9], v[160:163], v[204:207], v[6:9]
	v_mfma_f32_16x16x32_bf16 v[2:5], v[168:171], v[204:207], v[2:5]
	v_mfma_f32_16x16x32_bf16 v[54:57], v[164:167], v[180:183], v[54:57]
	v_mfma_f32_16x16x32_bf16 v[50:53], v[172:175], v[180:183], v[50:53]
	v_mfma_f32_16x16x32_bf16 v[38:41], v[164:167], v[188:191], v[38:41]
	v_mfma_f32_16x16x32_bf16 v[34:37], v[172:175], v[188:191], v[34:37]
	v_mfma_f32_16x16x32_bf16 v[22:25], v[164:167], v[200:203], v[22:25]
	v_mfma_f32_16x16x32_bf16 v[18:21], v[172:175], v[200:203], v[18:21]
	v_mfma_f32_16x16x32_bf16 v[6:9], v[164:167], v[208:211], v[6:9]
	v_mfma_f32_16x16x32_bf16 v[2:5], v[172:175], v[208:211], v[2:5]
	s_barrier
	s_add_i32 s20, 0, 0x18000
	s_add_i32 s26, 0, 0x1c000
	v_add_u32_e32 v156, s20, v146
	v_add_u32_e32 v172, s26, v146
	ds_read_b128 v[140:143], v156
	ds_read_b128 v[148:151], v156 offset:1024
	ds_read_b128 v[152:155], v156 offset:2048
	ds_read_b128 v[156:159], v156 offset:3072
	ds_read_b128 v[160:163], v172
	ds_read_b128 v[164:167], v172 offset:1024
	ds_read_b128 v[168:171], v172 offset:2048
	ds_read_b128 v[172:175], v172 offset:3072
	s_add_u32 s0, s74, 0xb0000
	s_addc_u32 s1, s75, 0
	s_mov_b32 m0, s77
	v_lshl_add_u64 v[216:217], s[0:1], 0, v[130:131]
	ds_read_b128 v[176:179], v147 offset:32768
	ds_read_b128 v[180:183], v147 offset:33792
	ds_read_b128 v[184:187], v147 offset:34816
	ds_read_b128 v[188:191], v147 offset:35840
	ds_read_b128 v[196:199], v147 offset:36864
	ds_read_b128 v[200:203], v147 offset:37888
	ds_read_b128 v[204:207], v147 offset:38912
	ds_read_b128 v[208:211], v147 offset:39936
	global_load_lds_dwordx4 v[216:217], off
	v_lshl_add_u64 v[216:217], s[0:1], 0, v[132:133]
	s_mov_b32 m0, s78
	s_nop 0
	global_load_lds_dwordx4 v[216:217], off
	s_waitcnt vmcnt(8)
	s_waitcnt lgkmcnt(0)
	s_barrier
	v_mfma_f32_16x16x32_bf16 v[126:129], v[140:143], v[176:179], v[126:129]
	v_mfma_f32_16x16x32_bf16 v[122:125], v[152:155], v[176:179], v[122:125]
	v_mfma_f32_16x16x32_bf16 v[110:113], v[140:143], v[184:187], v[110:113]
	v_mfma_f32_16x16x32_bf16 v[106:109], v[152:155], v[184:187], v[106:109]
	v_mfma_f32_16x16x32_bf16 v[94:97], v[140:143], v[196:199], v[94:97]
	v_mfma_f32_16x16x32_bf16 v[90:93], v[152:155], v[196:199], v[90:93]
	v_mfma_f32_16x16x32_bf16 v[78:81], v[140:143], v[204:207], v[78:81]
	v_mfma_f32_16x16x32_bf16 v[74:77], v[152:155], v[204:207], v[74:77]
	v_mfma_f32_16x16x32_bf16 v[126:129], v[148:151], v[180:183], v[126:129]
	v_mfma_f32_16x16x32_bf16 v[122:125], v[156:159], v[180:183], v[122:125]
	v_mfma_f32_16x16x32_bf16 v[110:113], v[148:151], v[188:191], v[110:113]
	v_mfma_f32_16x16x32_bf16 v[106:109], v[156:159], v[188:191], v[106:109]
	v_mfma_f32_16x16x32_bf16 v[94:97], v[148:151], v[200:203], v[94:97]
	v_mfma_f32_16x16x32_bf16 v[90:93], v[156:159], v[200:203], v[90:93]
	v_mfma_f32_16x16x32_bf16 v[78:81], v[148:151], v[208:211], v[78:81]
	v_mfma_f32_16x16x32_bf16 v[74:77], v[156:159], v[208:211], v[74:77]
	v_mfma_f32_16x16x32_bf16 v[118:121], v[160:163], v[176:179], v[118:121]
	v_mfma_f32_16x16x32_bf16 v[114:117], v[168:171], v[176:179], v[114:117]
	v_mfma_f32_16x16x32_bf16 v[102:105], v[160:163], v[184:187], v[102:105]
	v_mfma_f32_16x16x32_bf16 v[98:101], v[168:171], v[184:187], v[98:101]
	v_mfma_f32_16x16x32_bf16 v[86:89], v[160:163], v[196:199], v[86:89]
	v_mfma_f32_16x16x32_bf16 v[82:85], v[168:171], v[196:199], v[82:85]
	v_mfma_f32_16x16x32_bf16 v[70:73], v[160:163], v[204:207], v[70:73]
	v_mfma_f32_16x16x32_bf16 v[66:69], v[168:171], v[204:207], v[66:69]
	v_mfma_f32_16x16x32_bf16 v[118:121], v[164:167], v[180:183], v[118:121]
	v_mfma_f32_16x16x32_bf16 v[114:117], v[172:175], v[180:183], v[114:117]
	v_mfma_f32_16x16x32_bf16 v[102:105], v[164:167], v[188:191], v[102:105]
	v_mfma_f32_16x16x32_bf16 v[98:101], v[172:175], v[188:191], v[98:101]
	v_mfma_f32_16x16x32_bf16 v[86:89], v[164:167], v[200:203], v[86:89]
	v_mfma_f32_16x16x32_bf16 v[82:85], v[172:175], v[200:203], v[82:85]
	v_mfma_f32_16x16x32_bf16 v[70:73], v[164:167], v[208:211], v[70:73]
	v_mfma_f32_16x16x32_bf16 v[66:69], v[172:175], v[208:211], v[66:69]
	s_barrier
; #define PG8_STAGE(bufoff, gbase, voff) do { _Pragma("unroll") for (int _i = 0; _i < 2; ++_i) \
;         __builtin_amdgcn_global_load_lds((const unsigned*)((const char*)(gbase) + (voff)[_i]), (LAS unsigned*)(lds + (bufoff) + ldsw + _i * 8192), 16, 0, 0); } while (0)
; #define PG8_LDA(dst, b, h) do { _Pragma("unroll") for (int m = 0; m < 4; ++m) _Pragma("unroll") for (int k = 0; k < 2; ++k) dst[m][k] = *(const LAS bf16x8*)(lds + PG8_SA(b, h) + aoff + m * 2048 + k * 1024); } while (0)
; #define PG8_MMA(ai, bj, At, Bt) do { __builtin_amdgcn_s_setprio(1); _Pragma("unroll") for (int m = 0; m < 4; ++m) _Pragma("unroll") for (int n = 0; n < 2; ++n) _Pragma("unroll") for (int k = 0; k < 2; ++k) \
;         acc[ai][bj][m][n] = __builtin_amdgcn_mfma_f32_16x16x32_bf16(Bt[n][k], At[m][k], acc[ai][bj][m][n], 0, 0, 0); __builtin_amdgcn_s_setprio(0); } while (0)
; #define PG8_WAIT_V(n) asm volatile("s_waitcnt vmcnt(" #n ")" ::: "memory")
; #define PG8_WAIT_L(n) asm volatile("s_waitcnt lgkmcnt(" #n ")" ::: "memory")
; #define PG8_BAR __builtin_amdgcn_s_barrier()
; #define PG8_SCHED __builtin_amdgcn_sched_barrier(0)
; template <class Epi, class Sched>
; __device__ __forceinline__ void gemm_phase(LAS unsigned char* lds, const Gemm g, const Sched& S, const Epi& E, int wv) {
;     ...
;         for (int t = 0; t < nt; t += 2) {
;             const bool last = (t == nt - 2);
;     ...
;             PG8_LDA(At, 1, 1); PG8_STAGE(PG8_SB(1, 0), b3, voffB); PG8_STAGE(PG8_SB(1, 1), b3 + hstepB, voffB); PG8_STAGE(PG8_SA(1, 0), a3, voffA);
;             PG8_WAIT_V(8); PG8_WAIT_L(0); PG8_BAR; PG8_MMA(1, 0, At, B0); PG8_MMA(1, 1, At, B1); PG8_BAR; PG8_SCHED;
;         }
	s_add_i32 s0, s20, s61
	v_lshl_add_u64 v[144:145], v[144:145], 0, s[24:25]
	s_mov_b32 m0, s0
	ds_read_b128 v[176:179], v147 offset:49152
	ds_read_b128 v[180:183], v147 offset:50176
	ds_read_b128 v[184:187], v147 offset:51200
	ds_read_b128 v[188:191], v147 offset:52224
	ds_read_b128 v[196:199], v147 offset:53248
	ds_read_b128 v[200:203], v147 offset:54272
	ds_read_b128 v[204:207], v147 offset:55296
	ds_read_b128 v[208:211], v147 offset:56320
	global_load_lds_dwordx4 v[144:145], off
	s_add_i32 m0, s0, 0x2000
	s_add_u32 s0, s72, 0xb0080
	v_lshl_add_u64 v[144:145], v[192:193], 0, s[24:25]
	s_addc_u32 s1, s73, 0
	s_add_i32 s20, s26, s61
	global_load_lds_dwordx4 v[144:145], off
	v_lshl_add_u64 v[144:145], s[0:1], 0, v[0:1]
	s_mov_b32 m0, s20
	s_nop 0
	global_load_lds_dwordx4 v[144:145], off
	v_lshl_add_u64 v[144:145], s[0:1], 0, v[134:135]
	s_add_i32 m0, s20, 0x2000
	s_nop 0
	global_load_lds_dwordx4 v[144:145], off
	v_lshl_add_u64 v[144:145], v[212:213], 0, s[24:25]
	s_mov_b32 m0, s82
	s_nop 0
	global_load_lds_dwordx4 v[144:145], off
	v_lshl_add_u64 v[144:145], v[214:215], 0, s[24:25]
	s_mov_b32 m0, s83
	s_nop 0
	global_load_lds_dwordx4 v[144:145], off
	s_waitcnt vmcnt(8)
	s_waitcnt lgkmcnt(0)
	s_barrier
	v_mfma_f32_16x16x32_bf16 v[62:65], v[140:143], v[176:179], v[62:65]
	v_mfma_f32_16x16x32_bf16 v[58:61], v[152:155], v[176:179], v[58:61]
	v_mfma_f32_16x16x32_bf16 v[46:49], v[140:143], v[184:187], v[46:49]
	v_mfma_f32_16x16x32_bf16 v[42:45], v[152:155], v[184:187], v[42:45]
	v_mfma_f32_16x16x32_bf16 v[30:33], v[140:143], v[196:199], v[30:33]
	v_mfma_f32_16x16x32_bf16 v[26:29], v[152:155], v[196:199], v[26:29]
	v_mfma_f32_16x16x32_bf16 v[14:17], v[140:143], v[204:207], v[14:17]
	v_mfma_f32_16x16x32_bf16 v[10:13], v[152:155], v[204:207], v[10:13]
	v_mfma_f32_16x16x32_bf16 v[62:65], v[148:151], v[180:183], v[62:65]
	v_mfma_f32_16x16x32_bf16 v[58:61], v[156:159], v[180:183], v[58:61]
	v_mfma_f32_16x16x32_bf16 v[46:49], v[148:151], v[188:191], v[46:49]
	v_mfma_f32_16x16x32_bf16 v[42:45], v[156:159], v[188:191], v[42:45]
	v_mfma_f32_16x16x32_bf16 v[30:33], v[148:151], v[200:203], v[30:33]
	v_mfma_f32_16x16x32_bf16 v[26:29], v[156:159], v[200:203], v[26:29]
	v_mfma_f32_16x16x32_bf16 v[14:17], v[148:151], v[208:211], v[14:17]
	v_mfma_f32_16x16x32_bf16 v[10:13], v[156:159], v[208:211], v[10:13]
	v_mfma_f32_16x16x32_bf16 v[54:57], v[160:163], v[176:179], v[54:57]
	v_mfma_f32_16x16x32_bf16 v[50:53], v[168:171], v[176:179], v[50:53]
	v_mfma_f32_16x16x32_bf16 v[38:41], v[160:163], v[184:187], v[38:41]
	v_mfma_f32_16x16x32_bf16 v[34:37], v[168:171], v[184:187], v[34:37]
	v_mfma_f32_16x16x32_bf16 v[22:25], v[160:163], v[196:199], v[22:25]
	v_mfma_f32_16x16x32_bf16 v[18:21], v[168:171], v[196:199], v[18:21]
	v_mfma_f32_16x16x32_bf16 v[6:9], v[160:163], v[204:207], v[6:9]
	v_mfma_f32_16x16x32_bf16 v[2:5], v[168:171], v[204:207], v[2:5]
	v_mfma_f32_16x16x32_bf16 v[54:57], v[164:167], v[180:183], v[54:57]
	v_mfma_f32_16x16x32_bf16 v[50:53], v[172:175], v[180:183], v[50:53]
	v_mfma_f32_16x16x32_bf16 v[38:41], v[164:167], v[188:191], v[38:41]
	v_mfma_f32_16x16x32_bf16 v[34:37], v[172:175], v[188:191], v[34:37]
	v_mfma_f32_16x16x32_bf16 v[22:25], v[164:167], v[200:203], v[22:25]
	v_mfma_f32_16x16x32_bf16 v[18:21], v[172:175], v[200:203], v[18:21]
	v_mfma_f32_16x16x32_bf16 v[6:9], v[164:167], v[208:211], v[6:9]
	v_mfma_f32_16x16x32_bf16 v[2:5], v[172:175], v[208:211], v[2:5]
	s_barrier
	s_add_i32 s31, s31, 2
	s_add_u32 s11, s11, 0x100
	s_addc_u32 s21, s21, 0
	s_cmp_gt_u32 s31, 41
	s_mov_b64 s[68:69], s[70:71]
	s_cbranch_scc0 .LBB0_174
	s_and_b64 vcc, exec, s[64:65]
	s_cbranch_vccz .LBB0_177
	s_barrier

; #define PG8_STAGE(bufoff, gbase, voff) do { _Pragma("unroll") for (int _i = 0; _i < 2; ++_i) \
;         __builtin_amdgcn_global_load_lds((const unsigned*)((const char*)(gbase) + (voff)[_i]), (LAS unsigned*)(lds + (bufoff) + ldsw + _i * 8192), 16, 0, 0); } while (0)
; #define PG8_LDA(dst, b, h) do { _Pragma("unroll") for (int m = 0; m < 4; ++m) _Pragma("unroll") for (int k = 0; k < 2; ++k) dst[m][k] = *(const LAS bf16x8*)(lds + PG8_SA(b, h) + aoff + m * 2048 + k * 1024); } while (0)
; #define PG8_LDB(dst, b, h) do { _Pragma("unroll") for (int n = 0; n < 2; ++n) _Pragma("unroll") for (int k = 0; k < 2; ++k) dst[n][k] = *(const LAS bf16x8*)(lds + PG8_SB(b, h) + boff + n * 2048 + k * 1024); } while (0)
; #define PG8_MMA(ai, bj, At, Bt) do { __builtin_amdgcn_s_setprio(1); _Pragma("unroll") for (int m = 0; m < 4; ++m) _Pragma("unroll") for (int n = 0; n < 2; ++n) _Pragma("unroll") for (int k = 0; k < 2; ++k) \
;         acc[ai][bj][m][n] = __builtin_amdgcn_mfma_f32_16x16x32_bf16(Bt[n][k], At[m][k], acc[ai][bj][m][n], 0, 0, 0); __builtin_amdgcn_s_setprio(0); } while (0)
; #define PG8_WAIT_V(n) asm volatile("s_waitcnt vmcnt(" #n ")" ::: "memory")
; #define PG8_WAIT_L(n) asm volatile("s_waitcnt lgkmcnt(" #n ")" ::: "memory")
; #define PG8_BAR __builtin_amdgcn_s_barrier()
; #define PG8_SCHED __builtin_amdgcn_sched_barrier(0)
; template <class Epi, class Sched>
; __device__ __forceinline__ void gemm_phase(LAS unsigned char* lds, const Gemm g, const Sched& S, const Epi& E, int wv) {
;     ...
;         const char* nA = has_next ? (const char*)g.A + (size_t)nxt.pm * tstepA + (size_t)nxt.ak * 2 : cA; const char* nB = has_next ? (const char*)g.Bt + (size_t)nxt.pn * tstepB : cB;
;         for (int t = 0; t < nt; t += 2) {
;             const bool last = (t == nt - 2);
;             const char* a1 = cA + (size_t)(t + 1) * kstep;
;             const char* a2 = last ? nA : cA + (size_t)(t + 2) * kstep; const char* b2 = last ? nB : cB + (size_t)(t + 2) * kstep;
;             const char* a3 = a2 + kstep; const char* b3 = b2 + kstep;
;             PG8_LDB(B0, 0, 0); PG8_LDB(B1, 0, 1); PG8_SCHED; PG8_LDA(At, 0, 0); PG8_STAGE(PG8_SA(1, 1), a1 + hstepA, voffA);
;             PG8_WAIT_V(8); PG8_WAIT_L(0); PG8_BAR; PG8_MMA(0, 0, At, B0); PG8_MMA(0, 1, At, B1); PG8_BAR; PG8_SCHED;
.LBB0_225:
	s_add_u32 s20, s70, s35
	s_addc_u32 s26, s71, 0
	s_add_u32 s27, s20, 0x100
	s_addc_u32 s33, s26, 0
	s_and_b64 s[0:1], s[82:83], exec
	s_cselect_b32 s87, s75, s33
	s_cselect_b32 s86, s31, s27
	s_add_u32 s0, s68, s35
	s_addc_u32 s1, s69, 0
	s_add_u32 s27, s0, 0x100
	s_addc_u32 s33, s1, 0
	s_add_i32 s58, 0, 0x10000
	s_and_b64 s[0:1], s[82:83], exec
	s_cselect_b32 s89, s73, s33
	s_cselect_b32 s88, s34, s27
	s_add_i32 s27, 0, 0x14000
	s_add_u32 s92, s20, 0x10080
	s_addc_u32 s93, s26, 0
	s_add_i32 s1, s58, s61
	s_add_i32 m0, s62, 0xc000
	s_add_i32 s59, s62, 0xe000
	s_add_i32 s53, s1, 0x2000
	s_add_u32 s90, s88, 0x10000
	v_add_u32_e32 v150, s58, v136
	v_add_u32_e32 v166, s27, v136
	s_addc_u32 s91, s89, 0
	s_add_i32 s0, s27, s61
	ds_read_b128 v[138:141], v150
	ds_read_b128 v[142:145], v150 offset:1024
	ds_read_b128 v[146:149], v150 offset:2048
	ds_read_b128 v[150:153], v150 offset:3072
	ds_read_b128 v[154:157], v166
	ds_read_b128 v[158:161], v166 offset:1024
	ds_read_b128 v[162:165], v166 offset:2048
	ds_read_b128 v[166:169], v166 offset:3072
	s_add_i32 s20, s0, 0x2000
	s_add_i32 vcc_lo, 0, 0x18000
	s_add_i32 vcc_hi, 0, 0x1c000
	s_add_u32 s84, s86, 0x10000
	s_addc_u32 s85, s87, 0
	s_add_i32 s35, vcc_lo, s61
	s_add_i32 s95, s35, 0x2000
	s_add_u32 s82, s88, 0x10080
	s_addc_u32 s83, s89, 0
	s_add_i32 s33, vcc_hi, s61
	s_add_i32 s26, s33, 0x2000
	v_lshl_add_u64 v[204:205], s[92:93], 0, v[130:131]
	ds_read_b128 v[170:173], v137
	ds_read_b128 v[174:177], v137 offset:1024
	ds_read_b128 v[178:181], v137 offset:2048
	ds_read_b128 v[182:185], v137 offset:3072
	ds_read_b128 v[186:189], v137 offset:4096
	ds_read_b128 v[190:193], v137 offset:5120
	ds_read_b128 v[196:199], v137 offset:6144
	ds_read_b128 v[200:203], v137 offset:7168
	global_load_lds_dwordx4 v[204:205], off
	v_lshl_add_u64 v[204:205], s[92:93], 0, v[132:133]
	s_mov_b32 m0, s59
	s_nop 0
	global_load_lds_dwordx4 v[204:205], off
	s_waitcnt vmcnt(8)
	s_waitcnt lgkmcnt(0)
	s_barrier
	v_mfma_f32_16x16x32_bf16 v[126:129], v[138:141], v[170:173], v[126:129]
	v_mfma_f32_16x16x32_bf16 v[122:125], v[146:149], v[170:173], v[122:125]
	v_mfma_f32_16x16x32_bf16 v[118:121], v[138:141], v[178:181], v[118:121]
	v_mfma_f32_16x16x32_bf16 v[114:117], v[146:149], v[178:181], v[114:117]
	v_mfma_f32_16x16x32_bf16 v[102:105], v[138:141], v[186:189], v[102:105]
	v_mfma_f32_16x16x32_bf16 v[98:101], v[146:149], v[186:189], v[98:101]
	v_mfma_f32_16x16x32_bf16 v[86:89], v[138:141], v[196:199], v[86:89]
	v_mfma_f32_16x16x32_bf16 v[82:85], v[146:149], v[196:199], v[82:85]
	v_mfma_f32_16x16x32_bf16 v[126:129], v[142:145], v[174:177], v[126:129]
	v_mfma_f32_16x16x32_bf16 v[122:125], v[150:153], v[174:177], v[122:125]
	v_mfma_f32_16x16x32_bf16 v[118:121], v[142:145], v[182:185], v[118:121]
	v_mfma_f32_16x16x32_bf16 v[114:117], v[150:153], v[182:185], v[114:117]
	v_mfma_f32_16x16x32_bf16 v[102:105], v[142:145], v[190:193], v[102:105]
	v_mfma_f32_16x16x32_bf16 v[98:101], v[150:153], v[190:193], v[98:101]
	v_mfma_f32_16x16x32_bf16 v[86:89], v[142:145], v[200:203], v[86:89]
	v_mfma_f32_16x16x32_bf16 v[82:85], v[150:153], v[200:203], v[82:85]
	v_mfma_f32_16x16x32_bf16 v[110:113], v[154:157], v[170:173], v[110:113]
	v_mfma_f32_16x16x32_bf16 v[106:109], v[162:165], v[170:173], v[106:109]
	v_mfma_f32_16x16x32_bf16 v[94:97], v[154:157], v[178:181], v[94:97]
	v_mfma_f32_16x16x32_bf16 v[90:93], v[162:165], v[178:181], v[90:93]
	v_mfma_f32_16x16x32_bf16 v[78:81], v[154:157], v[186:189], v[78:81]
	v_mfma_f32_16x16x32_bf16 v[74:77], v[162:165], v[186:189], v[74:77]
	v_mfma_f32_16x16x32_bf16 v[70:73], v[154:157], v[196:199], v[70:73]
	v_mfma_f32_16x16x32_bf16 v[66:69], v[162:165], v[196:199], v[66:69]
	v_mfma_f32_16x16x32_bf16 v[110:113], v[158:161], v[174:177], v[110:113]
	v_mfma_f32_16x16x32_bf16 v[106:109], v[166:169], v[174:177], v[106:109]
	v_mfma_f32_16x16x32_bf16 v[94:97], v[158:161], v[182:185], v[94:97]
	v_mfma_f32_16x16x32_bf16 v[90:93], v[166:169], v[182:185], v[90:93]
	v_mfma_f32_16x16x32_bf16 v[78:81], v[158:161], v[190:193], v[78:81]
	v_mfma_f32_16x16x32_bf16 v[74:77], v[166:169], v[190:193], v[74:77]
	v_mfma_f32_16x16x32_bf16 v[70:73], v[158:161], v[200:203], v[70:73]
	v_mfma_f32_16x16x32_bf16 v[66:69], v[166:169], v[200:203], v[66:69]
	s_barrier
	s_mov_b32 m0, s1
	v_lshl_add_u64 v[204:205], s[88:89], 0, v[0:1]
	ds_read_b128 v[170:173], v137 offset:16384
	ds_read_b128 v[174:177], v137 offset:17408
	ds_read_b128 v[178:181], v137 offset:18432
	ds_read_b128 v[182:185], v137 offset:19456
	ds_read_b128 v[186:189], v137 offset:20480
	ds_read_b128 v[190:193], v137 offset:21504
	ds_read_b128 v[196:199], v137 offset:22528
	ds_read_b128 v[200:203], v137 offset:23552
	global_load_lds_dwordx4 v[204:205], off
	v_lshl_add_u64 v[206:207], s[88:89], 0, v[134:135]
	s_mov_b32 m0, s53
	v_lshl_add_u64 v[208:209], s[90:91], 0, v[0:1]
	global_load_lds_dwordx4 v[206:207], off
	s_mov_b32 m0, s0
	v_lshl_add_u64 v[210:211], s[86:87], 0, v[132:133]
	global_load_lds_dwordx4 v[208:209], off
	v_lshl_add_u64 v[208:209], s[90:91], 0, v[134:135]
	s_mov_b32 m0, s20
	s_nop 0
	global_load_lds_dwordx4 v[208:209], off
	v_lshl_add_u64 v[208:209], s[86:87], 0, v[130:131]
	s_mov_b32 m0, s62
	s_nop 0
	global_load_lds_dwordx4 v[208:209], off
	s_mov_b32 m0, s65
	s_nop 0
	global_load_lds_dwordx4 v[210:211], off
	s_waitcnt vmcnt(8)
	s_waitcnt lgkmcnt(0)
	s_barrier
; #define PG8_STAGE(bufoff, gbase, voff) do { _Pragma("unroll") for (int _i = 0; _i < 2; ++_i) \
;         __builtin_amdgcn_global_load_lds((const unsigned*)((const char*)(gbase) + (voff)[_i]), (LAS unsigned*)(lds + (bufoff) + ldsw + _i * 8192), 16, 0, 0); } while (0)
; #define PG8_LDA(dst, b, h) do { _Pragma("unroll") for (int m = 0; m < 4; ++m) _Pragma("unroll") for (int k = 0; k < 2; ++k) dst[m][k] = *(const LAS bf16x8*)(lds + PG8_SA(b, h) + aoff + m * 2048 + k * 1024); } while (0)
; #define PG8_LDB(dst, b, h) do { _Pragma("unroll") for (int n = 0; n < 2; ++n) _Pragma("unroll") for (int k = 0; k < 2; ++k) dst[n][k] = *(const LAS bf16x8*)(lds + PG8_SB(b, h) + boff + n * 2048 + k * 1024); } while (0)
; #define PG8_MMA(ai, bj, At, Bt) do { __builtin_amdgcn_s_setprio(1); _Pragma("unroll") for (int m = 0; m < 4; ++m) _Pragma("unroll") for (int n = 0; n < 2; ++n) _Pragma("unroll") for (int k = 0; k < 2; ++k) \
;         acc[ai][bj][m][n] = __builtin_amdgcn_mfma_f32_16x16x32_bf16(Bt[n][k], At[m][k], acc[ai][bj][m][n], 0, 0, 0); __builtin_amdgcn_s_setprio(0); } while (0)
; #define PG8_WAIT_V(n) asm volatile("s_waitcnt vmcnt(" #n ")" ::: "memory")
; #define PG8_WAIT_L(n) asm volatile("s_waitcnt lgkmcnt(" #n ")" ::: "memory")
; #define PG8_BAR __builtin_amdgcn_s_barrier()
; #define PG8_SCHED __builtin_amdgcn_sched_barrier(0)
; template <class Epi, class Sched>
; __device__ __forceinline__ void gemm_phase(LAS unsigned char* lds, const Gemm g, const Sched& S, const Epi& E, int wv) {
;     ...
;             PG8_LDA(At, 0, 1); PG8_STAGE(PG8_SB(0, 0), b2, voffB); PG8_STAGE(PG8_SB(0, 1), b2 + hstepB, voffB); PG8_STAGE(PG8_SA(0, 0), a2, voffA);
;             PG8_WAIT_V(8); PG8_WAIT_L(0); PG8_BAR; PG8_MMA(1, 0, At, B0); PG8_MMA(1, 1, At, B1); PG8_BAR; PG8_SCHED;
;             PG8_LDB(B0, 1, 0); PG8_LDB(B1, 1, 1); PG8_SCHED; PG8_LDA(At, 1, 0); PG8_STAGE(PG8_SA(0, 1), a2 + hstepA, voffA);
;             PG8_WAIT_V(8); PG8_WAIT_L(0); PG8_BAR; PG8_MMA(0, 0, At, B0); PG8_MMA(0, 1, At, B1); PG8_BAR; PG8_SCHED;
	v_mfma_f32_16x16x32_bf16 v[62:65], v[138:141], v[170:173], v[62:65]
	v_mfma_f32_16x16x32_bf16 v[58:61], v[146:149], v[170:173], v[58:61]
	v_mfma_f32_16x16x32_bf16 v[54:57], v[138:141], v[178:181], v[54:57]
	v_mfma_f32_16x16x32_bf16 v[50:53], v[146:149], v[178:181], v[50:53]
	v_mfma_f32_16x16x32_bf16 v[38:41], v[138:141], v[186:189], v[38:41]
	v_mfma_f32_16x16x32_bf16 v[34:37], v[146:149], v[186:189], v[34:37]
	v_mfma_f32_16x16x32_bf16 v[22:25], v[138:141], v[196:199], v[22:25]
	v_mfma_f32_16x16x32_bf16 v[18:21], v[146:149], v[196:199], v[18:21]
	v_mfma_f32_16x16x32_bf16 v[62:65], v[142:145], v[174:177], v[62:65]
	v_mfma_f32_16x16x32_bf16 v[58:61], v[150:153], v[174:177], v[58:61]
	v_mfma_f32_16x16x32_bf16 v[54:57], v[142:145], v[182:185], v[54:57]
	v_mfma_f32_16x16x32_bf16 v[50:53], v[150:153], v[182:185], v[50:53]
	v_mfma_f32_16x16x32_bf16 v[38:41], v[142:145], v[190:193], v[38:41]
	v_mfma_f32_16x16x32_bf16 v[34:37], v[150:153], v[190:193], v[34:37]
	v_mfma_f32_16x16x32_bf16 v[22:25], v[142:145], v[200:203], v[22:25]
	v_mfma_f32_16x16x32_bf16 v[18:21], v[150:153], v[200:203], v[18:21]
	v_mfma_f32_16x16x32_bf16 v[46:49], v[154:157], v[170:173], v[46:49]
	v_mfma_f32_16x16x32_bf16 v[42:45], v[162:165], v[170:173], v[42:45]
	v_mfma_f32_16x16x32_bf16 v[30:33], v[154:157], v[178:181], v[30:33]
	v_mfma_f32_16x16x32_bf16 v[26:29], v[162:165], v[178:181], v[26:29]
	v_mfma_f32_16x16x32_bf16 v[14:17], v[154:157], v[186:189], v[14:17]
	v_mfma_f32_16x16x32_bf16 v[10:13], v[162:165], v[186:189], v[10:13]
	v_mfma_f32_16x16x32_bf16 v[6:9], v[154:157], v[196:199], v[6:9]
	v_mfma_f32_16x16x32_bf16 v[2:5], v[162:165], v[196:199], v[2:5]
	v_mfma_f32_16x16x32_bf16 v[46:49], v[158:161], v[174:177], v[46:49]
	v_mfma_f32_16x16x32_bf16 v[42:45], v[166:169], v[174:177], v[42:45]
	v_mfma_f32_16x16x32_bf16 v[30:33], v[158:161], v[182:185], v[30:33]
	v_mfma_f32_16x16x32_bf16 v[26:29], v[166:169], v[182:185], v[26:29]
	v_mfma_f32_16x16x32_bf16 v[14:17], v[158:161], v[190:193], v[14:17]
	v_mfma_f32_16x16x32_bf16 v[10:13], v[166:169], v[190:193], v[10:13]
	v_mfma_f32_16x16x32_bf16 v[6:9], v[158:161], v[200:203], v[6:9]
	v_mfma_f32_16x16x32_bf16 v[2:5], v[166:169], v[200:203], v[2:5]
	s_barrier
	v_add_u32_e32 v150, vcc_lo, v136
	v_add_u32_e32 v166, vcc_hi, v136
	ds_read_b128 v[138:141], v150
	ds_read_b128 v[142:145], v150 offset:1024
	ds_read_b128 v[146:149], v150 offset:2048
	ds_read_b128 v[150:153], v150 offset:3072
	ds_read_b128 v[154:157], v166
	ds_read_b128 v[158:161], v166 offset:1024
	ds_read_b128 v[162:165], v166 offset:2048
	ds_read_b128 v[166:169], v166 offset:3072
	s_mov_b32 m0, s67
	v_lshl_add_u64 v[212:213], s[84:85], 0, v[130:131]
	ds_read_b128 v[170:173], v137 offset:32768
	ds_read_b128 v[174:177], v137 offset:33792
	ds_read_b128 v[178:181], v137 offset:34816
	ds_read_b128 v[182:185], v137 offset:35840
	ds_read_b128 v[186:189], v137 offset:36864
	ds_read_b128 v[190:193], v137 offset:37888
	ds_read_b128 v[196:199], v137 offset:38912
	ds_read_b128 v[200:203], v137 offset:39936
	global_load_lds_dwordx4 v[212:213], off
	v_lshl_add_u64 v[212:213], s[84:85], 0, v[132:133]
	s_mov_b32 m0, s96
	s_nop 0
	global_load_lds_dwordx4 v[212:213], off
	s_waitcnt vmcnt(8)
	s_waitcnt lgkmcnt(0)
	s_barrier
	v_mfma_f32_16x16x32_bf16 v[126:129], v[138:141], v[170:173], v[126:129]
	v_mfma_f32_16x16x32_bf16 v[122:125], v[146:149], v[170:173], v[122:125]
	v_mfma_f32_16x16x32_bf16 v[118:121], v[138:141], v[178:181], v[118:121]
	v_mfma_f32_16x16x32_bf16 v[114:117], v[146:149], v[178:181], v[114:117]
	v_mfma_f32_16x16x32_bf16 v[102:105], v[138:141], v[186:189], v[102:105]
	v_mfma_f32_16x16x32_bf16 v[98:101], v[146:149], v[186:189], v[98:101]
	v_mfma_f32_16x16x32_bf16 v[86:89], v[138:141], v[196:199], v[86:89]
	v_mfma_f32_16x16x32_bf16 v[82:85], v[146:149], v[196:199], v[82:85]
	v_mfma_f32_16x16x32_bf16 v[126:129], v[142:145], v[174:177], v[126:129]
	v_mfma_f32_16x16x32_bf16 v[122:125], v[150:153], v[174:177], v[122:125]
	v_mfma_f32_16x16x32_bf16 v[118:121], v[142:145], v[182:185], v[118:121]
	v_mfma_f32_16x16x32_bf16 v[114:117], v[150:153], v[182:185], v[114:117]
	v_mfma_f32_16x16x32_bf16 v[102:105], v[142:145], v[190:193], v[102:105]
	v_mfma_f32_16x16x32_bf16 v[98:101], v[150:153], v[190:193], v[98:101]
	v_mfma_f32_16x16x32_bf16 v[86:89], v[142:145], v[200:203], v[86:89]
	v_mfma_f32_16x16x32_bf16 v[82:85], v[150:153], v[200:203], v[82:85]
	v_mfma_f32_16x16x32_bf16 v[110:113], v[154:157], v[170:173], v[110:113]
	v_mfma_f32_16x16x32_bf16 v[106:109], v[162:165], v[170:173], v[106:109]
	v_mfma_f32_16x16x32_bf16 v[94:97], v[154:157], v[178:181], v[94:97]
	v_mfma_f32_16x16x32_bf16 v[90:93], v[162:165], v[178:181], v[90:93]
	v_mfma_f32_16x16x32_bf16 v[78:81], v[154:157], v[186:189], v[78:81]
	v_mfma_f32_16x16x32_bf16 v[74:77], v[162:165], v[186:189], v[74:77]
	v_mfma_f32_16x16x32_bf16 v[70:73], v[154:157], v[196:199], v[70:73]
	v_mfma_f32_16x16x32_bf16 v[66:69], v[162:165], v[196:199], v[66:69]
	v_mfma_f32_16x16x32_bf16 v[110:113], v[158:161], v[174:177], v[110:113]
	v_mfma_f32_16x16x32_bf16 v[106:109], v[166:169], v[174:177], v[106:109]
	v_mfma_f32_16x16x32_bf16 v[94:97], v[158:161], v[182:185], v[94:97]
	v_mfma_f32_16x16x32_bf16 v[90:93], v[166:169], v[182:185], v[90:93]
	v_mfma_f32_16x16x32_bf16 v[78:81], v[158:161], v[190:193], v[78:81]
	v_mfma_f32_16x16x32_bf16 v[74:77], v[166:169], v[190:193], v[74:77]
	v_mfma_f32_16x16x32_bf16 v[70:73], v[158:161], v[200:203], v[70:73]
	v_mfma_f32_16x16x32_bf16 v[66:69], v[166:169], v[200:203], v[66:69]
	s_barrier
; #define PG8_STAGE(bufoff, gbase, voff) do { _Pragma("unroll") for (int _i = 0; _i < 2; ++_i) \
;         __builtin_amdgcn_global_load_lds((const unsigned*)((const char*)(gbase) + (voff)[_i]), (LAS unsigned*)(lds + (bufoff) + ldsw + _i * 8192), 16, 0, 0); } while (0)
; #define PG8_LDA(dst, b, h) do { _Pragma("unroll") for (int m = 0; m < 4; ++m) _Pragma("unroll") for (int k = 0; k < 2; ++k) dst[m][k] = *(const LAS bf16x8*)(lds + PG8_SA(b, h) + aoff + m * 2048 + k * 1024); } while (0)
; #define PG8_MMA(ai, bj, At, Bt) do { __builtin_amdgcn_s_setprio(1); _Pragma("unroll") for (int m = 0; m < 4; ++m) _Pragma("unroll") for (int n = 0; n < 2; ++n) _Pragma("unroll") for (int k = 0; k < 2; ++k) \
;         acc[ai][bj][m][n] = __builtin_amdgcn_mfma_f32_16x16x32_bf16(Bt[n][k], At[m][k], acc[ai][bj][m][n], 0, 0, 0); __builtin_amdgcn_s_setprio(0); } while (0)
; #define PG8_WAIT_V(n) asm volatile("s_waitcnt vmcnt(" #n ")" ::: "memory")
; #define PG8_WAIT_L(n) asm volatile("s_waitcnt lgkmcnt(" #n ")" ::: "memory")
; #define PG8_BAR __builtin_amdgcn_s_barrier()
; #define PG8_SCHED __builtin_amdgcn_sched_barrier(0)
; template <class Epi, class Sched>
; __device__ __forceinline__ void gemm_phase(LAS unsigned char* lds, const Gemm g, const Sched& S, const Epi& E, int wv) {
;     ...
;             PG8_LDA(At, 1, 1); PG8_STAGE(PG8_SB(1, 0), b3, voffB); PG8_STAGE(PG8_SB(1, 1), b3 + hstepB, voffB); PG8_STAGE(PG8_SA(1, 0), a3, voffA);
;             PG8_WAIT_V(8); PG8_WAIT_L(0); PG8_BAR; PG8_MMA(1, 0, At, B0); PG8_MMA(1, 1, At, B1); PG8_BAR; PG8_SCHED;
;         }
;         if (wr == 0) PG8_BAR;
;         E(acc, cur, wv);
;         if (!has_next) break;
	s_mov_b32 m0, s35
	v_lshl_add_u64 v[204:205], v[204:205], 0, s[24:25]
	ds_read_b128 v[170:173], v137 offset:49152
	ds_read_b128 v[174:177], v137 offset:50176
	ds_read_b128 v[178:181], v137 offset:51200
	ds_read_b128 v[182:185], v137 offset:52224
	ds_read_b128 v[186:189], v137 offset:53248
	ds_read_b128 v[190:193], v137 offset:54272
	ds_read_b128 v[196:199], v137 offset:55296
	ds_read_b128 v[200:203], v137 offset:56320
	global_load_lds_dwordx4 v[204:205], off
	v_lshl_add_u64 v[204:205], v[206:207], 0, s[24:25]
	s_mov_b32 m0, s95
	s_nop 0
	global_load_lds_dwordx4 v[204:205], off
	v_lshl_add_u64 v[204:205], s[82:83], 0, v[0:1]
	s_mov_b32 m0, s33
	s_nop 0
	global_load_lds_dwordx4 v[204:205], off
	v_lshl_add_u64 v[204:205], s[82:83], 0, v[134:135]
	s_mov_b32 m0, s26
	s_nop 0
	global_load_lds_dwordx4 v[204:205], off
	v_lshl_add_u64 v[204:205], v[208:209], 0, s[24:25]
	s_mov_b32 m0, s94
	s_nop 0
	global_load_lds_dwordx4 v[204:205], off
	v_lshl_add_u64 v[204:205], v[210:211], 0, s[24:25]
	s_mov_b32 m0, s10
	s_nop 0
	global_load_lds_dwordx4 v[204:205], off
	s_waitcnt vmcnt(8)
	s_waitcnt lgkmcnt(0)
	s_barrier
	v_mfma_f32_16x16x32_bf16 v[62:65], v[138:141], v[170:173], v[62:65]
	v_mfma_f32_16x16x32_bf16 v[58:61], v[146:149], v[170:173], v[58:61]
	v_mfma_f32_16x16x32_bf16 v[54:57], v[138:141], v[178:181], v[54:57]
	v_mfma_f32_16x16x32_bf16 v[50:53], v[146:149], v[178:181], v[50:53]
	v_mfma_f32_16x16x32_bf16 v[38:41], v[138:141], v[186:189], v[38:41]
	v_mfma_f32_16x16x32_bf16 v[34:37], v[146:149], v[186:189], v[34:37]
	v_mfma_f32_16x16x32_bf16 v[22:25], v[138:141], v[196:199], v[22:25]
	v_mfma_f32_16x16x32_bf16 v[18:21], v[146:149], v[196:199], v[18:21]
	v_mfma_f32_16x16x32_bf16 v[62:65], v[142:145], v[174:177], v[62:65]
	v_mfma_f32_16x16x32_bf16 v[58:61], v[150:153], v[174:177], v[58:61]
	v_mfma_f32_16x16x32_bf16 v[54:57], v[142:145], v[182:185], v[54:57]
	v_mfma_f32_16x16x32_bf16 v[50:53], v[150:153], v[182:185], v[50:53]
	v_mfma_f32_16x16x32_bf16 v[38:41], v[142:145], v[190:193], v[38:41]
	v_mfma_f32_16x16x32_bf16 v[34:37], v[150:153], v[190:193], v[34:37]
	v_mfma_f32_16x16x32_bf16 v[22:25], v[142:145], v[200:203], v[22:25]
	v_mfma_f32_16x16x32_bf16 v[18:21], v[150:153], v[200:203], v[18:21]
	v_mfma_f32_16x16x32_bf16 v[46:49], v[154:157], v[170:173], v[46:49]
	v_mfma_f32_16x16x32_bf16 v[42:45], v[162:165], v[170:173], v[42:45]
	v_mfma_f32_16x16x32_bf16 v[30:33], v[154:157], v[178:181], v[30:33]
	v_mfma_f32_16x16x32_bf16 v[26:29], v[162:165], v[178:181], v[26:29]
	v_mfma_f32_16x16x32_bf16 v[14:17], v[154:157], v[186:189], v[14:17]
	v_mfma_f32_16x16x32_bf16 v[10:13], v[162:165], v[186:189], v[10:13]
	v_mfma_f32_16x16x32_bf16 v[6:9], v[154:157], v[196:199], v[6:9]
	v_mfma_f32_16x16x32_bf16 v[2:5], v[162:165], v[196:199], v[2:5]
	v_mfma_f32_16x16x32_bf16 v[46:49], v[158:161], v[174:177], v[46:49]
	v_mfma_f32_16x16x32_bf16 v[42:45], v[166:169], v[174:177], v[42:45]
	v_mfma_f32_16x16x32_bf16 v[30:33], v[158:161], v[182:185], v[30:33]
	v_mfma_f32_16x16x32_bf16 v[26:29], v[166:169], v[182:185], v[26:29]
	v_mfma_f32_16x16x32_bf16 v[14:17], v[158:161], v[190:193], v[14:17]
	v_mfma_f32_16x16x32_bf16 v[10:13], v[166:169], v[190:193], v[10:13]
	v_mfma_f32_16x16x32_bf16 v[6:9], v[158:161], v[200:203], v[6:9]
	v_mfma_f32_16x16x32_bf16 v[2:5], v[166:169], v[200:203], v[2:5]
	s_barrier
	s_movk_i32 s35, 0x100
	s_andn2_b64 vcc, exec, s[80:81]
	s_mov_b64 s[82:83], -1
	s_mov_b64 s[80:81], 0
	s_cbranch_vccz .LBB0_225
	s_and_b64 vcc, exec, s[12:13]
	s_cbranch_vccz .LBB0_228
	s_barrier

; #define PG8_STAGE(bufoff, gbase, voff) do { _Pragma("unroll") for (int _i = 0; _i < 2; ++_i) \
;         __builtin_amdgcn_global_load_lds((const unsigned*)((const char*)(gbase) + (voff)[_i]), (LAS unsigned*)(lds + (bufoff) + ldsw + _i * 8192), 16, 0, 0); } while (0)
; #define PG8_LDA(dst, b, h) do { _Pragma("unroll") for (int m = 0; m < 4; ++m) _Pragma("unroll") for (int k = 0; k < 2; ++k) dst[m][k] = *(const LAS bf16x8*)(lds + PG8_SA(b, h) + aoff + m * 2048 + k * 1024); } while (0)
; #define PG8_LDB(dst, b, h) do { _Pragma("unroll") for (int n = 0; n < 2; ++n) _Pragma("unroll") for (int k = 0; k < 2; ++k) dst[n][k] = *(const LAS bf16x8*)(lds + PG8_SB(b, h) + boff + n * 2048 + k * 1024); } while (0)
; #define PG8_MMA(ai, bj, At, Bt) do { __builtin_amdgcn_s_setprio(1); _Pragma("unroll") for (int m = 0; m < 4; ++m) _Pragma("unroll") for (int n = 0; n < 2; ++n) _Pragma("unroll") for (int k = 0; k < 2; ++k) \
;         acc[ai][bj][m][n] = __builtin_amdgcn_mfma_f32_16x16x32_bf16(Bt[n][k], At[m][k], acc[ai][bj][m][n], 0, 0, 0); __builtin_amdgcn_s_setprio(0); } while (0)
; #define PG8_WAIT_V(n) asm volatile("s_waitcnt vmcnt(" #n ")" ::: "memory")
; #define PG8_WAIT_L(n) asm volatile("s_waitcnt lgkmcnt(" #n ")" ::: "memory")
; #define PG8_BAR __builtin_amdgcn_s_barrier()
; template <class Epi, class Sched>
; __device__ __forceinline__ void gemm_phase(LAS unsigned char* lds, const Gemm g, const Sched& S, const Epi& E, int wv) {
;     ...
;         const char* nA = has_next ? (const char*)g.A + (size_t)nxt.pm * tstepA + (size_t)nxt.ak * 2 : cA; const char* nB = has_next ? (const char*)g.Bt + (size_t)nxt.pn * tstepB : cB;
;         for (int t = 0; t < nt; t += 2) {
;             const bool last = (t == nt - 2);
;             const char* a1 = cA + (size_t)(t + 1) * kstep;
;             const char* a2 = last ? nA : cA + (size_t)(t + 2) * kstep; const char* b2 = last ? nB : cB + (size_t)(t + 2) * kstep;
;             const char* a3 = a2 + kstep; const char* b3 = b2 + kstep;
;             PG8_LDB(B0, 0, 0); PG8_LDB(B1, 0, 1); PG8_SCHED; PG8_LDA(At, 0, 0); PG8_STAGE(PG8_SA(1, 1), a1 + hstepA, voffA);
;             PG8_WAIT_V(8); PG8_WAIT_L(0); PG8_BAR; PG8_MMA(0, 0, At, B0); PG8_MMA(0, 1, At, B1); PG8_BAR; PG8_SCHED;
;             PG8_LDA(At, 0, 1); PG8_STAGE(PG8_SB(0, 0), b2, voffB); PG8_STAGE(PG8_SB(0, 1), b2 + hstepB, voffB); PG8_STAGE(PG8_SA(0, 0), a2, voffA);
.LBB0_252:
	s_add_u32 s0, s74, 0xfffc0080
	s_addc_u32 s1, s75, -1
	s_add_i32 s20, 0, 0x10000
	s_cmp_eq_u32 s56, 12
	s_cselect_b32 s79, s10, s1
	s_cselect_b32 s78, s11, s0
	v_add_u32_e32 v144, s20, v146
	s_cselect_b32 s77, s21, s35
	s_cselect_b32 s76, s31, s34
	s_add_i32 s26, 0, 0x14000
	ds_read_b128 v[140:143], v144
	ds_read_b128 v[148:151], v144 offset:1024
	ds_read_b128 v[152:155], v144 offset:2048
	ds_read_b128 v[156:159], v144 offset:3072
	v_add_u32_e32 v144, s26, v146
	ds_read_b128 v[160:163], v144
	ds_read_b128 v[164:167], v144 offset:1024
	ds_read_b128 v[168:171], v144 offset:2048
	ds_read_b128 v[172:175], v144 offset:3072
	v_lshl_add_u64 v[144:145], s[74:75], 0, v[136:137]
	s_add_i32 m0, s62, 0xc000
	ds_read_b128 v[176:179], v147
	ds_read_b128 v[180:183], v147 offset:1024
	ds_read_b128 v[184:187], v147 offset:2048
	ds_read_b128 v[188:191], v147 offset:3072
	ds_read_b128 v[196:199], v147 offset:4096
	ds_read_b128 v[200:203], v147 offset:5120
	ds_read_b128 v[204:207], v147 offset:6144
	ds_read_b128 v[208:211], v147 offset:7168
	global_load_lds_dwordx4 v[144:145], off
	v_lshl_add_u64 v[144:145], s[74:75], 0, v[138:139]
	s_add_i32 m0, s62, 0xe000
	s_nop 0
	global_load_lds_dwordx4 v[144:145], off
	s_waitcnt vmcnt(8)
	s_waitcnt lgkmcnt(0)
	s_barrier
	v_mfma_f32_16x16x32_bf16 v[126:129], v[140:143], v[176:179], v[126:129]
	v_mfma_f32_16x16x32_bf16 v[122:125], v[152:155], v[176:179], v[122:125]
	v_mfma_f32_16x16x32_bf16 v[110:113], v[140:143], v[184:187], v[110:113]
	v_mfma_f32_16x16x32_bf16 v[106:109], v[152:155], v[184:187], v[106:109]
	v_mfma_f32_16x16x32_bf16 v[94:97], v[140:143], v[196:199], v[94:97]
	v_mfma_f32_16x16x32_bf16 v[90:93], v[152:155], v[196:199], v[90:93]
	v_mfma_f32_16x16x32_bf16 v[78:81], v[140:143], v[204:207], v[78:81]
	v_mfma_f32_16x16x32_bf16 v[74:77], v[152:155], v[204:207], v[74:77]
	v_mfma_f32_16x16x32_bf16 v[126:129], v[148:151], v[180:183], v[126:129]
	v_mfma_f32_16x16x32_bf16 v[122:125], v[156:159], v[180:183], v[122:125]
	v_mfma_f32_16x16x32_bf16 v[110:113], v[148:151], v[188:191], v[110:113]
	v_mfma_f32_16x16x32_bf16 v[106:109], v[156:159], v[188:191], v[106:109]
	v_mfma_f32_16x16x32_bf16 v[94:97], v[148:151], v[200:203], v[94:97]
	v_mfma_f32_16x16x32_bf16 v[90:93], v[156:159], v[200:203], v[90:93]
	v_mfma_f32_16x16x32_bf16 v[78:81], v[148:151], v[208:211], v[78:81]
	v_mfma_f32_16x16x32_bf16 v[74:77], v[156:159], v[208:211], v[74:77]
	v_mfma_f32_16x16x32_bf16 v[118:121], v[160:163], v[176:179], v[118:121]
	v_mfma_f32_16x16x32_bf16 v[114:117], v[168:171], v[176:179], v[114:117]
	v_mfma_f32_16x16x32_bf16 v[102:105], v[160:163], v[184:187], v[102:105]
	v_mfma_f32_16x16x32_bf16 v[98:101], v[168:171], v[184:187], v[98:101]
	v_mfma_f32_16x16x32_bf16 v[86:89], v[160:163], v[196:199], v[86:89]
	v_mfma_f32_16x16x32_bf16 v[82:85], v[168:171], v[196:199], v[82:85]
	v_mfma_f32_16x16x32_bf16 v[70:73], v[160:163], v[204:207], v[70:73]
	v_mfma_f32_16x16x32_bf16 v[66:69], v[168:171], v[204:207], v[66:69]
	v_mfma_f32_16x16x32_bf16 v[118:121], v[164:167], v[180:183], v[118:121]
	v_mfma_f32_16x16x32_bf16 v[114:117], v[172:175], v[180:183], v[114:117]
	v_mfma_f32_16x16x32_bf16 v[102:105], v[164:167], v[188:191], v[102:105]
	v_mfma_f32_16x16x32_bf16 v[98:101], v[172:175], v[188:191], v[98:101]
	v_mfma_f32_16x16x32_bf16 v[86:89], v[164:167], v[200:203], v[86:89]
	v_mfma_f32_16x16x32_bf16 v[82:85], v[172:175], v[200:203], v[82:85]
	v_mfma_f32_16x16x32_bf16 v[70:73], v[164:167], v[208:211], v[70:73]
	v_mfma_f32_16x16x32_bf16 v[66:69], v[172:175], v[208:211], v[66:69]
	s_barrier
	s_add_i32 s0, s20, s61
	v_lshl_add_u64 v[144:145], s[76:77], 0, v[0:1]
	s_mov_b32 m0, s0
	ds_read_b128 v[176:179], v147 offset:16384
	ds_read_b128 v[180:183], v147 offset:17408
	ds_read_b128 v[184:187], v147 offset:18432
	ds_read_b128 v[188:191], v147 offset:19456
	ds_read_b128 v[196:199], v147 offset:20480
	ds_read_b128 v[200:203], v147 offset:21504
	ds_read_b128 v[204:207], v147 offset:22528
	ds_read_b128 v[208:211], v147 offset:23552
	global_load_lds_dwordx4 v[144:145], off
	s_add_i32 m0, s0, 0x2000
	s_add_u32 s0, s76, 0x40000
	v_lshl_add_u64 v[192:193], s[76:77], 0, v[134:135]
	s_addc_u32 s1, s77, 0
	s_add_i32 s20, s26, s61
	global_load_lds_dwordx4 v[192:193], off
	v_lshl_add_u64 v[212:213], s[0:1], 0, v[0:1]
	s_mov_b32 m0, s20
	v_lshl_add_u64 v[214:215], s[78:79], 0, v[132:133]
	global_load_lds_dwordx4 v[212:213], off
	v_lshl_add_u64 v[212:213], s[0:1], 0, v[134:135]
	s_add_i32 m0, s20, 0x2000
	s_nop 0
	global_load_lds_dwordx4 v[212:213], off
	v_lshl_add_u64 v[212:213], s[78:79], 0, v[130:131]
	s_mov_b32 m0, s62
	s_nop 0
	global_load_lds_dwordx4 v[212:213], off
	s_mov_b32 m0, s80
	s_nop 0
	global_load_lds_dwordx4 v[214:215], off
	s_waitcnt vmcnt(8)
	s_waitcnt lgkmcnt(0)
	s_barrier
; #define PG8_STAGE(bufoff, gbase, voff) do { _Pragma("unroll") for (int _i = 0; _i < 2; ++_i) \
;         __builtin_amdgcn_global_load_lds((const unsigned*)((const char*)(gbase) + (voff)[_i]), (LAS unsigned*)(lds + (bufoff) + ldsw + _i * 8192), 16, 0, 0); } while (0)
; #define PG8_LDA(dst, b, h) do { _Pragma("unroll") for (int m = 0; m < 4; ++m) _Pragma("unroll") for (int k = 0; k < 2; ++k) dst[m][k] = *(const LAS bf16x8*)(lds + PG8_SA(b, h) + aoff + m * 2048 + k * 1024); } while (0)
; #define PG8_LDB(dst, b, h) do { _Pragma("unroll") for (int n = 0; n < 2; ++n) _Pragma("unroll") for (int k = 0; k < 2; ++k) dst[n][k] = *(const LAS bf16x8*)(lds + PG8_SB(b, h) + boff + n * 2048 + k * 1024); } while (0)
; #define PG8_MMA(ai, bj, At, Bt) do { __builtin_amdgcn_s_setprio(1); _Pragma("unroll") for (int m = 0; m < 4; ++m) _Pragma("unroll") for (int n = 0; n < 2; ++n) _Pragma("unroll") for (int k = 0; k < 2; ++k) \
;         acc[ai][bj][m][n] = __builtin_amdgcn_mfma_f32_16x16x32_bf16(Bt[n][k], At[m][k], acc[ai][bj][m][n], 0, 0, 0); __builtin_amdgcn_s_setprio(0); } while (0)
; #define PG8_WAIT_V(n) asm volatile("s_waitcnt vmcnt(" #n ")" ::: "memory")
; #define PG8_WAIT_L(n) asm volatile("s_waitcnt lgkmcnt(" #n ")" ::: "memory")
; #define PG8_BAR __builtin_amdgcn_s_barrier()
; #define PG8_SCHED __builtin_amdgcn_sched_barrier(0)
; template <class Epi, class Sched>
; __device__ __forceinline__ void gemm_phase(LAS unsigned char* lds, const Gemm g, const Sched& S, const Epi& E, int wv) {
;     ...
;             PG8_WAIT_V(8); PG8_WAIT_L(0); PG8_BAR; PG8_MMA(1, 0, At, B0); PG8_MMA(1, 1, At, B1); PG8_BAR; PG8_SCHED;
;             PG8_LDB(B0, 1, 0); PG8_LDB(B1, 1, 1); PG8_SCHED; PG8_LDA(At, 1, 0); PG8_STAGE(PG8_SA(0, 1), a2 + hstepA, voffA);
;             PG8_WAIT_V(8); PG8_WAIT_L(0); PG8_BAR; PG8_MMA(0, 0, At, B0); PG8_MMA(0, 1, At, B1); PG8_BAR; PG8_SCHED;
	v_mfma_f32_16x16x32_bf16 v[62:65], v[140:143], v[176:179], v[62:65]
	v_mfma_f32_16x16x32_bf16 v[58:61], v[152:155], v[176:179], v[58:61]
	v_mfma_f32_16x16x32_bf16 v[46:49], v[140:143], v[184:187], v[46:49]
	v_mfma_f32_16x16x32_bf16 v[42:45], v[152:155], v[184:187], v[42:45]
	v_mfma_f32_16x16x32_bf16 v[30:33], v[140:143], v[196:199], v[30:33]
	v_mfma_f32_16x16x32_bf16 v[26:29], v[152:155], v[196:199], v[26:29]
	v_mfma_f32_16x16x32_bf16 v[14:17], v[140:143], v[204:207], v[14:17]
	v_mfma_f32_16x16x32_bf16 v[10:13], v[152:155], v[204:207], v[10:13]
	v_mfma_f32_16x16x32_bf16 v[62:65], v[148:151], v[180:183], v[62:65]
	v_mfma_f32_16x16x32_bf16 v[58:61], v[156:159], v[180:183], v[58:61]
	v_mfma_f32_16x16x32_bf16 v[46:49], v[148:151], v[188:191], v[46:49]
	v_mfma_f32_16x16x32_bf16 v[42:45], v[156:159], v[188:191], v[42:45]
	v_mfma_f32_16x16x32_bf16 v[30:33], v[148:151], v[200:203], v[30:33]
	v_mfma_f32_16x16x32_bf16 v[26:29], v[156:159], v[200:203], v[26:29]
	v_mfma_f32_16x16x32_bf16 v[14:17], v[148:151], v[208:211], v[14:17]
	v_mfma_f32_16x16x32_bf16 v[10:13], v[156:159], v[208:211], v[10:13]
	v_mfma_f32_16x16x32_bf16 v[54:57], v[160:163], v[176:179], v[54:57]
	v_mfma_f32_16x16x32_bf16 v[50:53], v[168:171], v[176:179], v[50:53]
	v_mfma_f32_16x16x32_bf16 v[38:41], v[160:163], v[184:187], v[38:41]
	v_mfma_f32_16x16x32_bf16 v[34:37], v[168:171], v[184:187], v[34:37]
	v_mfma_f32_16x16x32_bf16 v[22:25], v[160:163], v[196:199], v[22:25]
	v_mfma_f32_16x16x32_bf16 v[18:21], v[168:171], v[196:199], v[18:21]
	v_mfma_f32_16x16x32_bf16 v[6:9], v[160:163], v[204:207], v[6:9]
	v_mfma_f32_16x16x32_bf16 v[2:5], v[168:171], v[204:207], v[2:5]
	v_mfma_f32_16x16x32_bf16 v[54:57], v[164:167], v[180:183], v[54:57]
	v_mfma_f32_16x16x32_bf16 v[50:53], v[172:175], v[180:183], v[50:53]
	v_mfma_f32_16x16x32_bf16 v[38:41], v[164:167], v[188:191], v[38:41]
	v_mfma_f32_16x16x32_bf16 v[34:37], v[172:175], v[188:191], v[34:37]
	v_mfma_f32_16x16x32_bf16 v[22:25], v[164:167], v[200:203], v[22:25]
	v_mfma_f32_16x16x32_bf16 v[18:21], v[172:175], v[200:203], v[18:21]
	v_mfma_f32_16x16x32_bf16 v[6:9], v[164:167], v[208:211], v[6:9]
	v_mfma_f32_16x16x32_bf16 v[2:5], v[172:175], v[208:211], v[2:5]
	s_barrier
	s_add_i32 s20, 0, 0x18000
	s_add_i32 s26, 0, 0x1c000
	v_add_u32_e32 v156, s20, v146
	v_add_u32_e32 v172, s26, v146
	ds_read_b128 v[140:143], v156
	ds_read_b128 v[148:151], v156 offset:1024
	ds_read_b128 v[152:155], v156 offset:2048
	ds_read_b128 v[156:159], v156 offset:3072
	ds_read_b128 v[160:163], v172
	ds_read_b128 v[164:167], v172 offset:1024
	ds_read_b128 v[168:171], v172 offset:2048
	ds_read_b128 v[172:175], v172 offset:3072
	s_add_u32 s0, s78, 0x40000
	s_addc_u32 s1, s79, 0
	s_mov_b32 m0, s81
	v_lshl_add_u64 v[216:217], s[0:1], 0, v[130:131]
	ds_read_b128 v[176:179], v147 offset:32768
	ds_read_b128 v[180:183], v147 offset:33792
	ds_read_b128 v[184:187], v147 offset:34816
	ds_read_b128 v[188:191], v147 offset:35840
	ds_read_b128 v[196:199], v147 offset:36864
	ds_read_b128 v[200:203], v147 offset:37888
	ds_read_b128 v[204:207], v147 offset:38912
	ds_read_b128 v[208:211], v147 offset:39936
	global_load_lds_dwordx4 v[216:217], off
	v_lshl_add_u64 v[216:217], s[0:1], 0, v[132:133]
	s_mov_b32 m0, s82
	s_nop 0
	global_load_lds_dwordx4 v[216:217], off
	s_waitcnt vmcnt(8)
	s_waitcnt lgkmcnt(0)
	s_barrier
	v_mfma_f32_16x16x32_bf16 v[126:129], v[140:143], v[176:179], v[126:129]
	v_mfma_f32_16x16x32_bf16 v[122:125], v[152:155], v[176:179], v[122:125]
	v_mfma_f32_16x16x32_bf16 v[110:113], v[140:143], v[184:187], v[110:113]
	v_mfma_f32_16x16x32_bf16 v[106:109], v[152:155], v[184:187], v[106:109]
	v_mfma_f32_16x16x32_bf16 v[94:97], v[140:143], v[196:199], v[94:97]
	v_mfma_f32_16x16x32_bf16 v[90:93], v[152:155], v[196:199], v[90:93]
	v_mfma_f32_16x16x32_bf16 v[78:81], v[140:143], v[204:207], v[78:81]
	v_mfma_f32_16x16x32_bf16 v[74:77], v[152:155], v[204:207], v[74:77]
	v_mfma_f32_16x16x32_bf16 v[126:129], v[148:151], v[180:183], v[126:129]
	v_mfma_f32_16x16x32_bf16 v[122:125], v[156:159], v[180:183], v[122:125]
	v_mfma_f32_16x16x32_bf16 v[110:113], v[148:151], v[188:191], v[110:113]
	v_mfma_f32_16x16x32_bf16 v[106:109], v[156:159], v[188:191], v[106:109]
	v_mfma_f32_16x16x32_bf16 v[94:97], v[148:151], v[200:203], v[94:97]
	v_mfma_f32_16x16x32_bf16 v[90:93], v[156:159], v[200:203], v[90:93]
	v_mfma_f32_16x16x32_bf16 v[78:81], v[148:151], v[208:211], v[78:81]
	v_mfma_f32_16x16x32_bf16 v[74:77], v[156:159], v[208:211], v[74:77]
	v_mfma_f32_16x16x32_bf16 v[118:121], v[160:163], v[176:179], v[118:121]
	v_mfma_f32_16x16x32_bf16 v[114:117], v[168:171], v[176:179], v[114:117]
	v_mfma_f32_16x16x32_bf16 v[102:105], v[160:163], v[184:187], v[102:105]
	v_mfma_f32_16x16x32_bf16 v[98:101], v[168:171], v[184:187], v[98:101]
	v_mfma_f32_16x16x32_bf16 v[86:89], v[160:163], v[196:199], v[86:89]
	v_mfma_f32_16x16x32_bf16 v[82:85], v[168:171], v[196:199], v[82:85]
	v_mfma_f32_16x16x32_bf16 v[70:73], v[160:163], v[204:207], v[70:73]
	v_mfma_f32_16x16x32_bf16 v[66:69], v[168:171], v[204:207], v[66:69]
	v_mfma_f32_16x16x32_bf16 v[118:121], v[164:167], v[180:183], v[118:121]
	v_mfma_f32_16x16x32_bf16 v[114:117], v[172:175], v[180:183], v[114:117]
	v_mfma_f32_16x16x32_bf16 v[102:105], v[164:167], v[188:191], v[102:105]
	v_mfma_f32_16x16x32_bf16 v[98:101], v[172:175], v[188:191], v[98:101]
	v_mfma_f32_16x16x32_bf16 v[86:89], v[164:167], v[200:203], v[86:89]
	v_mfma_f32_16x16x32_bf16 v[82:85], v[172:175], v[200:203], v[82:85]
	v_mfma_f32_16x16x32_bf16 v[70:73], v[164:167], v[208:211], v[70:73]
	v_mfma_f32_16x16x32_bf16 v[66:69], v[172:175], v[208:211], v[66:69]
	s_barrier
; #define PG8_STAGE(bufoff, gbase, voff) do { _Pragma("unroll") for (int _i = 0; _i < 2; ++_i) \
;         __builtin_amdgcn_global_load_lds((const unsigned*)((const char*)(gbase) + (voff)[_i]), (LAS unsigned*)(lds + (bufoff) + ldsw + _i * 8192), 16, 0, 0); } while (0)
; #define PG8_LDA(dst, b, h) do { _Pragma("unroll") for (int m = 0; m < 4; ++m) _Pragma("unroll") for (int k = 0; k < 2; ++k) dst[m][k] = *(const LAS bf16x8*)(lds + PG8_SA(b, h) + aoff + m * 2048 + k * 1024); } while (0)
; #define PG8_MMA(ai, bj, At, Bt) do { __builtin_amdgcn_s_setprio(1); _Pragma("unroll") for (int m = 0; m < 4; ++m) _Pragma("unroll") for (int n = 0; n < 2; ++n) _Pragma("unroll") for (int k = 0; k < 2; ++k) \
;         acc[ai][bj][m][n] = __builtin_amdgcn_mfma_f32_16x16x32_bf16(Bt[n][k], At[m][k], acc[ai][bj][m][n], 0, 0, 0); __builtin_amdgcn_s_setprio(0); } while (0)
; #define PG8_WAIT_V(n) asm volatile("s_waitcnt vmcnt(" #n ")" ::: "memory")
; #define PG8_WAIT_L(n) asm volatile("s_waitcnt lgkmcnt(" #n ")" ::: "memory")
; #define PG8_BAR __builtin_amdgcn_s_barrier()
; #define PG8_SCHED __builtin_amdgcn_sched_barrier(0)
; template <class Epi, class Sched>
; __device__ __forceinline__ void gemm_phase(LAS unsigned char* lds, const Gemm g, const Sched& S, const Epi& E, int wv) {
;     ...
;         for (int t = 0; t < nt; t += 2) {
;     ...
;             PG8_LDA(At, 1, 1); PG8_STAGE(PG8_SB(1, 0), b3, voffB); PG8_STAGE(PG8_SB(1, 1), b3 + hstepB, voffB); PG8_STAGE(PG8_SA(1, 0), a3, voffA);
;             PG8_WAIT_V(8); PG8_WAIT_L(0); PG8_BAR; PG8_MMA(1, 0, At, B0); PG8_MMA(1, 1, At, B1); PG8_BAR; PG8_SCHED;
;         }
	s_add_i32 s0, s20, s61
	v_lshl_add_u64 v[144:145], v[144:145], 0, s[24:25]
	s_mov_b32 m0, s0
	ds_read_b128 v[176:179], v147 offset:49152
	ds_read_b128 v[180:183], v147 offset:50176
	ds_read_b128 v[184:187], v147 offset:51200
	ds_read_b128 v[188:191], v147 offset:52224
	ds_read_b128 v[196:199], v147 offset:53248
	ds_read_b128 v[200:203], v147 offset:54272
	ds_read_b128 v[204:207], v147 offset:55296
	ds_read_b128 v[208:211], v147 offset:56320
	global_load_lds_dwordx4 v[144:145], off
	s_add_i32 m0, s0, 0x2000
	s_add_u32 s0, s76, 0x40080
	v_lshl_add_u64 v[144:145], v[192:193], 0, s[24:25]
	s_addc_u32 s1, s77, 0
	s_add_i32 s20, s26, s61
	global_load_lds_dwordx4 v[144:145], off
	v_lshl_add_u64 v[144:145], s[0:1], 0, v[0:1]
	s_mov_b32 m0, s20
	s_nop 0
	global_load_lds_dwordx4 v[144:145], off
	v_lshl_add_u64 v[144:145], s[0:1], 0, v[134:135]
	s_add_i32 m0, s20, 0x2000
	s_nop 0
	global_load_lds_dwordx4 v[144:145], off
	v_lshl_add_u64 v[144:145], v[212:213], 0, s[24:25]
	s_mov_b32 m0, s86
	s_nop 0
	global_load_lds_dwordx4 v[144:145], off
	v_lshl_add_u64 v[144:145], v[214:215], 0, s[24:25]
	s_mov_b32 m0, s87
	s_nop 0
	global_load_lds_dwordx4 v[144:145], off
	s_waitcnt vmcnt(8)
	s_waitcnt lgkmcnt(0)
	s_barrier
	v_mfma_f32_16x16x32_bf16 v[62:65], v[140:143], v[176:179], v[62:65]
	v_mfma_f32_16x16x32_bf16 v[58:61], v[152:155], v[176:179], v[58:61]
	v_mfma_f32_16x16x32_bf16 v[46:49], v[140:143], v[184:187], v[46:49]
	v_mfma_f32_16x16x32_bf16 v[42:45], v[152:155], v[184:187], v[42:45]
	v_mfma_f32_16x16x32_bf16 v[30:33], v[140:143], v[196:199], v[30:33]
	v_mfma_f32_16x16x32_bf16 v[26:29], v[152:155], v[196:199], v[26:29]
	v_mfma_f32_16x16x32_bf16 v[14:17], v[140:143], v[204:207], v[14:17]
	v_mfma_f32_16x16x32_bf16 v[10:13], v[152:155], v[204:207], v[10:13]
	v_mfma_f32_16x16x32_bf16 v[62:65], v[148:151], v[180:183], v[62:65]
	v_mfma_f32_16x16x32_bf16 v[58:61], v[156:159], v[180:183], v[58:61]
	v_mfma_f32_16x16x32_bf16 v[46:49], v[148:151], v[188:191], v[46:49]
	v_mfma_f32_16x16x32_bf16 v[42:45], v[156:159], v[188:191], v[42:45]
	v_mfma_f32_16x16x32_bf16 v[30:33], v[148:151], v[200:203], v[30:33]
	v_mfma_f32_16x16x32_bf16 v[26:29], v[156:159], v[200:203], v[26:29]
	v_mfma_f32_16x16x32_bf16 v[14:17], v[148:151], v[208:211], v[14:17]
	v_mfma_f32_16x16x32_bf16 v[10:13], v[156:159], v[208:211], v[10:13]
	v_mfma_f32_16x16x32_bf16 v[54:57], v[160:163], v[176:179], v[54:57]
	v_mfma_f32_16x16x32_bf16 v[50:53], v[168:171], v[176:179], v[50:53]
	v_mfma_f32_16x16x32_bf16 v[38:41], v[160:163], v[184:187], v[38:41]
	v_mfma_f32_16x16x32_bf16 v[34:37], v[168:171], v[184:187], v[34:37]
	v_mfma_f32_16x16x32_bf16 v[22:25], v[160:163], v[196:199], v[22:25]
	v_mfma_f32_16x16x32_bf16 v[18:21], v[168:171], v[196:199], v[18:21]
	v_mfma_f32_16x16x32_bf16 v[6:9], v[160:163], v[204:207], v[6:9]
	v_mfma_f32_16x16x32_bf16 v[2:5], v[168:171], v[204:207], v[2:5]
	v_mfma_f32_16x16x32_bf16 v[54:57], v[164:167], v[180:183], v[54:57]
	v_mfma_f32_16x16x32_bf16 v[50:53], v[172:175], v[180:183], v[50:53]
	v_mfma_f32_16x16x32_bf16 v[38:41], v[164:167], v[188:191], v[38:41]
	v_mfma_f32_16x16x32_bf16 v[34:37], v[172:175], v[188:191], v[34:37]
	v_mfma_f32_16x16x32_bf16 v[22:25], v[164:167], v[200:203], v[22:25]
	v_mfma_f32_16x16x32_bf16 v[18:21], v[172:175], v[200:203], v[18:21]
	v_mfma_f32_16x16x32_bf16 v[6:9], v[164:167], v[208:211], v[6:9]
	v_mfma_f32_16x16x32_bf16 v[2:5], v[172:175], v[208:211], v[2:5]
	s_barrier
	s_add_i32 s56, s56, 2
	s_add_u32 s74, s74, 0x100
	s_addc_u32 s75, s75, 0
	s_add_u32 s34, s34, 0x100
	s_addc_u32 s35, s35, 0
	s_cmp_gt_u32 s56, 13
	s_cbranch_scc0 .LBB0_252
	s_and_b64 vcc, exec, s[12:13]
	s_cbranch_vccz .LBB0_255
	s_barrier

; #define PG8_STAGE(bufoff, gbase, voff) do { _Pragma("unroll") for (int _i = 0; _i < 2; ++_i) \
;         __builtin_amdgcn_global_load_lds((const unsigned*)((const char*)(gbase) + (voff)[_i]), (LAS unsigned*)(lds + (bufoff) + ldsw + _i * 8192), 16, 0, 0); } while (0)
; #define PG8_LDA(dst, b, h) do { _Pragma("unroll") for (int m = 0; m < 4; ++m) _Pragma("unroll") for (int k = 0; k < 2; ++k) dst[m][k] = *(const LAS bf16x8*)(lds + PG8_SA(b, h) + aoff + m * 2048 + k * 1024); } while (0)
; #define PG8_LDB(dst, b, h) do { _Pragma("unroll") for (int n = 0; n < 2; ++n) _Pragma("unroll") for (int k = 0; k < 2; ++k) dst[n][k] = *(const LAS bf16x8*)(lds + PG8_SB(b, h) + boff + n * 2048 + k * 1024); } while (0)
; #define PG8_MMA(ai, bj, At, Bt) do { __builtin_amdgcn_s_setprio(1); _Pragma("unroll") for (int m = 0; m < 4; ++m) _Pragma("unroll") for (int n = 0; n < 2; ++n) _Pragma("unroll") for (int k = 0; k < 2; ++k) \
;         acc[ai][bj][m][n] = __builtin_amdgcn_mfma_f32_16x16x32_bf16(Bt[n][k], At[m][k], acc[ai][bj][m][n], 0, 0, 0); __builtin_amdgcn_s_setprio(0); } while (0)
; #define PG8_WAIT_V(n) asm volatile("s_waitcnt vmcnt(" #n ")" ::: "memory")
; #define PG8_WAIT_L(n) asm volatile("s_waitcnt lgkmcnt(" #n ")" ::: "memory")
; #define PG8_BAR __builtin_amdgcn_s_barrier()
; template <class Epi, class Sched>
; __device__ __forceinline__ void gemm_phase(LAS unsigned char* lds, const Gemm g, const Sched& S, const Epi& E, int wv) {
;     ...
;         const char* nA = has_next ? (const char*)g.A + (size_t)nxt.pm * tstepA + (size_t)nxt.ak * 2 : cA; const char* nB = has_next ? (const char*)g.Bt + (size_t)nxt.pn * tstepB : cB;
;         for (int t = 0; t < nt; t += 2) {
;             const bool last = (t == nt - 2);
;             const char* a1 = cA + (size_t)(t + 1) * kstep;
;             const char* a2 = last ? nA : cA + (size_t)(t + 2) * kstep; const char* b2 = last ? nB : cB + (size_t)(t + 2) * kstep;
;             const char* a3 = a2 + kstep; const char* b3 = b2 + kstep;
;             PG8_LDB(B0, 0, 0); PG8_LDB(B1, 0, 1); PG8_SCHED; PG8_LDA(At, 0, 0); PG8_STAGE(PG8_SA(1, 1), a1 + hstepA, voffA);
;             PG8_WAIT_V(8); PG8_WAIT_L(0); PG8_BAR; PG8_MMA(0, 0, At, B0); PG8_MMA(0, 1, At, B1); PG8_BAR; PG8_SCHED;
;             PG8_LDA(At, 0, 1); PG8_STAGE(PG8_SB(0, 0), b2, voffB); PG8_STAGE(PG8_SB(0, 1), b2 + hstepB, voffB); PG8_STAGE(PG8_SA(0, 0), a2, voffA);
.LBB0_304:
	s_add_u32 s0, s74, 0xfffc0080
	s_addc_u32 s1, s75, -1
	s_add_i32 s20, 0, 0x10000
	s_cmp_eq_u32 s35, 12
	s_cselect_b32 s81, s5, s1
	s_cselect_b32 s80, s10, s0
	v_add_u32_e32 v0, s20, v184
	s_cselect_b32 s79, s11, s34
	s_cselect_b32 s78, s21, s31
	s_add_i32 s26, 0, 0x14000
	ds_read_b128 v[130:133], v0
	ds_read_b128 v[134:137], v0 offset:1024
	ds_read_b128 v[150:153], v0 offset:2048
	ds_read_b128 v[154:157], v0 offset:3072
	v_add_u32_e32 v0, s26, v184
	ds_read_b128 v[158:161], v0
	ds_read_b128 v[162:165], v0 offset:1024
	ds_read_b128 v[166:169], v0 offset:2048
	ds_read_b128 v[170:173], v0 offset:3072
	v_lshl_add_u64 v[182:183], s[74:75], 0, v[146:147]
	s_add_i32 m0, s61, 0xc000
	ds_read_b128 v[174:177], v185
	ds_read_b128 v[178:181], v185 offset:1024
	ds_read_b128 v[186:189], v185 offset:2048
	ds_read_b128 v[190:193], v185 offset:3072
	ds_read_b128 v[196:199], v185 offset:4096
	ds_read_b128 v[200:203], v185 offset:5120
	ds_read_b128 v[204:207], v185 offset:6144
	ds_read_b128 v[208:211], v185 offset:7168
	global_load_lds_dwordx4 v[182:183], off
	v_lshl_add_u64 v[182:183], s[74:75], 0, v[148:149]
	s_add_i32 m0, s61, 0xe000
	s_nop 0
	global_load_lds_dwordx4 v[182:183], off
	s_waitcnt vmcnt(8)
	s_waitcnt lgkmcnt(0)
	s_barrier
	v_mfma_f32_16x16x32_bf16 v[126:129], v[130:133], v[174:177], v[126:129]
	v_mfma_f32_16x16x32_bf16 v[122:125], v[150:153], v[174:177], v[122:125]
	v_mfma_f32_16x16x32_bf16 v[110:113], v[130:133], v[186:189], v[110:113]
	v_mfma_f32_16x16x32_bf16 v[106:109], v[150:153], v[186:189], v[106:109]
	v_mfma_f32_16x16x32_bf16 v[94:97], v[130:133], v[196:199], v[94:97]
	v_mfma_f32_16x16x32_bf16 v[90:93], v[150:153], v[196:199], v[90:93]
	v_mfma_f32_16x16x32_bf16 v[78:81], v[130:133], v[204:207], v[78:81]
	v_mfma_f32_16x16x32_bf16 v[74:77], v[150:153], v[204:207], v[74:77]
	v_mfma_f32_16x16x32_bf16 v[126:129], v[134:137], v[178:181], v[126:129]
	v_mfma_f32_16x16x32_bf16 v[122:125], v[154:157], v[178:181], v[122:125]
	v_mfma_f32_16x16x32_bf16 v[110:113], v[134:137], v[190:193], v[110:113]
	v_mfma_f32_16x16x32_bf16 v[106:109], v[154:157], v[190:193], v[106:109]
	v_mfma_f32_16x16x32_bf16 v[94:97], v[134:137], v[200:203], v[94:97]
	v_mfma_f32_16x16x32_bf16 v[90:93], v[154:157], v[200:203], v[90:93]
	v_mfma_f32_16x16x32_bf16 v[78:81], v[134:137], v[208:211], v[78:81]
	v_mfma_f32_16x16x32_bf16 v[74:77], v[154:157], v[208:211], v[74:77]
	v_mfma_f32_16x16x32_bf16 v[118:121], v[158:161], v[174:177], v[118:121]
	v_mfma_f32_16x16x32_bf16 v[114:117], v[166:169], v[174:177], v[114:117]
	v_mfma_f32_16x16x32_bf16 v[102:105], v[158:161], v[186:189], v[102:105]
	v_mfma_f32_16x16x32_bf16 v[98:101], v[166:169], v[186:189], v[98:101]
	v_mfma_f32_16x16x32_bf16 v[86:89], v[158:161], v[196:199], v[86:89]
	v_mfma_f32_16x16x32_bf16 v[82:85], v[166:169], v[196:199], v[82:85]
	v_mfma_f32_16x16x32_bf16 v[70:73], v[158:161], v[204:207], v[70:73]
	v_mfma_f32_16x16x32_bf16 v[66:69], v[166:169], v[204:207], v[66:69]
	v_mfma_f32_16x16x32_bf16 v[118:121], v[162:165], v[178:181], v[118:121]
	v_mfma_f32_16x16x32_bf16 v[114:117], v[170:173], v[178:181], v[114:117]
	v_mfma_f32_16x16x32_bf16 v[102:105], v[162:165], v[190:193], v[102:105]
	v_mfma_f32_16x16x32_bf16 v[98:101], v[170:173], v[190:193], v[98:101]
	v_mfma_f32_16x16x32_bf16 v[86:89], v[162:165], v[200:203], v[86:89]
	v_mfma_f32_16x16x32_bf16 v[82:85], v[170:173], v[200:203], v[82:85]
	v_mfma_f32_16x16x32_bf16 v[70:73], v[162:165], v[208:211], v[70:73]
	v_mfma_f32_16x16x32_bf16 v[66:69], v[170:173], v[208:211], v[66:69]
	s_barrier
	s_add_i32 s0, s20, s60
	v_lshl_add_u64 v[182:183], s[78:79], 0, v[140:141]
	s_mov_b32 m0, s0
	ds_read_b128 v[174:177], v185 offset:16384
	ds_read_b128 v[178:181], v185 offset:17408
	ds_read_b128 v[186:189], v185 offset:18432
	ds_read_b128 v[190:193], v185 offset:19456
	ds_read_b128 v[196:199], v185 offset:20480
	ds_read_b128 v[200:203], v185 offset:21504
	ds_read_b128 v[204:207], v185 offset:22528
	ds_read_b128 v[208:211], v185 offset:23552
	global_load_lds_dwordx4 v[182:183], off
	s_add_i32 m0, s0, 0x2000
	s_add_u32 s0, s78, 0x40000
	v_lshl_add_u64 v[212:213], s[78:79], 0, v[144:145]
	s_addc_u32 s1, s79, 0
	s_add_i32 s20, s26, s60
	global_load_lds_dwordx4 v[212:213], off
	v_lshl_add_u64 v[214:215], s[0:1], 0, v[140:141]
	s_mov_b32 m0, s20
	v_lshl_add_u64 v[216:217], s[80:81], 0, v[142:143]
	global_load_lds_dwordx4 v[214:215], off
	v_lshl_add_u64 v[214:215], s[0:1], 0, v[144:145]
	s_add_i32 m0, s20, 0x2000
	s_nop 0
	global_load_lds_dwordx4 v[214:215], off
	v_lshl_add_u64 v[214:215], s[80:81], 0, v[138:139]
	s_mov_b32 m0, s61
	s_nop 0
	global_load_lds_dwordx4 v[214:215], off
	s_mov_b32 m0, s62
	s_nop 0
	global_load_lds_dwordx4 v[216:217], off
	s_waitcnt vmcnt(8)
	s_waitcnt lgkmcnt(0)
	s_barrier
; #define PG8_STAGE(bufoff, gbase, voff) do { _Pragma("unroll") for (int _i = 0; _i < 2; ++_i) \
;         __builtin_amdgcn_global_load_lds((const unsigned*)((const char*)(gbase) + (voff)[_i]), (LAS unsigned*)(lds + (bufoff) + ldsw + _i * 8192), 16, 0, 0); } while (0)
; #define PG8_LDA(dst, b, h) do { _Pragma("unroll") for (int m = 0; m < 4; ++m) _Pragma("unroll") for (int k = 0; k < 2; ++k) dst[m][k] = *(const LAS bf16x8*)(lds + PG8_SA(b, h) + aoff + m * 2048 + k * 1024); } while (0)
; #define PG8_LDB(dst, b, h) do { _Pragma("unroll") for (int n = 0; n < 2; ++n) _Pragma("unroll") for (int k = 0; k < 2; ++k) dst[n][k] = *(const LAS bf16x8*)(lds + PG8_SB(b, h) + boff + n * 2048 + k * 1024); } while (0)
; #define PG8_MMA(ai, bj, At, Bt) do { __builtin_amdgcn_s_setprio(1); _Pragma("unroll") for (int m = 0; m < 4; ++m) _Pragma("unroll") for (int n = 0; n < 2; ++n) _Pragma("unroll") for (int k = 0; k < 2; ++k) \
;         acc[ai][bj][m][n] = __builtin_amdgcn_mfma_f32_16x16x32_bf16(Bt[n][k], At[m][k], acc[ai][bj][m][n], 0, 0, 0); __builtin_amdgcn_s_setprio(0); } while (0)
; #define PG8_WAIT_V(n) asm volatile("s_waitcnt vmcnt(" #n ")" ::: "memory")
; #define PG8_WAIT_L(n) asm volatile("s_waitcnt lgkmcnt(" #n ")" ::: "memory")
; #define PG8_BAR __builtin_amdgcn_s_barrier()
; #define PG8_SCHED __builtin_amdgcn_sched_barrier(0)
; template <class Epi, class Sched>
; __device__ __forceinline__ void gemm_phase(LAS unsigned char* lds, const Gemm g, const Sched& S, const Epi& E, int wv) {
;     ...
;             PG8_WAIT_V(8); PG8_WAIT_L(0); PG8_BAR; PG8_MMA(1, 0, At, B0); PG8_MMA(1, 1, At, B1); PG8_BAR; PG8_SCHED;
;             PG8_LDB(B0, 1, 0); PG8_LDB(B1, 1, 1); PG8_SCHED; PG8_LDA(At, 1, 0); PG8_STAGE(PG8_SA(0, 1), a2 + hstepA, voffA);
;             PG8_WAIT_V(8); PG8_WAIT_L(0); PG8_BAR; PG8_MMA(0, 0, At, B0); PG8_MMA(0, 1, At, B1); PG8_BAR; PG8_SCHED;
	v_mfma_f32_16x16x32_bf16 v[62:65], v[130:133], v[174:177], v[62:65]
	v_mfma_f32_16x16x32_bf16 v[58:61], v[150:153], v[174:177], v[58:61]
	v_mfma_f32_16x16x32_bf16 v[46:49], v[130:133], v[186:189], v[46:49]
	v_mfma_f32_16x16x32_bf16 v[42:45], v[150:153], v[186:189], v[42:45]
	v_mfma_f32_16x16x32_bf16 v[30:33], v[130:133], v[196:199], v[30:33]
	v_mfma_f32_16x16x32_bf16 v[26:29], v[150:153], v[196:199], v[26:29]
	v_mfma_f32_16x16x32_bf16 v[14:17], v[130:133], v[204:207], v[14:17]
	v_mfma_f32_16x16x32_bf16 v[10:13], v[150:153], v[204:207], v[10:13]
	v_mfma_f32_16x16x32_bf16 v[62:65], v[134:137], v[178:181], v[62:65]
	v_mfma_f32_16x16x32_bf16 v[58:61], v[154:157], v[178:181], v[58:61]
	v_mfma_f32_16x16x32_bf16 v[46:49], v[134:137], v[190:193], v[46:49]
	v_mfma_f32_16x16x32_bf16 v[42:45], v[154:157], v[190:193], v[42:45]
	v_mfma_f32_16x16x32_bf16 v[30:33], v[134:137], v[200:203], v[30:33]
	v_mfma_f32_16x16x32_bf16 v[26:29], v[154:157], v[200:203], v[26:29]
	v_mfma_f32_16x16x32_bf16 v[14:17], v[134:137], v[208:211], v[14:17]
	v_mfma_f32_16x16x32_bf16 v[10:13], v[154:157], v[208:211], v[10:13]
	v_mfma_f32_16x16x32_bf16 v[54:57], v[158:161], v[174:177], v[54:57]
	v_mfma_f32_16x16x32_bf16 v[50:53], v[166:169], v[174:177], v[50:53]
	v_mfma_f32_16x16x32_bf16 v[38:41], v[158:161], v[186:189], v[38:41]
	v_mfma_f32_16x16x32_bf16 v[34:37], v[166:169], v[186:189], v[34:37]
	v_mfma_f32_16x16x32_bf16 v[22:25], v[158:161], v[196:199], v[22:25]
	v_mfma_f32_16x16x32_bf16 v[18:21], v[166:169], v[196:199], v[18:21]
	v_mfma_f32_16x16x32_bf16 v[6:9], v[158:161], v[204:207], v[6:9]
	v_mfma_f32_16x16x32_bf16 v[2:5], v[166:169], v[204:207], v[2:5]
	v_mfma_f32_16x16x32_bf16 v[54:57], v[162:165], v[178:181], v[54:57]
	v_mfma_f32_16x16x32_bf16 v[50:53], v[170:173], v[178:181], v[50:53]
	v_mfma_f32_16x16x32_bf16 v[38:41], v[162:165], v[190:193], v[38:41]
	v_mfma_f32_16x16x32_bf16 v[34:37], v[170:173], v[190:193], v[34:37]
	v_mfma_f32_16x16x32_bf16 v[22:25], v[162:165], v[200:203], v[22:25]
	v_mfma_f32_16x16x32_bf16 v[18:21], v[170:173], v[200:203], v[18:21]
	v_mfma_f32_16x16x32_bf16 v[6:9], v[162:165], v[208:211], v[6:9]
	v_mfma_f32_16x16x32_bf16 v[2:5], v[170:173], v[208:211], v[2:5]
	s_barrier
	s_add_i32 s20, 0, 0x18000
	v_add_u32_e32 v0, s20, v184
	s_add_i32 s26, 0, 0x1c000
	ds_read_b128 v[130:133], v0
	ds_read_b128 v[134:137], v0 offset:1024
	ds_read_b128 v[150:153], v0 offset:2048
	ds_read_b128 v[154:157], v0 offset:3072
	v_add_u32_e32 v0, s26, v184
	ds_read_b128 v[158:161], v0
	ds_read_b128 v[162:165], v0 offset:1024
	ds_read_b128 v[166:169], v0 offset:2048
	ds_read_b128 v[170:173], v0 offset:3072
	s_add_u32 s0, s80, 0x40000
	s_addc_u32 s1, s81, 0
	s_mov_b32 m0, s82
	v_lshl_add_u64 v[218:219], s[0:1], 0, v[138:139]
	ds_read_b128 v[174:177], v185 offset:32768
	ds_read_b128 v[178:181], v185 offset:33792
	ds_read_b128 v[186:189], v185 offset:34816
	ds_read_b128 v[190:193], v185 offset:35840
	ds_read_b128 v[196:199], v185 offset:36864
	ds_read_b128 v[200:203], v185 offset:37888
	ds_read_b128 v[204:207], v185 offset:38912
	ds_read_b128 v[208:211], v185 offset:39936
	global_load_lds_dwordx4 v[218:219], off
	v_lshl_add_u64 v[218:219], s[0:1], 0, v[142:143]
	s_mov_b32 m0, s83
	s_nop 0
	global_load_lds_dwordx4 v[218:219], off
	s_waitcnt vmcnt(8)
	s_waitcnt lgkmcnt(0)
	s_barrier
	v_mfma_f32_16x16x32_bf16 v[126:129], v[130:133], v[174:177], v[126:129]
	v_mfma_f32_16x16x32_bf16 v[122:125], v[150:153], v[174:177], v[122:125]
	v_mfma_f32_16x16x32_bf16 v[110:113], v[130:133], v[186:189], v[110:113]
	v_mfma_f32_16x16x32_bf16 v[106:109], v[150:153], v[186:189], v[106:109]
	v_mfma_f32_16x16x32_bf16 v[94:97], v[130:133], v[196:199], v[94:97]
	v_mfma_f32_16x16x32_bf16 v[90:93], v[150:153], v[196:199], v[90:93]
	v_mfma_f32_16x16x32_bf16 v[78:81], v[130:133], v[204:207], v[78:81]
	v_mfma_f32_16x16x32_bf16 v[74:77], v[150:153], v[204:207], v[74:77]
	v_mfma_f32_16x16x32_bf16 v[126:129], v[134:137], v[178:181], v[126:129]
	v_mfma_f32_16x16x32_bf16 v[122:125], v[154:157], v[178:181], v[122:125]
	v_mfma_f32_16x16x32_bf16 v[110:113], v[134:137], v[190:193], v[110:113]
	v_mfma_f32_16x16x32_bf16 v[106:109], v[154:157], v[190:193], v[106:109]
	v_mfma_f32_16x16x32_bf16 v[94:97], v[134:137], v[200:203], v[94:97]
	v_mfma_f32_16x16x32_bf16 v[90:93], v[154:157], v[200:203], v[90:93]
	v_mfma_f32_16x16x32_bf16 v[78:81], v[134:137], v[208:211], v[78:81]
	v_mfma_f32_16x16x32_bf16 v[74:77], v[154:157], v[208:211], v[74:77]
	v_mfma_f32_16x16x32_bf16 v[118:121], v[158:161], v[174:177], v[118:121]
	v_mfma_f32_16x16x32_bf16 v[114:117], v[166:169], v[174:177], v[114:117]
	v_mfma_f32_16x16x32_bf16 v[102:105], v[158:161], v[186:189], v[102:105]
	v_mfma_f32_16x16x32_bf16 v[98:101], v[166:169], v[186:189], v[98:101]
	v_mfma_f32_16x16x32_bf16 v[86:89], v[158:161], v[196:199], v[86:89]
	v_mfma_f32_16x16x32_bf16 v[82:85], v[166:169], v[196:199], v[82:85]
	v_mfma_f32_16x16x32_bf16 v[70:73], v[158:161], v[204:207], v[70:73]
	v_mfma_f32_16x16x32_bf16 v[66:69], v[166:169], v[204:207], v[66:69]
	v_mfma_f32_16x16x32_bf16 v[118:121], v[162:165], v[178:181], v[118:121]
	v_mfma_f32_16x16x32_bf16 v[114:117], v[170:173], v[178:181], v[114:117]
	v_mfma_f32_16x16x32_bf16 v[102:105], v[162:165], v[190:193], v[102:105]
	v_mfma_f32_16x16x32_bf16 v[98:101], v[170:173], v[190:193], v[98:101]
	v_mfma_f32_16x16x32_bf16 v[86:89], v[162:165], v[200:203], v[86:89]
	v_mfma_f32_16x16x32_bf16 v[82:85], v[170:173], v[200:203], v[82:85]
	v_mfma_f32_16x16x32_bf16 v[70:73], v[162:165], v[208:211], v[70:73]
	v_mfma_f32_16x16x32_bf16 v[66:69], v[170:173], v[208:211], v[66:69]
	s_barrier
; #define PG8_STAGE(bufoff, gbase, voff) do { _Pragma("unroll") for (int _i = 0; _i < 2; ++_i) \
;         __builtin_amdgcn_global_load_lds((const unsigned*)((const char*)(gbase) + (voff)[_i]), (LAS unsigned*)(lds + (bufoff) + ldsw + _i * 8192), 16, 0, 0); } while (0)
; #define PG8_LDA(dst, b, h) do { _Pragma("unroll") for (int m = 0; m < 4; ++m) _Pragma("unroll") for (int k = 0; k < 2; ++k) dst[m][k] = *(const LAS bf16x8*)(lds + PG8_SA(b, h) + aoff + m * 2048 + k * 1024); } while (0)
; #define PG8_MMA(ai, bj, At, Bt) do { __builtin_amdgcn_s_setprio(1); _Pragma("unroll") for (int m = 0; m < 4; ++m) _Pragma("unroll") for (int n = 0; n < 2; ++n) _Pragma("unroll") for (int k = 0; k < 2; ++k) \
;         acc[ai][bj][m][n] = __builtin_amdgcn_mfma_f32_16x16x32_bf16(Bt[n][k], At[m][k], acc[ai][bj][m][n], 0, 0, 0); __builtin_amdgcn_s_setprio(0); } while (0)
; #define PG8_WAIT_V(n) asm volatile("s_waitcnt vmcnt(" #n ")" ::: "memory")
; #define PG8_WAIT_L(n) asm volatile("s_waitcnt lgkmcnt(" #n ")" ::: "memory")
; #define PG8_BAR __builtin_amdgcn_s_barrier()
; #define PG8_SCHED __builtin_amdgcn_sched_barrier(0)
; template <class Epi, class Sched>
; __device__ __forceinline__ void gemm_phase(LAS unsigned char* lds, const Gemm g, const Sched& S, const Epi& E, int wv) {
;     ...
;         for (int t = 0; t < nt; t += 2) {
;     ...
;             PG8_LDA(At, 1, 1); PG8_STAGE(PG8_SB(1, 0), b3, voffB); PG8_STAGE(PG8_SB(1, 1), b3 + hstepB, voffB); PG8_STAGE(PG8_SA(1, 0), a3, voffA);
;             PG8_WAIT_V(8); PG8_WAIT_L(0); PG8_BAR; PG8_MMA(1, 0, At, B0); PG8_MMA(1, 1, At, B1); PG8_BAR; PG8_SCHED;
;         }
	s_add_i32 s0, s20, s60
	v_lshl_add_u64 v[182:183], v[182:183], 0, s[24:25]
	s_mov_b32 m0, s0
	ds_read_b128 v[174:177], v185 offset:49152
	ds_read_b128 v[178:181], v185 offset:50176
	ds_read_b128 v[186:189], v185 offset:51200
	ds_read_b128 v[190:193], v185 offset:52224
	ds_read_b128 v[196:199], v185 offset:53248
	ds_read_b128 v[200:203], v185 offset:54272
	ds_read_b128 v[204:207], v185 offset:55296
	ds_read_b128 v[208:211], v185 offset:56320
	global_load_lds_dwordx4 v[182:183], off
	s_add_i32 m0, s0, 0x2000
	s_add_u32 s0, s78, 0x40080
	v_lshl_add_u64 v[182:183], v[212:213], 0, s[24:25]
	s_addc_u32 s1, s79, 0
	s_add_i32 s20, s26, s60
	global_load_lds_dwordx4 v[182:183], off
	v_lshl_add_u64 v[182:183], s[0:1], 0, v[140:141]
	s_mov_b32 m0, s20
	s_nop 0
	global_load_lds_dwordx4 v[182:183], off
	v_lshl_add_u64 v[182:183], s[0:1], 0, v[144:145]
	s_add_i32 m0, s20, 0x2000
	s_nop 0
	global_load_lds_dwordx4 v[182:183], off
	v_lshl_add_u64 v[182:183], v[214:215], 0, s[24:25]
	s_mov_b32 m0, s84
	s_nop 0
	global_load_lds_dwordx4 v[182:183], off
	v_lshl_add_u64 v[182:183], v[216:217], 0, s[24:25]
	s_mov_b32 m0, s85
	s_nop 0
	global_load_lds_dwordx4 v[182:183], off
	s_waitcnt vmcnt(8)
	s_waitcnt lgkmcnt(0)
	s_barrier
	v_mfma_f32_16x16x32_bf16 v[62:65], v[130:133], v[174:177], v[62:65]
	v_mfma_f32_16x16x32_bf16 v[58:61], v[150:153], v[174:177], v[58:61]
	v_mfma_f32_16x16x32_bf16 v[46:49], v[130:133], v[186:189], v[46:49]
	v_mfma_f32_16x16x32_bf16 v[42:45], v[150:153], v[186:189], v[42:45]
	v_mfma_f32_16x16x32_bf16 v[30:33], v[130:133], v[196:199], v[30:33]
	v_mfma_f32_16x16x32_bf16 v[26:29], v[150:153], v[196:199], v[26:29]
	v_mfma_f32_16x16x32_bf16 v[14:17], v[130:133], v[204:207], v[14:17]
	v_mfma_f32_16x16x32_bf16 v[10:13], v[150:153], v[204:207], v[10:13]
	v_mfma_f32_16x16x32_bf16 v[62:65], v[134:137], v[178:181], v[62:65]
	v_mfma_f32_16x16x32_bf16 v[58:61], v[154:157], v[178:181], v[58:61]
	v_mfma_f32_16x16x32_bf16 v[46:49], v[134:137], v[190:193], v[46:49]
	v_mfma_f32_16x16x32_bf16 v[42:45], v[154:157], v[190:193], v[42:45]
	v_mfma_f32_16x16x32_bf16 v[30:33], v[134:137], v[200:203], v[30:33]
	v_mfma_f32_16x16x32_bf16 v[26:29], v[154:157], v[200:203], v[26:29]
	v_mfma_f32_16x16x32_bf16 v[14:17], v[134:137], v[208:211], v[14:17]
	v_mfma_f32_16x16x32_bf16 v[10:13], v[154:157], v[208:211], v[10:13]
	v_mfma_f32_16x16x32_bf16 v[54:57], v[158:161], v[174:177], v[54:57]
	v_mfma_f32_16x16x32_bf16 v[50:53], v[166:169], v[174:177], v[50:53]
	v_mfma_f32_16x16x32_bf16 v[38:41], v[158:161], v[186:189], v[38:41]
	v_mfma_f32_16x16x32_bf16 v[34:37], v[166:169], v[186:189], v[34:37]
	v_mfma_f32_16x16x32_bf16 v[22:25], v[158:161], v[196:199], v[22:25]
	v_mfma_f32_16x16x32_bf16 v[18:21], v[166:169], v[196:199], v[18:21]
	v_mfma_f32_16x16x32_bf16 v[6:9], v[158:161], v[204:207], v[6:9]
	v_mfma_f32_16x16x32_bf16 v[2:5], v[166:169], v[204:207], v[2:5]
	v_mfma_f32_16x16x32_bf16 v[54:57], v[162:165], v[178:181], v[54:57]
	v_mfma_f32_16x16x32_bf16 v[50:53], v[170:173], v[178:181], v[50:53]
	v_mfma_f32_16x16x32_bf16 v[38:41], v[162:165], v[190:193], v[38:41]
	v_mfma_f32_16x16x32_bf16 v[34:37], v[170:173], v[190:193], v[34:37]
	v_mfma_f32_16x16x32_bf16 v[22:25], v[162:165], v[200:203], v[22:25]
	v_mfma_f32_16x16x32_bf16 v[18:21], v[170:173], v[200:203], v[18:21]
	v_mfma_f32_16x16x32_bf16 v[6:9], v[162:165], v[208:211], v[6:9]
	v_mfma_f32_16x16x32_bf16 v[2:5], v[170:173], v[208:211], v[2:5]
	s_barrier
	s_add_i32 s35, s35, 2
	s_add_u32 s74, s74, 0x100
	s_addc_u32 s75, s75, 0
	s_add_u32 s31, s31, 0x100
	s_addc_u32 s34, s34, 0
	s_cmp_gt_u32 s35, 13
	s_cbranch_scc0 .LBB0_304
	s_and_b64 vcc, exec, s[64:65]
	s_cbranch_vccz .LBB0_307
	s_barrier

; #define PG8_STAGE(bufoff, gbase, voff) do { _Pragma("unroll") for (int _i = 0; _i < 2; ++_i) \
;         __builtin_amdgcn_global_load_lds((const unsigned*)((const char*)(gbase) + (voff)[_i]), (LAS unsigned*)(lds + (bufoff) + ldsw + _i * 8192), 16, 0, 0); } while (0)
; #define PG8_LDA(dst, b, h) do { _Pragma("unroll") for (int m = 0; m < 4; ++m) _Pragma("unroll") for (int k = 0; k < 2; ++k) dst[m][k] = *(const LAS bf16x8*)(lds + PG8_SA(b, h) + aoff + m * 2048 + k * 1024); } while (0)
; #define PG8_LDB(dst, b, h) do { _Pragma("unroll") for (int n = 0; n < 2; ++n) _Pragma("unroll") for (int k = 0; k < 2; ++k) dst[n][k] = *(const LAS bf16x8*)(lds + PG8_SB(b, h) + boff + n * 2048 + k * 1024); } while (0)
; #define PG8_MMA(ai, bj, At, Bt) do { __builtin_amdgcn_s_setprio(1); _Pragma("unroll") for (int m = 0; m < 4; ++m) _Pragma("unroll") for (int n = 0; n < 2; ++n) _Pragma("unroll") for (int k = 0; k < 2; ++k) \
;         acc[ai][bj][m][n] = __builtin_amdgcn_mfma_f32_16x16x32_bf16(Bt[n][k], At[m][k], acc[ai][bj][m][n], 0, 0, 0); __builtin_amdgcn_s_setprio(0); } while (0)
; #define PG8_WAIT_V(n) asm volatile("s_waitcnt vmcnt(" #n ")" ::: "memory")
; #define PG8_WAIT_L(n) asm volatile("s_waitcnt lgkmcnt(" #n ")" ::: "memory")
; #define PG8_BAR __builtin_amdgcn_s_barrier()
; template <class Epi, class Sched>
; __device__ __forceinline__ void gemm_phase(LAS unsigned char* lds, const Gemm g, const Sched& S, const Epi& E, int wv) {
;     ...
;         const char* nA = has_next ? (const char*)g.A + (size_t)nxt.pm * tstepA + (size_t)nxt.ak * 2 : cA; const char* nB = has_next ? (const char*)g.Bt + (size_t)nxt.pn * tstepB : cB;
;         for (int t = 0; t < nt; t += 2) {
;             const bool last = (t == nt - 2);
;             const char* a1 = cA + (size_t)(t + 1) * kstep;
;             const char* a2 = last ? nA : cA + (size_t)(t + 2) * kstep; const char* b2 = last ? nB : cB + (size_t)(t + 2) * kstep;
;             const char* a3 = a2 + kstep; const char* b3 = b2 + kstep;
;             PG8_LDB(B0, 0, 0); PG8_LDB(B1, 0, 1); PG8_SCHED; PG8_LDA(At, 0, 0); PG8_STAGE(PG8_SA(1, 1), a1 + hstepA, voffA);
;             PG8_WAIT_V(8); PG8_WAIT_L(0); PG8_BAR; PG8_MMA(0, 0, At, B0); PG8_MMA(0, 1, At, B1); PG8_BAR; PG8_SCHED;
;             PG8_LDA(At, 0, 1); PG8_STAGE(PG8_SB(0, 0), b2, voffB); PG8_STAGE(PG8_SB(0, 1), b2 + hstepB, voffB); PG8_STAGE(PG8_SA(0, 0), a2, voffA);
.LBB0_556:
	s_add_u32 s0, s78, 0xfff00080
	s_addc_u32 s1, s79, -1
	s_add_i32 s20, 0, 0x10000
	s_cmp_eq_u32 s34, s16
	s_cselect_b32 s83, s5, s1
	s_cselect_b32 s82, s7, s0
	v_add_u32_e32 v0, s20, v231
	s_cselect_b32 s81, s10, s31
	s_cselect_b32 s80, s11, s21
	s_add_i32 s26, 0, 0x14000
	ds_read_b128 v[114:117], v0
	ds_read_b128 v[118:121], v0 offset:1024
	ds_read_b128 v[130:133], v0 offset:2048
	ds_read_b128 v[134:137], v0 offset:3072
	v_add_u32_e32 v0, s26, v231
	ds_read_b128 v[146:149], v0
	ds_read_b128 v[150:153], v0 offset:1024
	ds_read_b128 v[154:157], v0 offset:2048
	ds_read_b128 v[158:161], v0 offset:3072
	v_lshl_add_u64 v[208:209], s[78:79], 0, v[204:205]
	s_add_i32 m0, s60, 0xc000
	ds_read_b128 v[162:165], v232
	ds_read_b128 v[166:169], v232 offset:1024
	ds_read_b128 v[170:173], v232 offset:2048
	ds_read_b128 v[174:177], v232 offset:3072
	ds_read_b128 v[178:181], v232 offset:4096
	ds_read_b128 v[182:185], v232 offset:5120
	ds_read_b128 v[186:189], v232 offset:6144
	ds_read_b128 v[190:193], v232 offset:7168
	global_load_lds_dwordx4 v[208:209], off
	v_lshl_add_u64 v[208:209], s[78:79], 0, v[206:207]
	s_add_i32 m0, s60, 0xe000
	s_nop 0
	global_load_lds_dwordx4 v[208:209], off
	s_waitcnt vmcnt(8)
	s_waitcnt lgkmcnt(0)
	s_barrier
	v_mfma_f32_16x16x32_bf16 v[142:145], v[114:117], v[162:165], v[142:145]
	v_mfma_f32_16x16x32_bf16 v[138:141], v[130:133], v[162:165], v[138:141]
	v_mfma_f32_16x16x32_bf16 v[126:129], v[114:117], v[170:173], v[126:129]
	v_mfma_f32_16x16x32_bf16 v[122:125], v[130:133], v[170:173], v[122:125]
	v_mfma_f32_16x16x32_bf16 v[110:113], v[114:117], v[178:181], v[110:113]
	v_mfma_f32_16x16x32_bf16 v[106:109], v[130:133], v[178:181], v[106:109]
	v_mfma_f32_16x16x32_bf16 v[102:105], v[114:117], v[186:189], v[102:105]
	v_mfma_f32_16x16x32_bf16 v[98:101], v[130:133], v[186:189], v[98:101]
	v_mfma_f32_16x16x32_bf16 v[142:145], v[118:121], v[166:169], v[142:145]
	v_mfma_f32_16x16x32_bf16 v[138:141], v[134:137], v[166:169], v[138:141]
	v_mfma_f32_16x16x32_bf16 v[126:129], v[118:121], v[174:177], v[126:129]
	v_mfma_f32_16x16x32_bf16 v[122:125], v[134:137], v[174:177], v[122:125]
	v_mfma_f32_16x16x32_bf16 v[110:113], v[118:121], v[182:185], v[110:113]
	v_mfma_f32_16x16x32_bf16 v[106:109], v[134:137], v[182:185], v[106:109]
	v_mfma_f32_16x16x32_bf16 v[102:105], v[118:121], v[190:193], v[102:105]
	v_mfma_f32_16x16x32_bf16 v[98:101], v[134:137], v[190:193], v[98:101]
	v_mfma_f32_16x16x32_bf16 v[62:65], v[146:149], v[162:165], v[62:65]
	v_mfma_f32_16x16x32_bf16 v[58:61], v[154:157], v[162:165], v[58:61]
	v_mfma_f32_16x16x32_bf16 v[54:57], v[146:149], v[170:173], v[54:57]
	v_mfma_f32_16x16x32_bf16 v[50:53], v[154:157], v[170:173], v[50:53]
	v_mfma_f32_16x16x32_bf16 v[46:49], v[146:149], v[178:181], v[46:49]
	v_mfma_f32_16x16x32_bf16 v[42:45], v[154:157], v[178:181], v[42:45]
	v_mfma_f32_16x16x32_bf16 v[38:41], v[146:149], v[186:189], v[38:41]
	v_mfma_f32_16x16x32_bf16 v[34:37], v[154:157], v[186:189], v[34:37]
	v_mfma_f32_16x16x32_bf16 v[62:65], v[150:153], v[166:169], v[62:65]
	v_mfma_f32_16x16x32_bf16 v[58:61], v[158:161], v[166:169], v[58:61]
	v_mfma_f32_16x16x32_bf16 v[54:57], v[150:153], v[174:177], v[54:57]
	v_mfma_f32_16x16x32_bf16 v[50:53], v[158:161], v[174:177], v[50:53]
	v_mfma_f32_16x16x32_bf16 v[46:49], v[150:153], v[182:185], v[46:49]
	v_mfma_f32_16x16x32_bf16 v[42:45], v[158:161], v[182:185], v[42:45]
	v_mfma_f32_16x16x32_bf16 v[38:41], v[150:153], v[190:193], v[38:41]
	v_mfma_f32_16x16x32_bf16 v[34:37], v[158:161], v[190:193], v[34:37]
	s_barrier
	s_add_i32 s0, s20, s50
	v_lshl_add_u64 v[208:209], s[80:81], 0, v[198:199]
	s_mov_b32 m0, s0
	ds_read_b128 v[162:165], v232 offset:16384
	ds_read_b128 v[166:169], v232 offset:17408
	ds_read_b128 v[170:173], v232 offset:18432
	ds_read_b128 v[174:177], v232 offset:19456
	ds_read_b128 v[178:181], v232 offset:20480
	ds_read_b128 v[182:185], v232 offset:21504
	ds_read_b128 v[186:189], v232 offset:22528
	ds_read_b128 v[190:193], v232 offset:23552
	global_load_lds_dwordx4 v[208:209], off
	s_add_i32 m0, s0, 0x2000
	s_add_u32 s0, s80, 0x20000
	v_lshl_add_u64 v[210:211], s[80:81], 0, v[202:203]
	s_addc_u32 s1, s81, 0
	s_add_i32 s20, s26, s50
	global_load_lds_dwordx4 v[210:211], off
	v_lshl_add_u64 v[212:213], s[0:1], 0, v[198:199]
	s_mov_b32 m0, s20
	v_lshl_add_u64 v[214:215], s[82:83], 0, v[200:201]
	global_load_lds_dwordx4 v[212:213], off
	v_lshl_add_u64 v[212:213], s[0:1], 0, v[202:203]
	s_add_i32 m0, s20, 0x2000
	s_nop 0
	global_load_lds_dwordx4 v[212:213], off
	v_lshl_add_u64 v[212:213], s[82:83], 0, v[196:197]
	s_mov_b32 m0, s60
	s_nop 0
	global_load_lds_dwordx4 v[212:213], off
	s_mov_b32 m0, s61
	s_nop 0
	global_load_lds_dwordx4 v[214:215], off
	s_waitcnt vmcnt(8)
	s_waitcnt lgkmcnt(0)
	s_barrier
; #define PG8_STAGE(bufoff, gbase, voff) do { _Pragma("unroll") for (int _i = 0; _i < 2; ++_i) \
;         __builtin_amdgcn_global_load_lds((const unsigned*)((const char*)(gbase) + (voff)[_i]), (LAS unsigned*)(lds + (bufoff) + ldsw + _i * 8192), 16, 0, 0); } while (0)
; #define PG8_LDA(dst, b, h) do { _Pragma("unroll") for (int m = 0; m < 4; ++m) _Pragma("unroll") for (int k = 0; k < 2; ++k) dst[m][k] = *(const LAS bf16x8*)(lds + PG8_SA(b, h) + aoff + m * 2048 + k * 1024); } while (0)
; #define PG8_LDB(dst, b, h) do { _Pragma("unroll") for (int n = 0; n < 2; ++n) _Pragma("unroll") for (int k = 0; k < 2; ++k) dst[n][k] = *(const LAS bf16x8*)(lds + PG8_SB(b, h) + boff + n * 2048 + k * 1024); } while (0)
; #define PG8_MMA(ai, bj, At, Bt) do { __builtin_amdgcn_s_setprio(1); _Pragma("unroll") for (int m = 0; m < 4; ++m) _Pragma("unroll") for (int n = 0; n < 2; ++n) _Pragma("unroll") for (int k = 0; k < 2; ++k) \
;         acc[ai][bj][m][n] = __builtin_amdgcn_mfma_f32_16x16x32_bf16(Bt[n][k], At[m][k], acc[ai][bj][m][n], 0, 0, 0); __builtin_amdgcn_s_setprio(0); } while (0)
; #define PG8_WAIT_V(n) asm volatile("s_waitcnt vmcnt(" #n ")" ::: "memory")
; #define PG8_WAIT_L(n) asm volatile("s_waitcnt lgkmcnt(" #n ")" ::: "memory")
; #define PG8_BAR __builtin_amdgcn_s_barrier()
; #define PG8_SCHED __builtin_amdgcn_sched_barrier(0)
; template <class Epi, class Sched>
; __device__ __forceinline__ void gemm_phase(LAS unsigned char* lds, const Gemm g, const Sched& S, const Epi& E, int wv) {
;     ...
;             PG8_WAIT_V(8); PG8_WAIT_L(0); PG8_BAR; PG8_MMA(1, 0, At, B0); PG8_MMA(1, 1, At, B1); PG8_BAR; PG8_SCHED;
;             PG8_LDB(B0, 1, 0); PG8_LDB(B1, 1, 1); PG8_SCHED; PG8_LDA(At, 1, 0); PG8_STAGE(PG8_SA(0, 1), a2 + hstepA, voffA);
;             PG8_WAIT_V(8); PG8_WAIT_L(0); PG8_BAR; PG8_MMA(0, 0, At, B0); PG8_MMA(0, 1, At, B1); PG8_BAR; PG8_SCHED;
	v_mfma_f32_16x16x32_bf16 v[94:97], v[114:117], v[162:165], v[94:97]
	v_mfma_f32_16x16x32_bf16 v[90:93], v[130:133], v[162:165], v[90:93]
	v_mfma_f32_16x16x32_bf16 v[86:89], v[114:117], v[170:173], v[86:89]
	v_mfma_f32_16x16x32_bf16 v[82:85], v[130:133], v[170:173], v[82:85]
	v_mfma_f32_16x16x32_bf16 v[78:81], v[114:117], v[178:181], v[78:81]
	v_mfma_f32_16x16x32_bf16 v[74:77], v[130:133], v[178:181], v[74:77]
	v_mfma_f32_16x16x32_bf16 v[70:73], v[114:117], v[186:189], v[70:73]
	v_mfma_f32_16x16x32_bf16 v[66:69], v[130:133], v[186:189], v[66:69]
	v_mfma_f32_16x16x32_bf16 v[94:97], v[118:121], v[166:169], v[94:97]
	v_mfma_f32_16x16x32_bf16 v[90:93], v[134:137], v[166:169], v[90:93]
	v_mfma_f32_16x16x32_bf16 v[86:89], v[118:121], v[174:177], v[86:89]
	v_mfma_f32_16x16x32_bf16 v[82:85], v[134:137], v[174:177], v[82:85]
	v_mfma_f32_16x16x32_bf16 v[78:81], v[118:121], v[182:185], v[78:81]
	v_mfma_f32_16x16x32_bf16 v[74:77], v[134:137], v[182:185], v[74:77]
	v_mfma_f32_16x16x32_bf16 v[70:73], v[118:121], v[190:193], v[70:73]
	v_mfma_f32_16x16x32_bf16 v[66:69], v[134:137], v[190:193], v[66:69]
	v_mfma_f32_16x16x32_bf16 v[30:33], v[146:149], v[162:165], v[30:33]
	v_mfma_f32_16x16x32_bf16 v[26:29], v[154:157], v[162:165], v[26:29]
	v_mfma_f32_16x16x32_bf16 v[22:25], v[146:149], v[170:173], v[22:25]
	v_mfma_f32_16x16x32_bf16 v[18:21], v[154:157], v[170:173], v[18:21]
	v_mfma_f32_16x16x32_bf16 v[14:17], v[146:149], v[178:181], v[14:17]
	v_mfma_f32_16x16x32_bf16 v[10:13], v[154:157], v[178:181], v[10:13]
	v_mfma_f32_16x16x32_bf16 v[6:9], v[146:149], v[186:189], v[6:9]
	v_mfma_f32_16x16x32_bf16 v[2:5], v[154:157], v[186:189], v[2:5]
	v_mfma_f32_16x16x32_bf16 v[30:33], v[150:153], v[166:169], v[30:33]
	v_mfma_f32_16x16x32_bf16 v[26:29], v[158:161], v[166:169], v[26:29]
	v_mfma_f32_16x16x32_bf16 v[22:25], v[150:153], v[174:177], v[22:25]
	v_mfma_f32_16x16x32_bf16 v[18:21], v[158:161], v[174:177], v[18:21]
	v_mfma_f32_16x16x32_bf16 v[14:17], v[150:153], v[182:185], v[14:17]
	v_mfma_f32_16x16x32_bf16 v[10:13], v[158:161], v[182:185], v[10:13]
	v_mfma_f32_16x16x32_bf16 v[6:9], v[150:153], v[190:193], v[6:9]
	v_mfma_f32_16x16x32_bf16 v[2:5], v[158:161], v[190:193], v[2:5]
	s_barrier
	s_add_i32 s20, 0, 0x18000
	v_add_u32_e32 v0, s20, v231
	s_add_i32 s26, 0, 0x1c000
	ds_read_b128 v[114:117], v0
	ds_read_b128 v[118:121], v0 offset:1024
	ds_read_b128 v[130:133], v0 offset:2048
	ds_read_b128 v[134:137], v0 offset:3072
	v_add_u32_e32 v0, s26, v231
	ds_read_b128 v[146:149], v0
	ds_read_b128 v[150:153], v0 offset:1024
	ds_read_b128 v[154:157], v0 offset:2048
	ds_read_b128 v[158:161], v0 offset:3072
	s_add_u32 s0, s82, 0x100000
	s_addc_u32 s1, s83, 0
	s_mov_b32 m0, s62
	v_lshl_add_u64 v[216:217], s[0:1], 0, v[196:197]
	ds_read_b128 v[162:165], v232 offset:32768
	ds_read_b128 v[166:169], v232 offset:33792
	ds_read_b128 v[170:173], v232 offset:34816
	ds_read_b128 v[174:177], v232 offset:35840
	ds_read_b128 v[178:181], v232 offset:36864
	ds_read_b128 v[182:185], v232 offset:37888
	ds_read_b128 v[186:189], v232 offset:38912
	ds_read_b128 v[190:193], v232 offset:39936
	global_load_lds_dwordx4 v[216:217], off
	v_lshl_add_u64 v[216:217], s[0:1], 0, v[200:201]
	s_mov_b32 m0, s84
	s_nop 0
	global_load_lds_dwordx4 v[216:217], off
	s_waitcnt vmcnt(8)
	s_waitcnt lgkmcnt(0)
	s_barrier
	v_mfma_f32_16x16x32_bf16 v[142:145], v[114:117], v[162:165], v[142:145]
	v_mfma_f32_16x16x32_bf16 v[138:141], v[130:133], v[162:165], v[138:141]
	v_mfma_f32_16x16x32_bf16 v[126:129], v[114:117], v[170:173], v[126:129]
	v_mfma_f32_16x16x32_bf16 v[122:125], v[130:133], v[170:173], v[122:125]
	v_mfma_f32_16x16x32_bf16 v[110:113], v[114:117], v[178:181], v[110:113]
	v_mfma_f32_16x16x32_bf16 v[106:109], v[130:133], v[178:181], v[106:109]
	v_mfma_f32_16x16x32_bf16 v[102:105], v[114:117], v[186:189], v[102:105]
	v_mfma_f32_16x16x32_bf16 v[98:101], v[130:133], v[186:189], v[98:101]
	v_mfma_f32_16x16x32_bf16 v[142:145], v[118:121], v[166:169], v[142:145]
	v_mfma_f32_16x16x32_bf16 v[138:141], v[134:137], v[166:169], v[138:141]
	v_mfma_f32_16x16x32_bf16 v[126:129], v[118:121], v[174:177], v[126:129]
	v_mfma_f32_16x16x32_bf16 v[122:125], v[134:137], v[174:177], v[122:125]
	v_mfma_f32_16x16x32_bf16 v[110:113], v[118:121], v[182:185], v[110:113]
	v_mfma_f32_16x16x32_bf16 v[106:109], v[134:137], v[182:185], v[106:109]
	v_mfma_f32_16x16x32_bf16 v[102:105], v[118:121], v[190:193], v[102:105]
	v_mfma_f32_16x16x32_bf16 v[98:101], v[134:137], v[190:193], v[98:101]
	v_mfma_f32_16x16x32_bf16 v[62:65], v[146:149], v[162:165], v[62:65]
	v_mfma_f32_16x16x32_bf16 v[58:61], v[154:157], v[162:165], v[58:61]
	v_mfma_f32_16x16x32_bf16 v[54:57], v[146:149], v[170:173], v[54:57]
	v_mfma_f32_16x16x32_bf16 v[50:53], v[154:157], v[170:173], v[50:53]
	v_mfma_f32_16x16x32_bf16 v[46:49], v[146:149], v[178:181], v[46:49]
	v_mfma_f32_16x16x32_bf16 v[42:45], v[154:157], v[178:181], v[42:45]
	v_mfma_f32_16x16x32_bf16 v[38:41], v[146:149], v[186:189], v[38:41]
	v_mfma_f32_16x16x32_bf16 v[34:37], v[154:157], v[186:189], v[34:37]
	v_mfma_f32_16x16x32_bf16 v[62:65], v[150:153], v[166:169], v[62:65]
	v_mfma_f32_16x16x32_bf16 v[58:61], v[158:161], v[166:169], v[58:61]
	v_mfma_f32_16x16x32_bf16 v[54:57], v[150:153], v[174:177], v[54:57]
	v_mfma_f32_16x16x32_bf16 v[50:53], v[158:161], v[174:177], v[50:53]
	v_mfma_f32_16x16x32_bf16 v[46:49], v[150:153], v[182:185], v[46:49]
	v_mfma_f32_16x16x32_bf16 v[42:45], v[158:161], v[182:185], v[42:45]
	v_mfma_f32_16x16x32_bf16 v[38:41], v[150:153], v[190:193], v[38:41]
	v_mfma_f32_16x16x32_bf16 v[34:37], v[158:161], v[190:193], v[34:37]
	s_barrier
; #define PG8_STAGE(bufoff, gbase, voff) do { _Pragma("unroll") for (int _i = 0; _i < 2; ++_i) \
;         __builtin_amdgcn_global_load_lds((const unsigned*)((const char*)(gbase) + (voff)[_i]), (LAS unsigned*)(lds + (bufoff) + ldsw + _i * 8192), 16, 0, 0); } while (0)
; #define PG8_LDA(dst, b, h) do { _Pragma("unroll") for (int m = 0; m < 4; ++m) _Pragma("unroll") for (int k = 0; k < 2; ++k) dst[m][k] = *(const LAS bf16x8*)(lds + PG8_SA(b, h) + aoff + m * 2048 + k * 1024); } while (0)
; #define PG8_MMA(ai, bj, At, Bt) do { __builtin_amdgcn_s_setprio(1); _Pragma("unroll") for (int m = 0; m < 4; ++m) _Pragma("unroll") for (int n = 0; n < 2; ++n) _Pragma("unroll") for (int k = 0; k < 2; ++k) \
;         acc[ai][bj][m][n] = __builtin_amdgcn_mfma_f32_16x16x32_bf16(Bt[n][k], At[m][k], acc[ai][bj][m][n], 0, 0, 0); __builtin_amdgcn_s_setprio(0); } while (0)
; #define PG8_WAIT_V(n) asm volatile("s_waitcnt vmcnt(" #n ")" ::: "memory")
; #define PG8_WAIT_L(n) asm volatile("s_waitcnt lgkmcnt(" #n ")" ::: "memory")
; #define PG8_BAR __builtin_amdgcn_s_barrier()
; #define PG8_SCHED __builtin_amdgcn_sched_barrier(0)
; template <class Epi, class Sched>
; __device__ __forceinline__ void gemm_phase(LAS unsigned char* lds, const Gemm g, const Sched& S, const Epi& E, int wv) {
;     ...
;         for (int t = 0; t < nt; t += 2) {
;     ...
;             PG8_LDA(At, 1, 1); PG8_STAGE(PG8_SB(1, 0), b3, voffB); PG8_STAGE(PG8_SB(1, 1), b3 + hstepB, voffB); PG8_STAGE(PG8_SA(1, 0), a3, voffA);
;             PG8_WAIT_V(8); PG8_WAIT_L(0); PG8_BAR; PG8_MMA(1, 0, At, B0); PG8_MMA(1, 1, At, B1); PG8_BAR; PG8_SCHED;
;         }
	s_add_i32 s0, s20, s50
	v_lshl_add_u64 v[208:209], v[208:209], 0, s[24:25]
	s_mov_b32 m0, s0
	ds_read_b128 v[162:165], v232 offset:49152
	ds_read_b128 v[166:169], v232 offset:50176
	ds_read_b128 v[170:173], v232 offset:51200
	ds_read_b128 v[174:177], v232 offset:52224
	ds_read_b128 v[178:181], v232 offset:53248
	ds_read_b128 v[182:185], v232 offset:54272
	ds_read_b128 v[186:189], v232 offset:55296
	ds_read_b128 v[190:193], v232 offset:56320
	global_load_lds_dwordx4 v[208:209], off
	s_add_i32 m0, s0, 0x2000
	s_add_u32 s0, s80, 0x20080
	v_lshl_add_u64 v[208:209], v[210:211], 0, s[24:25]
	s_addc_u32 s1, s81, 0
	s_add_i32 s20, s26, s50
	global_load_lds_dwordx4 v[208:209], off
	v_lshl_add_u64 v[208:209], s[0:1], 0, v[198:199]
	s_mov_b32 m0, s20
	s_nop 0
	global_load_lds_dwordx4 v[208:209], off
	v_lshl_add_u64 v[208:209], s[0:1], 0, v[202:203]
	s_add_i32 m0, s20, 0x2000
	s_nop 0
	global_load_lds_dwordx4 v[208:209], off
	v_lshl_add_u64 v[208:209], v[212:213], 0, s[24:25]
	s_mov_b32 m0, s85
	s_nop 0
	global_load_lds_dwordx4 v[208:209], off
	v_lshl_add_u64 v[208:209], v[214:215], 0, s[24:25]
	s_mov_b32 m0, s86
	s_nop 0
	global_load_lds_dwordx4 v[208:209], off
	s_waitcnt vmcnt(8)
	s_waitcnt lgkmcnt(0)
	s_barrier
	v_mfma_f32_16x16x32_bf16 v[94:97], v[114:117], v[162:165], v[94:97]
	v_mfma_f32_16x16x32_bf16 v[90:93], v[130:133], v[162:165], v[90:93]
	v_mfma_f32_16x16x32_bf16 v[86:89], v[114:117], v[170:173], v[86:89]
	v_mfma_f32_16x16x32_bf16 v[82:85], v[130:133], v[170:173], v[82:85]
	v_mfma_f32_16x16x32_bf16 v[78:81], v[114:117], v[178:181], v[78:81]
	v_mfma_f32_16x16x32_bf16 v[74:77], v[130:133], v[178:181], v[74:77]
	v_mfma_f32_16x16x32_bf16 v[70:73], v[114:117], v[186:189], v[70:73]
	v_mfma_f32_16x16x32_bf16 v[66:69], v[130:133], v[186:189], v[66:69]
	v_mfma_f32_16x16x32_bf16 v[94:97], v[118:121], v[166:169], v[94:97]
	v_mfma_f32_16x16x32_bf16 v[90:93], v[134:137], v[166:169], v[90:93]
	v_mfma_f32_16x16x32_bf16 v[86:89], v[118:121], v[174:177], v[86:89]
	v_mfma_f32_16x16x32_bf16 v[82:85], v[134:137], v[174:177], v[82:85]
	v_mfma_f32_16x16x32_bf16 v[78:81], v[118:121], v[182:185], v[78:81]
	v_mfma_f32_16x16x32_bf16 v[74:77], v[134:137], v[182:185], v[74:77]
	v_mfma_f32_16x16x32_bf16 v[70:73], v[118:121], v[190:193], v[70:73]
	v_mfma_f32_16x16x32_bf16 v[66:69], v[134:137], v[190:193], v[66:69]
	v_mfma_f32_16x16x32_bf16 v[30:33], v[146:149], v[162:165], v[30:33]
	v_mfma_f32_16x16x32_bf16 v[26:29], v[154:157], v[162:165], v[26:29]
	v_mfma_f32_16x16x32_bf16 v[22:25], v[146:149], v[170:173], v[22:25]
	v_mfma_f32_16x16x32_bf16 v[18:21], v[154:157], v[170:173], v[18:21]
	v_mfma_f32_16x16x32_bf16 v[14:17], v[146:149], v[178:181], v[14:17]
	v_mfma_f32_16x16x32_bf16 v[10:13], v[154:157], v[178:181], v[10:13]
	v_mfma_f32_16x16x32_bf16 v[6:9], v[146:149], v[186:189], v[6:9]
	v_mfma_f32_16x16x32_bf16 v[2:5], v[154:157], v[186:189], v[2:5]
	v_mfma_f32_16x16x32_bf16 v[30:33], v[150:153], v[166:169], v[30:33]
	v_mfma_f32_16x16x32_bf16 v[26:29], v[158:161], v[166:169], v[26:29]
	v_mfma_f32_16x16x32_bf16 v[22:25], v[150:153], v[174:177], v[22:25]
	v_mfma_f32_16x16x32_bf16 v[18:21], v[158:161], v[174:177], v[18:21]
	v_mfma_f32_16x16x32_bf16 v[14:17], v[150:153], v[182:185], v[14:17]
	v_mfma_f32_16x16x32_bf16 v[10:13], v[158:161], v[182:185], v[10:13]
	v_mfma_f32_16x16x32_bf16 v[6:9], v[150:153], v[190:193], v[6:9]
	v_mfma_f32_16x16x32_bf16 v[2:5], v[158:161], v[190:193], v[2:5]
	s_barrier
	s_add_i32 s34, s34, 2
	s_add_u32 s78, s78, 0x100
	s_addc_u32 s79, s79, 0
	s_add_u32 s21, s21, 0x100
	s_addc_u32 s31, s31, 0
	s_cmp_gt_i32 s34, s17
	s_cbranch_scc0 .LBB0_556
	s_and_b64 vcc, exec, s[68:69]
	s_cbranch_vccz .LBB0_559
	s_barrier

; #define PG8_STAGE(bufoff, gbase, voff) do { _Pragma("unroll") for (int _i = 0; _i < 2; ++_i) \
;         __builtin_amdgcn_global_load_lds((const unsigned*)((const char*)(gbase) + (voff)[_i]), (LAS unsigned*)(lds + (bufoff) + ldsw + _i * 8192), 16, 0, 0); } while (0)
; #define PG8_LDA(dst, b, h) do { _Pragma("unroll") for (int m = 0; m < 4; ++m) _Pragma("unroll") for (int k = 0; k < 2; ++k) dst[m][k] = *(const LAS bf16x8*)(lds + PG8_SA(b, h) + aoff + m * 2048 + k * 1024); } while (0)
; #define PG8_LDB(dst, b, h) do { _Pragma("unroll") for (int n = 0; n < 2; ++n) _Pragma("unroll") for (int k = 0; k < 2; ++k) dst[n][k] = *(const LAS bf16x8*)(lds + PG8_SB(b, h) + boff + n * 2048 + k * 1024); } while (0)
; #define PG8_MMA(ai, bj, At, Bt) do { __builtin_amdgcn_s_setprio(1); _Pragma("unroll") for (int m = 0; m < 4; ++m) _Pragma("unroll") for (int n = 0; n < 2; ++n) _Pragma("unroll") for (int k = 0; k < 2; ++k) \
;         acc[ai][bj][m][n] = __builtin_amdgcn_mfma_f32_16x16x32_bf16(Bt[n][k], At[m][k], acc[ai][bj][m][n], 0, 0, 0); __builtin_amdgcn_s_setprio(0); } while (0)
; #define PG8_WAIT_V(n) asm volatile("s_waitcnt vmcnt(" #n ")" ::: "memory")
; #define PG8_WAIT_L(n) asm volatile("s_waitcnt lgkmcnt(" #n ")" ::: "memory")
; #define PG8_BAR __builtin_amdgcn_s_barrier()
; template <class Epi, class Sched>
; __device__ __forceinline__ void gemm_phase(LAS unsigned char* lds, const Gemm g, const Sched& S, const Epi& E, int wv) {
;     ...
;         const char* nA = has_next ? (const char*)g.A + (size_t)nxt.pm * tstepA + (size_t)nxt.ak * 2 : cA; const char* nB = has_next ? (const char*)g.Bt + (size_t)nxt.pn * tstepB : cB;
;         for (int t = 0; t < nt; t += 2) {
;             const bool last = (t == nt - 2);
;             const char* a1 = cA + (size_t)(t + 1) * kstep;
;             const char* a2 = last ? nA : cA + (size_t)(t + 2) * kstep; const char* b2 = last ? nB : cB + (size_t)(t + 2) * kstep;
;             const char* a3 = a2 + kstep; const char* b3 = b2 + kstep;
;             PG8_LDB(B0, 0, 0); PG8_LDB(B1, 0, 1); PG8_SCHED; PG8_LDA(At, 0, 0); PG8_STAGE(PG8_SA(1, 1), a1 + hstepA, voffA);
;             PG8_WAIT_V(8); PG8_WAIT_L(0); PG8_BAR; PG8_MMA(0, 0, At, B0); PG8_MMA(0, 1, At, B1); PG8_BAR; PG8_SCHED;
;             PG8_LDA(At, 0, 1); PG8_STAGE(PG8_SB(0, 0), b2, voffB); PG8_STAGE(PG8_SB(0, 1), b2 + hstepB, voffB); PG8_STAGE(PG8_SA(0, 0), a2, voffA);
.LBB0_717:
	s_add_u32 s0, s8, 0xfffc0080
	s_addc_u32 s1, s9, -1
	s_add_i32 s20, 0, 0x10000
	s_cmp_eq_u32 s35, 12
	s_cselect_b32 s13, s5, s1
	s_cselect_b32 s12, s7, s0
	s_waitcnt lgkmcnt(0)
	v_add_u32_e32 v0, s20, v178
	s_cselect_b32 s11, s21, s34
	s_cselect_b32 s10, s22, s31
	s_add_i32 s26, 0, 0x14000
	ds_read_b128 v[142:145], v0
	ds_read_b128 v[146:149], v0 offset:1024
	ds_read_b128 v[150:153], v0 offset:2048
	ds_read_b128 v[154:157], v0 offset:3072
	v_add_u32_e32 v0, s26, v178
	ds_read_b128 v[158:161], v0
	ds_read_b128 v[162:165], v0 offset:1024
	ds_read_b128 v[166:169], v0 offset:2048
	ds_read_b128 v[170:173], v0 offset:3072
	v_lshl_add_u64 v[192:193], s[8:9], 0, v[138:139]
	s_add_i32 m0, s49, 0xc000
	ds_read_b128 v[174:177], v179
	ds_read_b128 v[180:183], v179 offset:1024
	ds_read_b128 v[184:187], v179 offset:2048
	ds_read_b128 v[188:191], v179 offset:3072
	ds_read_b128 v[196:199], v179 offset:4096
	ds_read_b128 v[200:203], v179 offset:5120
	ds_read_b128 v[204:207], v179 offset:6144
	ds_read_b128 v[208:211], v179 offset:7168
	global_load_lds_dwordx4 v[192:193], off
	v_lshl_add_u64 v[192:193], s[8:9], 0, v[140:141]
	s_add_i32 m0, s49, 0xe000
	s_nop 0
	global_load_lds_dwordx4 v[192:193], off
	s_waitcnt vmcnt(8)
	s_waitcnt lgkmcnt(0)
	s_barrier
	v_mfma_f32_16x16x32_bf16 v[126:129], v[142:145], v[174:177], v[126:129]
	v_mfma_f32_16x16x32_bf16 v[122:125], v[150:153], v[174:177], v[122:125]
	v_mfma_f32_16x16x32_bf16 v[110:113], v[142:145], v[184:187], v[110:113]
	v_mfma_f32_16x16x32_bf16 v[106:109], v[150:153], v[184:187], v[106:109]
	v_mfma_f32_16x16x32_bf16 v[94:97], v[142:145], v[196:199], v[94:97]
	v_mfma_f32_16x16x32_bf16 v[90:93], v[150:153], v[196:199], v[90:93]
	v_mfma_f32_16x16x32_bf16 v[78:81], v[142:145], v[204:207], v[78:81]
	v_mfma_f32_16x16x32_bf16 v[74:77], v[150:153], v[204:207], v[74:77]
	v_mfma_f32_16x16x32_bf16 v[126:129], v[146:149], v[180:183], v[126:129]
	v_mfma_f32_16x16x32_bf16 v[122:125], v[154:157], v[180:183], v[122:125]
	v_mfma_f32_16x16x32_bf16 v[110:113], v[146:149], v[188:191], v[110:113]
	v_mfma_f32_16x16x32_bf16 v[106:109], v[154:157], v[188:191], v[106:109]
	v_mfma_f32_16x16x32_bf16 v[94:97], v[146:149], v[200:203], v[94:97]
	v_mfma_f32_16x16x32_bf16 v[90:93], v[154:157], v[200:203], v[90:93]
	v_mfma_f32_16x16x32_bf16 v[78:81], v[146:149], v[208:211], v[78:81]
	v_mfma_f32_16x16x32_bf16 v[74:77], v[154:157], v[208:211], v[74:77]
	v_mfma_f32_16x16x32_bf16 v[118:121], v[158:161], v[174:177], v[118:121]
	v_mfma_f32_16x16x32_bf16 v[114:117], v[166:169], v[174:177], v[114:117]
	v_mfma_f32_16x16x32_bf16 v[102:105], v[158:161], v[184:187], v[102:105]
	v_mfma_f32_16x16x32_bf16 v[98:101], v[166:169], v[184:187], v[98:101]
	v_mfma_f32_16x16x32_bf16 v[86:89], v[158:161], v[196:199], v[86:89]
	v_mfma_f32_16x16x32_bf16 v[82:85], v[166:169], v[196:199], v[82:85]
	v_mfma_f32_16x16x32_bf16 v[70:73], v[158:161], v[204:207], v[70:73]
	v_mfma_f32_16x16x32_bf16 v[66:69], v[166:169], v[204:207], v[66:69]
	v_mfma_f32_16x16x32_bf16 v[118:121], v[162:165], v[180:183], v[118:121]
	v_mfma_f32_16x16x32_bf16 v[114:117], v[170:173], v[180:183], v[114:117]
	v_mfma_f32_16x16x32_bf16 v[102:105], v[162:165], v[188:191], v[102:105]
	v_mfma_f32_16x16x32_bf16 v[98:101], v[170:173], v[188:191], v[98:101]
	v_mfma_f32_16x16x32_bf16 v[86:89], v[162:165], v[200:203], v[86:89]
	v_mfma_f32_16x16x32_bf16 v[82:85], v[170:173], v[200:203], v[82:85]
	v_mfma_f32_16x16x32_bf16 v[70:73], v[162:165], v[208:211], v[70:73]
	v_mfma_f32_16x16x32_bf16 v[66:69], v[170:173], v[208:211], v[66:69]
	s_barrier
	s_add_i32 s0, s20, s48
	v_lshl_add_u64 v[192:193], s[10:11], 0, v[132:133]
	s_mov_b32 m0, s0
	ds_read_b128 v[174:177], v179 offset:16384
	ds_read_b128 v[180:183], v179 offset:17408
	ds_read_b128 v[184:187], v179 offset:18432
	ds_read_b128 v[188:191], v179 offset:19456
	ds_read_b128 v[196:199], v179 offset:20480
	ds_read_b128 v[200:203], v179 offset:21504
	ds_read_b128 v[204:207], v179 offset:22528
	ds_read_b128 v[208:211], v179 offset:23552
	global_load_lds_dwordx4 v[192:193], off
	s_add_i32 m0, s0, 0x2000
	s_add_u32 s0, s10, 0x40000
	v_lshl_add_u64 v[212:213], s[10:11], 0, v[136:137]
	s_addc_u32 s1, s11, 0
	s_add_i32 s20, s26, s48
	global_load_lds_dwordx4 v[212:213], off
	v_lshl_add_u64 v[214:215], s[0:1], 0, v[132:133]
	s_mov_b32 m0, s20
	v_lshl_add_u64 v[216:217], s[12:13], 0, v[134:135]
	global_load_lds_dwordx4 v[214:215], off
	v_lshl_add_u64 v[214:215], s[0:1], 0, v[136:137]
	s_add_i32 m0, s20, 0x2000
	s_nop 0
	global_load_lds_dwordx4 v[214:215], off
	v_lshl_add_u64 v[214:215], s[12:13], 0, v[130:131]
	s_mov_b32 m0, s49
	s_nop 0
	global_load_lds_dwordx4 v[214:215], off
	s_mov_b32 m0, s50
	s_nop 0
	global_load_lds_dwordx4 v[216:217], off
	s_waitcnt vmcnt(8)
	s_waitcnt lgkmcnt(0)
	s_barrier
; #define PG8_STAGE(bufoff, gbase, voff) do { _Pragma("unroll") for (int _i = 0; _i < 2; ++_i) \
;         __builtin_amdgcn_global_load_lds((const unsigned*)((const char*)(gbase) + (voff)[_i]), (LAS unsigned*)(lds + (bufoff) + ldsw + _i * 8192), 16, 0, 0); } while (0)
; #define PG8_LDA(dst, b, h) do { _Pragma("unroll") for (int m = 0; m < 4; ++m) _Pragma("unroll") for (int k = 0; k < 2; ++k) dst[m][k] = *(const LAS bf16x8*)(lds + PG8_SA(b, h) + aoff + m * 2048 + k * 1024); } while (0)
; #define PG8_LDB(dst, b, h) do { _Pragma("unroll") for (int n = 0; n < 2; ++n) _Pragma("unroll") for (int k = 0; k < 2; ++k) dst[n][k] = *(const LAS bf16x8*)(lds + PG8_SB(b, h) + boff + n * 2048 + k * 1024); } while (0)
; #define PG8_MMA(ai, bj, At, Bt) do { __builtin_amdgcn_s_setprio(1); _Pragma("unroll") for (int m = 0; m < 4; ++m) _Pragma("unroll") for (int n = 0; n < 2; ++n) _Pragma("unroll") for (int k = 0; k < 2; ++k) \
;         acc[ai][bj][m][n] = __builtin_amdgcn_mfma_f32_16x16x32_bf16(Bt[n][k], At[m][k], acc[ai][bj][m][n], 0, 0, 0); __builtin_amdgcn_s_setprio(0); } while (0)
; #define PG8_WAIT_V(n) asm volatile("s_waitcnt vmcnt(" #n ")" ::: "memory")
; #define PG8_WAIT_L(n) asm volatile("s_waitcnt lgkmcnt(" #n ")" ::: "memory")
; #define PG8_BAR __builtin_amdgcn_s_barrier()
; #define PG8_SCHED __builtin_amdgcn_sched_barrier(0)
; template <class Epi, class Sched>
; __device__ __forceinline__ void gemm_phase(LAS unsigned char* lds, const Gemm g, const Sched& S, const Epi& E, int wv) {
;     ...
;             PG8_WAIT_V(8); PG8_WAIT_L(0); PG8_BAR; PG8_MMA(1, 0, At, B0); PG8_MMA(1, 1, At, B1); PG8_BAR; PG8_SCHED;
;             PG8_LDB(B0, 1, 0); PG8_LDB(B1, 1, 1); PG8_SCHED; PG8_LDA(At, 1, 0); PG8_STAGE(PG8_SA(0, 1), a2 + hstepA, voffA);
;             PG8_WAIT_V(8); PG8_WAIT_L(0); PG8_BAR; PG8_MMA(0, 0, At, B0); PG8_MMA(0, 1, At, B1); PG8_BAR; PG8_SCHED;
	v_mfma_f32_16x16x32_bf16 v[62:65], v[142:145], v[174:177], v[62:65]
	v_mfma_f32_16x16x32_bf16 v[58:61], v[150:153], v[174:177], v[58:61]
	v_mfma_f32_16x16x32_bf16 v[46:49], v[142:145], v[184:187], v[46:49]
	v_mfma_f32_16x16x32_bf16 v[42:45], v[150:153], v[184:187], v[42:45]
	v_mfma_f32_16x16x32_bf16 v[30:33], v[142:145], v[196:199], v[30:33]
	v_mfma_f32_16x16x32_bf16 v[26:29], v[150:153], v[196:199], v[26:29]
	v_mfma_f32_16x16x32_bf16 v[14:17], v[142:145], v[204:207], v[14:17]
	v_mfma_f32_16x16x32_bf16 v[10:13], v[150:153], v[204:207], v[10:13]
	v_mfma_f32_16x16x32_bf16 v[62:65], v[146:149], v[180:183], v[62:65]
	v_mfma_f32_16x16x32_bf16 v[58:61], v[154:157], v[180:183], v[58:61]
	v_mfma_f32_16x16x32_bf16 v[46:49], v[146:149], v[188:191], v[46:49]
	v_mfma_f32_16x16x32_bf16 v[42:45], v[154:157], v[188:191], v[42:45]
	v_mfma_f32_16x16x32_bf16 v[30:33], v[146:149], v[200:203], v[30:33]
	v_mfma_f32_16x16x32_bf16 v[26:29], v[154:157], v[200:203], v[26:29]
	v_mfma_f32_16x16x32_bf16 v[14:17], v[146:149], v[208:211], v[14:17]
	v_mfma_f32_16x16x32_bf16 v[10:13], v[154:157], v[208:211], v[10:13]
	v_mfma_f32_16x16x32_bf16 v[54:57], v[158:161], v[174:177], v[54:57]
	v_mfma_f32_16x16x32_bf16 v[50:53], v[166:169], v[174:177], v[50:53]
	v_mfma_f32_16x16x32_bf16 v[38:41], v[158:161], v[184:187], v[38:41]
	v_mfma_f32_16x16x32_bf16 v[34:37], v[166:169], v[184:187], v[34:37]
	v_mfma_f32_16x16x32_bf16 v[22:25], v[158:161], v[196:199], v[22:25]
	v_mfma_f32_16x16x32_bf16 v[18:21], v[166:169], v[196:199], v[18:21]
	v_mfma_f32_16x16x32_bf16 v[6:9], v[158:161], v[204:207], v[6:9]
	v_mfma_f32_16x16x32_bf16 v[2:5], v[166:169], v[204:207], v[2:5]
	v_mfma_f32_16x16x32_bf16 v[54:57], v[162:165], v[180:183], v[54:57]
	v_mfma_f32_16x16x32_bf16 v[50:53], v[170:173], v[180:183], v[50:53]
	v_mfma_f32_16x16x32_bf16 v[38:41], v[162:165], v[188:191], v[38:41]
	v_mfma_f32_16x16x32_bf16 v[34:37], v[170:173], v[188:191], v[34:37]
	v_mfma_f32_16x16x32_bf16 v[22:25], v[162:165], v[200:203], v[22:25]
	v_mfma_f32_16x16x32_bf16 v[18:21], v[170:173], v[200:203], v[18:21]
	v_mfma_f32_16x16x32_bf16 v[6:9], v[162:165], v[208:211], v[6:9]
	v_mfma_f32_16x16x32_bf16 v[2:5], v[170:173], v[208:211], v[2:5]
	s_barrier
	s_add_i32 s20, 0, 0x18000
	v_add_u32_e32 v0, s20, v178
	s_add_i32 s26, 0, 0x1c000
	ds_read_b128 v[142:145], v0
	ds_read_b128 v[146:149], v0 offset:1024
	ds_read_b128 v[150:153], v0 offset:2048
	ds_read_b128 v[154:157], v0 offset:3072
	v_add_u32_e32 v0, s26, v178
	ds_read_b128 v[158:161], v0
	ds_read_b128 v[162:165], v0 offset:1024
	ds_read_b128 v[166:169], v0 offset:2048
	ds_read_b128 v[170:173], v0 offset:3072
	s_add_u32 s0, s12, 0x40000
	s_addc_u32 s1, s13, 0
	s_mov_b32 m0, s60
	v_lshl_add_u64 v[218:219], s[0:1], 0, v[130:131]
	ds_read_b128 v[174:177], v179 offset:32768
	ds_read_b128 v[180:183], v179 offset:33792
	ds_read_b128 v[184:187], v179 offset:34816
	ds_read_b128 v[188:191], v179 offset:35840
	ds_read_b128 v[196:199], v179 offset:36864
	ds_read_b128 v[200:203], v179 offset:37888
	ds_read_b128 v[204:207], v179 offset:38912
	ds_read_b128 v[208:211], v179 offset:39936
	global_load_lds_dwordx4 v[218:219], off
	v_lshl_add_u64 v[218:219], s[0:1], 0, v[134:135]
	s_mov_b32 m0, s61
	s_nop 0
	global_load_lds_dwordx4 v[218:219], off
	s_waitcnt vmcnt(8)
	s_waitcnt lgkmcnt(0)
	s_barrier
	v_mfma_f32_16x16x32_bf16 v[126:129], v[142:145], v[174:177], v[126:129]
	v_mfma_f32_16x16x32_bf16 v[122:125], v[150:153], v[174:177], v[122:125]
	v_mfma_f32_16x16x32_bf16 v[110:113], v[142:145], v[184:187], v[110:113]
	v_mfma_f32_16x16x32_bf16 v[106:109], v[150:153], v[184:187], v[106:109]
	v_mfma_f32_16x16x32_bf16 v[94:97], v[142:145], v[196:199], v[94:97]
	v_mfma_f32_16x16x32_bf16 v[90:93], v[150:153], v[196:199], v[90:93]
	v_mfma_f32_16x16x32_bf16 v[78:81], v[142:145], v[204:207], v[78:81]
	v_mfma_f32_16x16x32_bf16 v[74:77], v[150:153], v[204:207], v[74:77]
	v_mfma_f32_16x16x32_bf16 v[126:129], v[146:149], v[180:183], v[126:129]
	v_mfma_f32_16x16x32_bf16 v[122:125], v[154:157], v[180:183], v[122:125]
	v_mfma_f32_16x16x32_bf16 v[110:113], v[146:149], v[188:191], v[110:113]
	v_mfma_f32_16x16x32_bf16 v[106:109], v[154:157], v[188:191], v[106:109]
	v_mfma_f32_16x16x32_bf16 v[94:97], v[146:149], v[200:203], v[94:97]
	v_mfma_f32_16x16x32_bf16 v[90:93], v[154:157], v[200:203], v[90:93]
	v_mfma_f32_16x16x32_bf16 v[78:81], v[146:149], v[208:211], v[78:81]
	v_mfma_f32_16x16x32_bf16 v[74:77], v[154:157], v[208:211], v[74:77]
	v_mfma_f32_16x16x32_bf16 v[118:121], v[158:161], v[174:177], v[118:121]
	v_mfma_f32_16x16x32_bf16 v[114:117], v[166:169], v[174:177], v[114:117]
	v_mfma_f32_16x16x32_bf16 v[102:105], v[158:161], v[184:187], v[102:105]
	v_mfma_f32_16x16x32_bf16 v[98:101], v[166:169], v[184:187], v[98:101]
	v_mfma_f32_16x16x32_bf16 v[86:89], v[158:161], v[196:199], v[86:89]
	v_mfma_f32_16x16x32_bf16 v[82:85], v[166:169], v[196:199], v[82:85]
	v_mfma_f32_16x16x32_bf16 v[70:73], v[158:161], v[204:207], v[70:73]
	v_mfma_f32_16x16x32_bf16 v[66:69], v[166:169], v[204:207], v[66:69]
	v_mfma_f32_16x16x32_bf16 v[118:121], v[162:165], v[180:183], v[118:121]
	v_mfma_f32_16x16x32_bf16 v[114:117], v[170:173], v[180:183], v[114:117]
	v_mfma_f32_16x16x32_bf16 v[102:105], v[162:165], v[188:191], v[102:105]
	v_mfma_f32_16x16x32_bf16 v[98:101], v[170:173], v[188:191], v[98:101]
	v_mfma_f32_16x16x32_bf16 v[86:89], v[162:165], v[200:203], v[86:89]
	v_mfma_f32_16x16x32_bf16 v[82:85], v[170:173], v[200:203], v[82:85]
	v_mfma_f32_16x16x32_bf16 v[70:73], v[162:165], v[208:211], v[70:73]
	v_mfma_f32_16x16x32_bf16 v[66:69], v[170:173], v[208:211], v[66:69]
	s_barrier
; #define PG8_STAGE(bufoff, gbase, voff) do { _Pragma("unroll") for (int _i = 0; _i < 2; ++_i) \
;         __builtin_amdgcn_global_load_lds((const unsigned*)((const char*)(gbase) + (voff)[_i]), (LAS unsigned*)(lds + (bufoff) + ldsw + _i * 8192), 16, 0, 0); } while (0)
; #define PG8_LDA(dst, b, h) do { _Pragma("unroll") for (int m = 0; m < 4; ++m) _Pragma("unroll") for (int k = 0; k < 2; ++k) dst[m][k] = *(const LAS bf16x8*)(lds + PG8_SA(b, h) + aoff + m * 2048 + k * 1024); } while (0)
; #define PG8_MMA(ai, bj, At, Bt) do { __builtin_amdgcn_s_setprio(1); _Pragma("unroll") for (int m = 0; m < 4; ++m) _Pragma("unroll") for (int n = 0; n < 2; ++n) _Pragma("unroll") for (int k = 0; k < 2; ++k) \
;         acc[ai][bj][m][n] = __builtin_amdgcn_mfma_f32_16x16x32_bf16(Bt[n][k], At[m][k], acc[ai][bj][m][n], 0, 0, 0); __builtin_amdgcn_s_setprio(0); } while (0)
; #define PG8_WAIT_V(n) asm volatile("s_waitcnt vmcnt(" #n ")" ::: "memory")
; #define PG8_WAIT_L(n) asm volatile("s_waitcnt lgkmcnt(" #n ")" ::: "memory")
; #define PG8_BAR __builtin_amdgcn_s_barrier()
; #define PG8_SCHED __builtin_amdgcn_sched_barrier(0)
; template <class Epi, class Sched>
; __device__ __forceinline__ void gemm_phase(LAS unsigned char* lds, const Gemm g, const Sched& S, const Epi& E, int wv) {
;     ...
;         for (int t = 0; t < nt; t += 2) {
;     ...
;             PG8_LDA(At, 1, 1); PG8_STAGE(PG8_SB(1, 0), b3, voffB); PG8_STAGE(PG8_SB(1, 1), b3 + hstepB, voffB); PG8_STAGE(PG8_SA(1, 0), a3, voffA);
;             PG8_WAIT_V(8); PG8_WAIT_L(0); PG8_BAR; PG8_MMA(1, 0, At, B0); PG8_MMA(1, 1, At, B1); PG8_BAR; PG8_SCHED;
;         }
	s_add_i32 s0, s20, s48
	v_lshl_add_u64 v[192:193], v[192:193], 0, s[24:25]
	s_mov_b32 m0, s0
	ds_read_b128 v[174:177], v179 offset:49152
	ds_read_b128 v[180:183], v179 offset:50176
	ds_read_b128 v[184:187], v179 offset:51200
	ds_read_b128 v[188:191], v179 offset:52224
	ds_read_b128 v[196:199], v179 offset:53248
	ds_read_b128 v[200:203], v179 offset:54272
	ds_read_b128 v[204:207], v179 offset:55296
	ds_read_b128 v[208:211], v179 offset:56320
	global_load_lds_dwordx4 v[192:193], off
	s_add_i32 m0, s0, 0x2000
	s_add_u32 s0, s10, 0x40080
	v_lshl_add_u64 v[192:193], v[212:213], 0, s[24:25]
	s_addc_u32 s1, s11, 0
	s_add_i32 s10, s26, s48
	global_load_lds_dwordx4 v[192:193], off
	v_lshl_add_u64 v[192:193], s[0:1], 0, v[132:133]
	s_mov_b32 m0, s10
	s_nop 0
	global_load_lds_dwordx4 v[192:193], off
	v_lshl_add_u64 v[192:193], s[0:1], 0, v[136:137]
	s_add_i32 m0, s10, 0x2000
	s_nop 0
	global_load_lds_dwordx4 v[192:193], off
	v_lshl_add_u64 v[192:193], v[214:215], 0, s[24:25]
	s_mov_b32 m0, s62
	s_nop 0
	global_load_lds_dwordx4 v[192:193], off
	v_lshl_add_u64 v[192:193], v[216:217], 0, s[24:25]
	s_mov_b32 m0, s63
	s_nop 0
	global_load_lds_dwordx4 v[192:193], off
	s_waitcnt vmcnt(8)
	s_waitcnt lgkmcnt(0)
	s_barrier
	v_mfma_f32_16x16x32_bf16 v[62:65], v[142:145], v[174:177], v[62:65]
	v_mfma_f32_16x16x32_bf16 v[58:61], v[150:153], v[174:177], v[58:61]
	v_mfma_f32_16x16x32_bf16 v[46:49], v[142:145], v[184:187], v[46:49]
	v_mfma_f32_16x16x32_bf16 v[42:45], v[150:153], v[184:187], v[42:45]
	v_mfma_f32_16x16x32_bf16 v[30:33], v[142:145], v[196:199], v[30:33]
	v_mfma_f32_16x16x32_bf16 v[26:29], v[150:153], v[196:199], v[26:29]
	v_mfma_f32_16x16x32_bf16 v[14:17], v[142:145], v[204:207], v[14:17]
	v_mfma_f32_16x16x32_bf16 v[10:13], v[150:153], v[204:207], v[10:13]
	v_mfma_f32_16x16x32_bf16 v[62:65], v[146:149], v[180:183], v[62:65]
	v_mfma_f32_16x16x32_bf16 v[58:61], v[154:157], v[180:183], v[58:61]
	v_mfma_f32_16x16x32_bf16 v[46:49], v[146:149], v[188:191], v[46:49]
	v_mfma_f32_16x16x32_bf16 v[42:45], v[154:157], v[188:191], v[42:45]
	v_mfma_f32_16x16x32_bf16 v[30:33], v[146:149], v[200:203], v[30:33]
	v_mfma_f32_16x16x32_bf16 v[26:29], v[154:157], v[200:203], v[26:29]
	v_mfma_f32_16x16x32_bf16 v[14:17], v[146:149], v[208:211], v[14:17]
	v_mfma_f32_16x16x32_bf16 v[10:13], v[154:157], v[208:211], v[10:13]
	v_mfma_f32_16x16x32_bf16 v[54:57], v[158:161], v[174:177], v[54:57]
	v_mfma_f32_16x16x32_bf16 v[50:53], v[166:169], v[174:177], v[50:53]
	v_mfma_f32_16x16x32_bf16 v[38:41], v[158:161], v[184:187], v[38:41]
	v_mfma_f32_16x16x32_bf16 v[34:37], v[166:169], v[184:187], v[34:37]
	v_mfma_f32_16x16x32_bf16 v[22:25], v[158:161], v[196:199], v[22:25]
	v_mfma_f32_16x16x32_bf16 v[18:21], v[166:169], v[196:199], v[18:21]
	v_mfma_f32_16x16x32_bf16 v[6:9], v[158:161], v[204:207], v[6:9]
	v_mfma_f32_16x16x32_bf16 v[2:5], v[166:169], v[204:207], v[2:5]
	v_mfma_f32_16x16x32_bf16 v[54:57], v[162:165], v[180:183], v[54:57]
	v_mfma_f32_16x16x32_bf16 v[50:53], v[170:173], v[180:183], v[50:53]
	v_mfma_f32_16x16x32_bf16 v[38:41], v[162:165], v[188:191], v[38:41]
	v_mfma_f32_16x16x32_bf16 v[34:37], v[170:173], v[188:191], v[34:37]
	v_mfma_f32_16x16x32_bf16 v[22:25], v[162:165], v[200:203], v[22:25]
	v_mfma_f32_16x16x32_bf16 v[18:21], v[170:173], v[200:203], v[18:21]
	v_mfma_f32_16x16x32_bf16 v[6:9], v[162:165], v[208:211], v[6:9]
	v_mfma_f32_16x16x32_bf16 v[2:5], v[170:173], v[208:211], v[2:5]
	s_barrier
	s_add_i32 s35, s35, 2
	s_add_u32 s8, s8, 0x100
	s_addc_u32 s9, s9, 0
	s_add_u32 s31, s31, 0x100
	s_addc_u32 s34, s34, 0
	s_cmp_gt_u32 s35, 13
	s_cbranch_scc0 .LBB0_717
	s_and_b64 vcc, exec, s[74:75]
	s_cbranch_vccz .LBB0_720
	s_barrier
